# GEMM K-loops: removed the redundant back-to-back s_setprio 0 / s_setprio 1 pair in the middle of each 32-MFMA compute segment (priority stays 1)
# speedup vs baseline: 1.0193x; 1.0158x over previous
; #define PG8_STAGE(bufoff, gbase, voff) do { _Pragma("unroll") for (int _i = 0; _i < 2; ++_i) \
;         __builtin_amdgcn_global_load_lds((const unsigned*)((const char*)(gbase) + _i * rdelta + (voff)), (LAS unsigned*)(lds + (bufoff) + ldsw + _i * 8192), 16, 0, 0); } while (0)
; #define PG8_LDA(dst, b, h) do { _Pragma("unroll") for (int m = 0; m < 4; ++m) _Pragma("unroll") for (int k = 0; k < 2; ++k) dst[m][k] = *(const LAS bf16x8*)(lds + PG8_SA(b, h) + aoff + m * 2048 + k * 1024); } while (0)
; #define PG8_LDB(dst, b, h) do { _Pragma("unroll") for (int n = 0; n < 2; ++n) _Pragma("unroll") for (int k = 0; k < 2; ++k) dst[n][k] = *(const LAS bf16x8*)(lds + PG8_SB(b, h) + boff + n * 2048 + k * 1024); } while (0)
; #define PG8_MMA(ai, bj, At, Bt) do { __builtin_amdgcn_s_setprio(1); _Pragma("unroll") for (int m = 0; m < 4; ++m) _Pragma("unroll") for (int n = 0; n < 2; ++n) _Pragma("unroll") for (int k = 0; k < 2; ++k) \
;         acc[ai][bj][m][n] = __builtin_amdgcn_mfma_f32_16x16x32_bf16(Bt[n][k], At[m][k], acc[ai][bj][m][n], 0, 0, 0); __builtin_amdgcn_s_setprio(0); } while (0)
; #define PG8_WAIT_V(n) asm volatile("s_waitcnt vmcnt(" #n ")" ::: "memory")
; #define PG8_WAIT_L(n) asm volatile("s_waitcnt lgkmcnt(" #n ")" ::: "memory")
; #define PG8_BAR __builtin_amdgcn_s_barrier()
; #define PG8_SCHED __builtin_amdgcn_sched_barrier(0)
; template <class Epi, class Sched, bool ALIGN_EPI, bool SP2>
; __device__ __forceinline__ void gemm_phase(LAS unsigned char* lds, const Gemm g, const Sched& S, const Epi& E) {
;     ...
;             const bool last = (t == nt - 2);
;             const char* a1 = cA + (size_t)(t + 1) * kstep;
;             const char* a2 = last ? nA : cA + (size_t)(t + 2) * kstep; const char* b2 = last ? nB : cB + (size_t)(t + 2) * kstep;
;             const char* a3 = a2 + kstep; const char* b3 = b2 + kstep;
;             PG8_LDB(B0, 0, 0); PG8_LDB(B1, 0, 1); PG8_SCHED; PG8_LDA(At, 0, 0); PG8_STAGE(PG8_SA(1, 1), a1 + hstep, voffA);
;             PG8_WAIT_V(8); PG8_WAIT_L(0); PG8_BAR; PG8_MMA(0, 0, At, B0); PG8_MMA(0, 1, At, B1); PG8_BAR; PG8_SCHED;
;             PG8_LDA(At, 0, 1); PG8_STAGE(PG8_SB(0, 0), b2, voffB); PG8_STAGE(PG8_SB(0, 1), b2 + hstep, voffB); PG8_STAGE(PG8_SA(0, 0), a2, voffA);
;             PG8_WAIT_V(8); PG8_WAIT_L(0); PG8_BAR; PG8_MMA(1, 0, At, B0); PG8_MMA(1, 1, At, B1); PG8_BAR; PG8_SCHED;
.LBB0_194:
	s_add_i32 s18, s4, 2
	s_add_u32 s14, s6, 0x80
	s_addc_u32 s15, s7, 0
	s_add_i32 s19, 0, 0x10000
	s_cmp_eq_u32 s96, s4
	s_cselect_b32 s15, s69, s15
	s_cselect_b32 s14, s68, s14
	v_add_u32_e32 v128, s19, v145
	s_cselect_b32 s51, s71, s17
	s_cselect_b32 s50, s70, s16
	s_add_i32 s4, 0, 0x14000
	ds_read_b128 v[136:139], v128
	ds_read_b128 v[152:155], v128 offset:1024
	ds_read_b128 v[156:159], v128 offset:2048
	ds_read_b128 v[160:163], v128 offset:3072
	v_add_u32_e32 v128, s4, v145
	ds_read_b128 v[164:167], v128
	ds_read_b128 v[172:175], v128 offset:1024
	ds_read_b128 v[176:179], v128 offset:2048
	ds_read_b128 v[180:183], v128 offset:3072
	v_lshl_add_u64 v[168:169], s[6:7], 0, v[148:149]
	s_add_i32 m0, s37, 0xc000
	ds_read_b128 v[208:211], v171
	ds_read_b128 v[212:215], v171 offset:1024
	ds_read_b128 v[216:219], v171 offset:2048
	ds_read_b128 v[220:223], v171 offset:3072
	ds_read_b128 v[224:227], v171 offset:4096
	ds_read_b128 v[228:231], v171 offset:5120
	ds_read_b128 v[232:235], v171 offset:6144
	ds_read_b128 v[236:239], v171 offset:7168
	global_load_lds_dwordx4 v[168:169], off
	v_lshl_add_u64 v[168:169], s[6:7], 0, v[150:151]
	s_add_i32 m0, s37, 0xe000
	s_nop 0
	global_load_lds_dwordx4 v[168:169], off
	s_waitcnt vmcnt(8)
	s_waitcnt lgkmcnt(0)
	s_barrier
	s_setprio 1
	s_waitcnt lgkmcnt(0)
	v_mfma_f32_16x16x32_bf16 v[120:123], v[136:139], v[208:211], v[120:123]
	v_mfma_f32_16x16x32_bf16 v[124:127], v[156:159], v[208:211], v[124:127]
	v_mfma_f32_16x16x32_bf16 v[108:111], v[136:139], v[216:219], v[108:111]
	v_mfma_f32_16x16x32_bf16 v[104:107], v[156:159], v[216:219], v[104:107]
	v_mfma_f32_16x16x32_bf16 v[92:95], v[136:139], v[224:227], v[92:95]
	v_mfma_f32_16x16x32_bf16 v[88:91], v[156:159], v[224:227], v[88:91]
	v_mfma_f32_16x16x32_bf16 v[76:79], v[136:139], v[232:235], v[76:79]
	v_mfma_f32_16x16x32_bf16 v[72:75], v[156:159], v[232:235], v[72:75]
	v_mfma_f32_16x16x32_bf16 v[120:123], v[152:155], v[212:215], v[120:123]
	v_mfma_f32_16x16x32_bf16 v[124:127], v[160:163], v[212:215], v[124:127]
	v_mfma_f32_16x16x32_bf16 v[108:111], v[152:155], v[220:223], v[108:111]
	v_mfma_f32_16x16x32_bf16 v[104:107], v[160:163], v[220:223], v[104:107]
	v_mfma_f32_16x16x32_bf16 v[92:95], v[152:155], v[228:231], v[92:95]
	v_mfma_f32_16x16x32_bf16 v[88:91], v[160:163], v[228:231], v[88:91]
	v_mfma_f32_16x16x32_bf16 v[76:79], v[152:155], v[236:239], v[76:79]
	v_mfma_f32_16x16x32_bf16 v[72:75], v[160:163], v[236:239], v[72:75]
	v_mfma_f32_16x16x32_bf16 v[116:119], v[164:167], v[208:211], v[116:119]
	v_mfma_f32_16x16x32_bf16 v[112:115], v[176:179], v[208:211], v[112:115]
	v_mfma_f32_16x16x32_bf16 v[100:103], v[164:167], v[216:219], v[100:103]
	v_mfma_f32_16x16x32_bf16 v[96:99], v[176:179], v[216:219], v[96:99]
	v_mfma_f32_16x16x32_bf16 v[84:87], v[164:167], v[224:227], v[84:87]
	v_mfma_f32_16x16x32_bf16 v[80:83], v[176:179], v[224:227], v[80:83]
	v_mfma_f32_16x16x32_bf16 v[68:71], v[164:167], v[232:235], v[68:71]
	v_mfma_f32_16x16x32_bf16 v[64:67], v[176:179], v[232:235], v[64:67]
	v_mfma_f32_16x16x32_bf16 v[116:119], v[172:175], v[212:215], v[116:119]
	v_mfma_f32_16x16x32_bf16 v[112:115], v[180:183], v[212:215], v[112:115]
	v_mfma_f32_16x16x32_bf16 v[100:103], v[172:175], v[220:223], v[100:103]
	v_mfma_f32_16x16x32_bf16 v[96:99], v[180:183], v[220:223], v[96:99]
	v_mfma_f32_16x16x32_bf16 v[84:87], v[172:175], v[228:231], v[84:87]
	v_mfma_f32_16x16x32_bf16 v[80:83], v[180:183], v[228:231], v[80:83]
	v_mfma_f32_16x16x32_bf16 v[68:71], v[172:175], v[236:239], v[68:71]
	v_mfma_f32_16x16x32_bf16 v[64:67], v[180:183], v[236:239], v[64:67]
	s_setprio 0
	s_barrier
	s_add_i32 s19, s19, s36
	v_lshl_add_u64 v[168:169], s[50:51], 0, v[130:131]
	s_mov_b32 m0, s19
	ds_read_b128 v[208:211], v171 offset:16384
	ds_read_b128 v[212:215], v171 offset:17408
	ds_read_b128 v[216:219], v171 offset:18432
	ds_read_b128 v[220:223], v171 offset:19456
	ds_read_b128 v[224:227], v171 offset:20480
	ds_read_b128 v[228:231], v171 offset:21504
	ds_read_b128 v[232:235], v171 offset:22528
	ds_read_b128 v[236:239], v171 offset:23552
	global_load_lds_dwordx4 v[168:169], off
	s_add_i32 m0, s19, 0x2000
	s_add_u32 s50, s50, s12
	v_lshl_add_u64 v[240:241], v[168:169], 0, s[10:11]
	s_addc_u32 s51, s51, s13
	s_add_i32 s4, s4, s36
	global_load_lds_dwordx4 v[240:241], off
	v_lshl_add_u64 v[242:243], s[50:51], 0, v[130:131]
	s_mov_b32 m0, s4
	v_lshl_add_u64 v[244:245], v[242:243], 0, s[10:11]
	global_load_lds_dwordx4 v[242:243], off
	s_add_i32 m0, s4, 0x2000
	v_lshl_add_u64 v[246:247], s[14:15], 0, v[140:141]
	global_load_lds_dwordx4 v[244:245], off
	s_mov_b32 m0, s37
	v_lshl_add_u64 v[248:249], v[246:247], 0, s[10:11]
	global_load_lds_dwordx4 v[246:247], off
	s_mov_b32 m0, s90
	s_nop 0
	global_load_lds_dwordx4 v[248:249], off
	s_waitcnt vmcnt(8)
	s_waitcnt lgkmcnt(0)
	s_barrier
; #define PG8_STAGE(bufoff, gbase, voff) do { _Pragma("unroll") for (int _i = 0; _i < 2; ++_i) \
;         __builtin_amdgcn_global_load_lds((const unsigned*)((const char*)(gbase) + _i * rdelta + (voff)), (LAS unsigned*)(lds + (bufoff) + ldsw + _i * 8192), 16, 0, 0); } while (0)
; #define PG8_LDA(dst, b, h) do { _Pragma("unroll") for (int m = 0; m < 4; ++m) _Pragma("unroll") for (int k = 0; k < 2; ++k) dst[m][k] = *(const LAS bf16x8*)(lds + PG8_SA(b, h) + aoff + m * 2048 + k * 1024); } while (0)
; #define PG8_LDB(dst, b, h) do { _Pragma("unroll") for (int n = 0; n < 2; ++n) _Pragma("unroll") for (int k = 0; k < 2; ++k) dst[n][k] = *(const LAS bf16x8*)(lds + PG8_SB(b, h) + boff + n * 2048 + k * 1024); } while (0)
; #define PG8_MMA(ai, bj, At, Bt) do { __builtin_amdgcn_s_setprio(1); _Pragma("unroll") for (int m = 0; m < 4; ++m) _Pragma("unroll") for (int n = 0; n < 2; ++n) _Pragma("unroll") for (int k = 0; k < 2; ++k) \
;         acc[ai][bj][m][n] = __builtin_amdgcn_mfma_f32_16x16x32_bf16(Bt[n][k], At[m][k], acc[ai][bj][m][n], 0, 0, 0); __builtin_amdgcn_s_setprio(0); } while (0)
; #define PG8_WAIT_V(n) asm volatile("s_waitcnt vmcnt(" #n ")" ::: "memory")
; #define PG8_WAIT_L(n) asm volatile("s_waitcnt lgkmcnt(" #n ")" ::: "memory")
; #define PG8_BAR __builtin_amdgcn_s_barrier()
; #define PG8_SCHED __builtin_amdgcn_sched_barrier(0)
; template <class Epi, class Sched, bool ALIGN_EPI, bool SP2>
; __device__ __forceinline__ void gemm_phase(LAS unsigned char* lds, const Gemm g, const Sched& S, const Epi& E) {
;     ...
;             PG8_WAIT_V(8); PG8_WAIT_L(0); PG8_BAR; PG8_MMA(0, 0, At, B0); PG8_MMA(0, 1, At, B1); PG8_BAR; PG8_SCHED;
;             PG8_LDA(At, 0, 1); PG8_STAGE(PG8_SB(0, 0), b2, voffB); PG8_STAGE(PG8_SB(0, 1), b2 + hstep, voffB); PG8_STAGE(PG8_SA(0, 0), a2, voffA);
;             PG8_WAIT_V(8); PG8_WAIT_L(0); PG8_BAR; PG8_MMA(1, 0, At, B0); PG8_MMA(1, 1, At, B1); PG8_BAR; PG8_SCHED;
;             PG8_LDB(B0, 1, 0); PG8_LDB(B1, 1, 1); PG8_SCHED; PG8_LDA(At, 1, 0); PG8_STAGE(PG8_SA(0, 1), a2 + hstep, voffA);
;             PG8_WAIT_V(8); PG8_WAIT_L(0); PG8_BAR; PG8_MMA(0, 0, At, B0); PG8_MMA(0, 1, At, B1); PG8_BAR; PG8_SCHED;
	s_setprio 1
	s_waitcnt lgkmcnt(0)
	v_mfma_f32_16x16x32_bf16 v[60:63], v[136:139], v[208:211], v[60:63]
	v_mfma_f32_16x16x32_bf16 v[56:59], v[156:159], v[208:211], v[56:59]
	v_mfma_f32_16x16x32_bf16 v[44:47], v[136:139], v[216:219], v[44:47]
	v_mfma_f32_16x16x32_bf16 v[40:43], v[156:159], v[216:219], v[40:43]
	v_mfma_f32_16x16x32_bf16 v[28:31], v[136:139], v[224:227], v[28:31]
	v_mfma_f32_16x16x32_bf16 v[24:27], v[156:159], v[224:227], v[24:27]
	v_mfma_f32_16x16x32_bf16 v[12:15], v[136:139], v[232:235], v[12:15]
	v_mfma_f32_16x16x32_bf16 v[8:11], v[156:159], v[232:235], v[8:11]
	v_mfma_f32_16x16x32_bf16 v[60:63], v[152:155], v[212:215], v[60:63]
	v_mfma_f32_16x16x32_bf16 v[56:59], v[160:163], v[212:215], v[56:59]
	v_mfma_f32_16x16x32_bf16 v[44:47], v[152:155], v[220:223], v[44:47]
	v_mfma_f32_16x16x32_bf16 v[40:43], v[160:163], v[220:223], v[40:43]
	v_mfma_f32_16x16x32_bf16 v[28:31], v[152:155], v[228:231], v[28:31]
	v_mfma_f32_16x16x32_bf16 v[24:27], v[160:163], v[228:231], v[24:27]
	v_mfma_f32_16x16x32_bf16 v[12:15], v[152:155], v[236:239], v[12:15]
	v_mfma_f32_16x16x32_bf16 v[8:11], v[160:163], v[236:239], v[8:11]
	v_mfma_f32_16x16x32_bf16 v[52:55], v[164:167], v[208:211], v[52:55]
	v_mfma_f32_16x16x32_bf16 v[48:51], v[176:179], v[208:211], v[48:51]
	v_mfma_f32_16x16x32_bf16 v[36:39], v[164:167], v[216:219], v[36:39]
	v_mfma_f32_16x16x32_bf16 v[32:35], v[176:179], v[216:219], v[32:35]
	v_mfma_f32_16x16x32_bf16 v[20:23], v[164:167], v[224:227], v[20:23]
	v_mfma_f32_16x16x32_bf16 v[16:19], v[176:179], v[224:227], v[16:19]
	v_mfma_f32_16x16x32_bf16 v[4:7], v[164:167], v[232:235], v[4:7]
	v_mfma_f32_16x16x32_bf16 v[0:3], v[176:179], v[232:235], v[0:3]
	v_mfma_f32_16x16x32_bf16 v[52:55], v[172:175], v[212:215], v[52:55]
	v_mfma_f32_16x16x32_bf16 v[48:51], v[180:183], v[212:215], v[48:51]
	v_mfma_f32_16x16x32_bf16 v[36:39], v[172:175], v[220:223], v[36:39]
	v_mfma_f32_16x16x32_bf16 v[32:35], v[180:183], v[220:223], v[32:35]
	v_mfma_f32_16x16x32_bf16 v[20:23], v[172:175], v[228:231], v[20:23]
	v_mfma_f32_16x16x32_bf16 v[16:19], v[180:183], v[228:231], v[16:19]
	v_mfma_f32_16x16x32_bf16 v[4:7], v[172:175], v[236:239], v[4:7]
	v_mfma_f32_16x16x32_bf16 v[0:3], v[180:183], v[236:239], v[0:3]
	s_setprio 0
	s_barrier
	s_add_i32 s4, 0, 0x18000
	v_add_u32_e32 v128, s4, v145
	s_add_i32 s19, 0, 0x1c000
	ds_read_b128 v[136:139], v128
	ds_read_b128 v[152:155], v128 offset:1024
	ds_read_b128 v[156:159], v128 offset:2048
	ds_read_b128 v[160:163], v128 offset:3072
	v_add_u32_e32 v128, s19, v145
	ds_read_b128 v[164:167], v128
	ds_read_b128 v[172:175], v128 offset:1024
	ds_read_b128 v[176:179], v128 offset:2048
	ds_read_b128 v[180:183], v128 offset:3072
	s_add_u32 s14, s14, s12
	s_addc_u32 s15, s15, s13
	s_mov_b32 m0, s91
	v_lshl_add_u64 v[250:251], s[14:15], 0, v[140:141]
	ds_read_b128 v[208:211], v171 offset:32768
	ds_read_b128 v[212:215], v171 offset:33792
	ds_read_b128 v[216:219], v171 offset:34816
	ds_read_b128 v[220:223], v171 offset:35840
	ds_read_b128 v[224:227], v171 offset:36864
	ds_read_b128 v[228:231], v171 offset:37888
	ds_read_b128 v[232:235], v171 offset:38912
	ds_read_b128 v[236:239], v171 offset:39936
	global_load_lds_dwordx4 v[250:251], off
	v_lshl_add_u64 v[250:251], v[250:251], 0, s[10:11]
	s_mov_b32 m0, s92
	s_nop 0
	global_load_lds_dwordx4 v[250:251], off
	s_waitcnt vmcnt(8)
	s_waitcnt lgkmcnt(0)
	s_barrier
	s_setprio 1
	s_waitcnt lgkmcnt(0)
	v_mfma_f32_16x16x32_bf16 v[120:123], v[136:139], v[208:211], v[120:123]
	v_mfma_f32_16x16x32_bf16 v[124:127], v[156:159], v[208:211], v[124:127]
	v_mfma_f32_16x16x32_bf16 v[108:111], v[136:139], v[216:219], v[108:111]
	v_mfma_f32_16x16x32_bf16 v[104:107], v[156:159], v[216:219], v[104:107]
	v_mfma_f32_16x16x32_bf16 v[92:95], v[136:139], v[224:227], v[92:95]
	v_mfma_f32_16x16x32_bf16 v[88:91], v[156:159], v[224:227], v[88:91]
	v_mfma_f32_16x16x32_bf16 v[76:79], v[136:139], v[232:235], v[76:79]
	v_mfma_f32_16x16x32_bf16 v[72:75], v[156:159], v[232:235], v[72:75]
	v_mfma_f32_16x16x32_bf16 v[120:123], v[152:155], v[212:215], v[120:123]
	v_mfma_f32_16x16x32_bf16 v[124:127], v[160:163], v[212:215], v[124:127]
	v_mfma_f32_16x16x32_bf16 v[108:111], v[152:155], v[220:223], v[108:111]
	v_mfma_f32_16x16x32_bf16 v[104:107], v[160:163], v[220:223], v[104:107]
	v_mfma_f32_16x16x32_bf16 v[92:95], v[152:155], v[228:231], v[92:95]
	v_mfma_f32_16x16x32_bf16 v[88:91], v[160:163], v[228:231], v[88:91]
	v_mfma_f32_16x16x32_bf16 v[76:79], v[152:155], v[236:239], v[76:79]
	v_mfma_f32_16x16x32_bf16 v[72:75], v[160:163], v[236:239], v[72:75]
	v_mfma_f32_16x16x32_bf16 v[116:119], v[164:167], v[208:211], v[116:119]
	v_mfma_f32_16x16x32_bf16 v[112:115], v[176:179], v[208:211], v[112:115]
	v_mfma_f32_16x16x32_bf16 v[100:103], v[164:167], v[216:219], v[100:103]
	v_mfma_f32_16x16x32_bf16 v[96:99], v[176:179], v[216:219], v[96:99]
	v_mfma_f32_16x16x32_bf16 v[84:87], v[164:167], v[224:227], v[84:87]
	v_mfma_f32_16x16x32_bf16 v[80:83], v[176:179], v[224:227], v[80:83]
	v_mfma_f32_16x16x32_bf16 v[68:71], v[164:167], v[232:235], v[68:71]
	v_mfma_f32_16x16x32_bf16 v[64:67], v[176:179], v[232:235], v[64:67]
	v_mfma_f32_16x16x32_bf16 v[116:119], v[172:175], v[212:215], v[116:119]
	v_mfma_f32_16x16x32_bf16 v[112:115], v[180:183], v[212:215], v[112:115]
	v_mfma_f32_16x16x32_bf16 v[100:103], v[172:175], v[220:223], v[100:103]
	v_mfma_f32_16x16x32_bf16 v[96:99], v[180:183], v[220:223], v[96:99]
	v_mfma_f32_16x16x32_bf16 v[84:87], v[172:175], v[228:231], v[84:87]
	v_mfma_f32_16x16x32_bf16 v[80:83], v[180:183], v[228:231], v[80:83]
	v_mfma_f32_16x16x32_bf16 v[68:71], v[172:175], v[236:239], v[68:71]
	v_mfma_f32_16x16x32_bf16 v[64:67], v[180:183], v[236:239], v[64:67]
	s_setprio 0
	s_barrier
; #define PG8_STAGE(bufoff, gbase, voff) do { _Pragma("unroll") for (int _i = 0; _i < 2; ++_i) \
;         __builtin_amdgcn_global_load_lds((const unsigned*)((const char*)(gbase) + _i * rdelta + (voff)), (LAS unsigned*)(lds + (bufoff) + ldsw + _i * 8192), 16, 0, 0); } while (0)
; #define PG8_LDA(dst, b, h) do { _Pragma("unroll") for (int m = 0; m < 4; ++m) _Pragma("unroll") for (int k = 0; k < 2; ++k) dst[m][k] = *(const LAS bf16x8*)(lds + PG8_SA(b, h) + aoff + m * 2048 + k * 1024); } while (0)
; #define PG8_MMA(ai, bj, At, Bt) do { __builtin_amdgcn_s_setprio(1); _Pragma("unroll") for (int m = 0; m < 4; ++m) _Pragma("unroll") for (int n = 0; n < 2; ++n) _Pragma("unroll") for (int k = 0; k < 2; ++k) \
;         acc[ai][bj][m][n] = __builtin_amdgcn_mfma_f32_16x16x32_bf16(Bt[n][k], At[m][k], acc[ai][bj][m][n], 0, 0, 0); __builtin_amdgcn_s_setprio(0); } while (0)
; #define PG8_WAIT_V(n) asm volatile("s_waitcnt vmcnt(" #n ")" ::: "memory")
; #define PG8_WAIT_L(n) asm volatile("s_waitcnt lgkmcnt(" #n ")" ::: "memory")
; #define PG8_BAR __builtin_amdgcn_s_barrier()
; #define PG8_SCHED __builtin_amdgcn_sched_barrier(0)
; template <class Epi, class Sched, bool ALIGN_EPI, bool SP2>
; __device__ __forceinline__ void gemm_phase(LAS unsigned char* lds, const Gemm g, const Sched& S, const Epi& E) {
;     ...
;             PG8_LDA(At, 1, 1); PG8_STAGE(PG8_SB(1, 0), b3, voffB); PG8_STAGE(PG8_SB(1, 1), b3 + hstep, voffB); PG8_STAGE(PG8_SA(1, 0), a3, voffA);
;             PG8_WAIT_V(8); PG8_WAIT_L(0); PG8_BAR; PG8_MMA(1, 0, At, B0); PG8_MMA(1, 1, At, B1); PG8_BAR; PG8_SCHED;
	s_add_i32 s4, s4, s36
	v_lshl_add_u64 v[168:169], v[168:169], 0, s[30:31]
	s_mov_b32 m0, s4
	ds_read_b128 v[208:211], v171 offset:49152
	ds_read_b128 v[212:215], v171 offset:50176
	ds_read_b128 v[216:219], v171 offset:51200
	ds_read_b128 v[220:223], v171 offset:52224
	ds_read_b128 v[224:227], v171 offset:53248
	ds_read_b128 v[228:231], v171 offset:54272
	ds_read_b128 v[232:235], v171 offset:55296
	ds_read_b128 v[236:239], v171 offset:56320
	global_load_lds_dwordx4 v[168:169], off
	v_lshl_add_u64 v[168:169], v[240:241], 0, s[30:31]
	s_add_i32 m0, s4, 0x2000
	s_add_i32 s4, s19, s36
	global_load_lds_dwordx4 v[168:169], off
	v_lshl_add_u64 v[168:169], v[242:243], 0, s[30:31]
	s_mov_b32 m0, s4
	s_nop 0
	global_load_lds_dwordx4 v[168:169], off
	v_lshl_add_u64 v[168:169], v[244:245], 0, s[30:31]
	s_add_i32 m0, s4, 0x2000
	s_nop 0
	global_load_lds_dwordx4 v[168:169], off
	v_lshl_add_u64 v[168:169], v[246:247], 0, s[30:31]
	s_mov_b32 m0, s93
	s_nop 0
	global_load_lds_dwordx4 v[168:169], off
	v_lshl_add_u64 v[168:169], v[248:249], 0, s[30:31]
	s_mov_b32 m0, s94
	s_nop 0
	global_load_lds_dwordx4 v[168:169], off
	s_waitcnt vmcnt(8)
	s_waitcnt lgkmcnt(0)
	s_barrier
	s_setprio 1
	s_waitcnt lgkmcnt(0)
	v_mfma_f32_16x16x32_bf16 v[60:63], v[136:139], v[208:211], v[60:63]
	v_mfma_f32_16x16x32_bf16 v[56:59], v[156:159], v[208:211], v[56:59]
	v_mfma_f32_16x16x32_bf16 v[44:47], v[136:139], v[216:219], v[44:47]
	v_mfma_f32_16x16x32_bf16 v[40:43], v[156:159], v[216:219], v[40:43]
	v_mfma_f32_16x16x32_bf16 v[28:31], v[136:139], v[224:227], v[28:31]
	v_mfma_f32_16x16x32_bf16 v[24:27], v[156:159], v[224:227], v[24:27]
	v_mfma_f32_16x16x32_bf16 v[12:15], v[136:139], v[232:235], v[12:15]
	v_mfma_f32_16x16x32_bf16 v[8:11], v[156:159], v[232:235], v[8:11]
	v_mfma_f32_16x16x32_bf16 v[60:63], v[152:155], v[212:215], v[60:63]
	v_mfma_f32_16x16x32_bf16 v[56:59], v[160:163], v[212:215], v[56:59]
	v_mfma_f32_16x16x32_bf16 v[44:47], v[152:155], v[220:223], v[44:47]
	v_mfma_f32_16x16x32_bf16 v[40:43], v[160:163], v[220:223], v[40:43]
	v_mfma_f32_16x16x32_bf16 v[28:31], v[152:155], v[228:231], v[28:31]
	v_mfma_f32_16x16x32_bf16 v[24:27], v[160:163], v[228:231], v[24:27]
	v_mfma_f32_16x16x32_bf16 v[12:15], v[152:155], v[236:239], v[12:15]
	v_mfma_f32_16x16x32_bf16 v[8:11], v[160:163], v[236:239], v[8:11]
	v_mfma_f32_16x16x32_bf16 v[52:55], v[164:167], v[208:211], v[52:55]
	v_mfma_f32_16x16x32_bf16 v[48:51], v[176:179], v[208:211], v[48:51]
	v_mfma_f32_16x16x32_bf16 v[36:39], v[164:167], v[216:219], v[36:39]
	v_mfma_f32_16x16x32_bf16 v[32:35], v[176:179], v[216:219], v[32:35]
	v_mfma_f32_16x16x32_bf16 v[20:23], v[164:167], v[224:227], v[20:23]
	v_mfma_f32_16x16x32_bf16 v[16:19], v[176:179], v[224:227], v[16:19]
	v_mfma_f32_16x16x32_bf16 v[4:7], v[164:167], v[232:235], v[4:7]
	v_mfma_f32_16x16x32_bf16 v[0:3], v[176:179], v[232:235], v[0:3]
	v_mfma_f32_16x16x32_bf16 v[52:55], v[172:175], v[212:215], v[52:55]
	v_mfma_f32_16x16x32_bf16 v[48:51], v[180:183], v[212:215], v[48:51]
	v_mfma_f32_16x16x32_bf16 v[36:39], v[172:175], v[220:223], v[36:39]
	v_mfma_f32_16x16x32_bf16 v[32:35], v[180:183], v[220:223], v[32:35]
	v_mfma_f32_16x16x32_bf16 v[20:23], v[172:175], v[228:231], v[20:23]
	v_mfma_f32_16x16x32_bf16 v[16:19], v[180:183], v[228:231], v[16:19]
	v_mfma_f32_16x16x32_bf16 v[4:7], v[172:175], v[236:239], v[4:7]
	v_mfma_f32_16x16x32_bf16 v[0:3], v[180:183], v[236:239], v[0:3]
	s_setprio 0
	s_barrier
	s_add_u32 s6, s6, 0x100
	s_addc_u32 s7, s7, 0
	s_add_u32 s16, s16, 0x100
	s_addc_u32 s17, s17, 0
	s_cmp_ge_i32 s18, s95
	s_mov_b32 s4, s18
	s_cbranch_scc0 .LBB0_194

; #define PG8_STAGE(bufoff, gbase, voff) do { _Pragma("unroll") for (int _i = 0; _i < 2; ++_i) \
;         __builtin_amdgcn_global_load_lds((const unsigned*)((const char*)(gbase) + _i * rdelta + (voff)), (LAS unsigned*)(lds + (bufoff) + ldsw + _i * 8192), 16, 0, 0); } while (0)
; #define PG8_LDA(dst, b, h) do { _Pragma("unroll") for (int m = 0; m < 4; ++m) _Pragma("unroll") for (int k = 0; k < 2; ++k) dst[m][k] = *(const LAS bf16x8*)(lds + PG8_SA(b, h) + aoff + m * 2048 + k * 1024); } while (0)
; #define PG8_LDB(dst, b, h) do { _Pragma("unroll") for (int n = 0; n < 2; ++n) _Pragma("unroll") for (int k = 0; k < 2; ++k) dst[n][k] = *(const LAS bf16x8*)(lds + PG8_SB(b, h) + boff + n * 2048 + k * 1024); } while (0)
; #define PG8_MMA(ai, bj, At, Bt) do { __builtin_amdgcn_s_setprio(1); _Pragma("unroll") for (int m = 0; m < 4; ++m) _Pragma("unroll") for (int n = 0; n < 2; ++n) _Pragma("unroll") for (int k = 0; k < 2; ++k) \
;         acc[ai][bj][m][n] = __builtin_amdgcn_mfma_f32_16x16x32_bf16(Bt[n][k], At[m][k], acc[ai][bj][m][n], 0, 0, 0); __builtin_amdgcn_s_setprio(0); } while (0)
; #define PG8_WAIT_V(n) asm volatile("s_waitcnt vmcnt(" #n ")" ::: "memory")
; #define PG8_WAIT_L(n) asm volatile("s_waitcnt lgkmcnt(" #n ")" ::: "memory")
; #define PG8_BAR __builtin_amdgcn_s_barrier()
; #define PG8_SCHED __builtin_amdgcn_sched_barrier(0)
; template <class Epi, class Sched, bool ALIGN_EPI, bool SP2>
; __device__ __forceinline__ void gemm_phase(LAS unsigned char* lds, const Gemm g, const Sched& S, const Epi& E) {
;     ...
;             const bool last = (t == nt - 2);
;             const char* a1 = cA + (size_t)(t + 1) * kstep;
;             const char* a2 = last ? nA : cA + (size_t)(t + 2) * kstep; const char* b2 = last ? nB : cB + (size_t)(t + 2) * kstep;
;             const char* a3 = a2 + kstep; const char* b3 = b2 + kstep;
;             PG8_LDB(B0, 0, 0); PG8_LDB(B1, 0, 1); PG8_SCHED; PG8_LDA(At, 0, 0); PG8_STAGE(PG8_SA(1, 1), a1 + hstep, voffA);
;             PG8_WAIT_V(8); PG8_WAIT_L(0); PG8_BAR; PG8_MMA(0, 0, At, B0); PG8_MMA(0, 1, At, B1); PG8_BAR; PG8_SCHED;
;             PG8_LDA(At, 0, 1); PG8_STAGE(PG8_SB(0, 0), b2, voffB); PG8_STAGE(PG8_SB(0, 1), b2 + hstep, voffB); PG8_STAGE(PG8_SA(0, 0), a2, voffA);
;             PG8_WAIT_V(8); PG8_WAIT_L(0); PG8_BAR; PG8_MMA(1, 0, At, B0); PG8_MMA(1, 1, At, B1); PG8_BAR; PG8_SCHED;
.LBB0_805:
	s_add_i32 s18, s4, 2
	s_add_u32 s14, s6, 0x80
	s_addc_u32 s15, s7, 0
	s_add_i32 s19, 0, 0x10000
	s_cmp_eq_u32 s63, s4
	s_cselect_b32 s15, s59, s15
	s_cselect_b32 s14, s58, s14
	v_add_u32_e32 v128, s19, v151
	s_cselect_b32 s69, s61, s17
	s_cselect_b32 s68, s60, s16
	s_add_i32 s4, 0, 0x14000
	ds_read_b128 v[142:145], v128
	ds_read_b128 v[146:149], v128 offset:1024
	ds_read_b128 v[154:157], v128 offset:2048
	ds_read_b128 v[158:161], v128 offset:3072
	v_add_u32_e32 v128, s4, v151
	ds_read_b128 v[162:165], v128
	ds_read_b128 v[166:169], v128 offset:1024
	ds_read_b128 v[170:173], v128 offset:2048
	ds_read_b128 v[174:177], v128 offset:3072
	v_lshl_add_u64 v[182:183], s[6:7], 0, v[138:139]
	s_add_i32 m0, s35, 0xc000
	ds_read_b128 v[178:181], v153
	ds_read_b128 v[208:211], v153 offset:1024
	ds_read_b128 v[212:215], v153 offset:2048
	ds_read_b128 v[216:219], v153 offset:3072
	ds_read_b128 v[220:223], v153 offset:4096
	ds_read_b128 v[224:227], v153 offset:5120
	ds_read_b128 v[228:231], v153 offset:6144
	ds_read_b128 v[232:235], v153 offset:7168
	global_load_lds_dwordx4 v[182:183], off
	v_lshl_add_u64 v[182:183], s[6:7], 0, v[140:141]
	s_add_i32 m0, s35, 0xe000
	s_nop 0
	global_load_lds_dwordx4 v[182:183], off
	s_waitcnt vmcnt(8)
	s_waitcnt lgkmcnt(0)
	s_barrier
	s_setprio 1
	s_waitcnt lgkmcnt(0)
	v_mfma_f32_16x16x32_bf16 v[120:123], v[142:145], v[178:181], v[120:123]
	v_mfma_f32_16x16x32_bf16 v[124:127], v[154:157], v[178:181], v[124:127]
	v_mfma_f32_16x16x32_bf16 v[108:111], v[142:145], v[212:215], v[108:111]
	v_mfma_f32_16x16x32_bf16 v[104:107], v[154:157], v[212:215], v[104:107]
	v_mfma_f32_16x16x32_bf16 v[92:95], v[142:145], v[220:223], v[92:95]
	v_mfma_f32_16x16x32_bf16 v[88:91], v[154:157], v[220:223], v[88:91]
	v_mfma_f32_16x16x32_bf16 v[76:79], v[142:145], v[228:231], v[76:79]
	v_mfma_f32_16x16x32_bf16 v[72:75], v[154:157], v[228:231], v[72:75]
	v_mfma_f32_16x16x32_bf16 v[120:123], v[146:149], v[208:211], v[120:123]
	v_mfma_f32_16x16x32_bf16 v[124:127], v[158:161], v[208:211], v[124:127]
	v_mfma_f32_16x16x32_bf16 v[108:111], v[146:149], v[216:219], v[108:111]
	v_mfma_f32_16x16x32_bf16 v[104:107], v[158:161], v[216:219], v[104:107]
	v_mfma_f32_16x16x32_bf16 v[92:95], v[146:149], v[224:227], v[92:95]
	v_mfma_f32_16x16x32_bf16 v[88:91], v[158:161], v[224:227], v[88:91]
	v_mfma_f32_16x16x32_bf16 v[76:79], v[146:149], v[232:235], v[76:79]
	v_mfma_f32_16x16x32_bf16 v[72:75], v[158:161], v[232:235], v[72:75]
	v_mfma_f32_16x16x32_bf16 v[116:119], v[162:165], v[178:181], v[116:119]
	v_mfma_f32_16x16x32_bf16 v[112:115], v[170:173], v[178:181], v[112:115]
	v_mfma_f32_16x16x32_bf16 v[100:103], v[162:165], v[212:215], v[100:103]
	v_mfma_f32_16x16x32_bf16 v[96:99], v[170:173], v[212:215], v[96:99]
	v_mfma_f32_16x16x32_bf16 v[84:87], v[162:165], v[220:223], v[84:87]
	v_mfma_f32_16x16x32_bf16 v[80:83], v[170:173], v[220:223], v[80:83]
	v_mfma_f32_16x16x32_bf16 v[68:71], v[162:165], v[228:231], v[68:71]
	v_mfma_f32_16x16x32_bf16 v[64:67], v[170:173], v[228:231], v[64:67]
	v_mfma_f32_16x16x32_bf16 v[116:119], v[166:169], v[208:211], v[116:119]
	v_mfma_f32_16x16x32_bf16 v[112:115], v[174:177], v[208:211], v[112:115]
	v_mfma_f32_16x16x32_bf16 v[100:103], v[166:169], v[216:219], v[100:103]
	v_mfma_f32_16x16x32_bf16 v[96:99], v[174:177], v[216:219], v[96:99]
	v_mfma_f32_16x16x32_bf16 v[84:87], v[166:169], v[224:227], v[84:87]
	v_mfma_f32_16x16x32_bf16 v[80:83], v[174:177], v[224:227], v[80:83]
	v_mfma_f32_16x16x32_bf16 v[68:71], v[166:169], v[232:235], v[68:71]
	v_mfma_f32_16x16x32_bf16 v[64:67], v[174:177], v[232:235], v[64:67]
	s_setprio 0
	s_barrier
	s_add_i32 s19, s19, s34
	v_lshl_add_u64 v[182:183], s[68:69], 0, v[130:131]
	s_mov_b32 m0, s19
	ds_read_b128 v[178:181], v153 offset:16384
	ds_read_b128 v[208:211], v153 offset:17408
	ds_read_b128 v[212:215], v153 offset:18432
	ds_read_b128 v[216:219], v153 offset:19456
	ds_read_b128 v[220:223], v153 offset:20480
	ds_read_b128 v[224:227], v153 offset:21504
	ds_read_b128 v[228:231], v153 offset:22528
	ds_read_b128 v[232:235], v153 offset:23552
	global_load_lds_dwordx4 v[182:183], off
	s_add_i32 m0, s19, 0x2000
	s_add_u32 s68, s68, s10
	v_lshl_add_u64 v[236:237], v[182:183], 0, s[8:9]
	s_addc_u32 s69, s69, s11
	s_add_i32 s4, s4, s34
	global_load_lds_dwordx4 v[236:237], off
	v_lshl_add_u64 v[238:239], s[68:69], 0, v[130:131]
	s_mov_b32 m0, s4
	v_lshl_add_u64 v[240:241], v[238:239], 0, s[8:9]
	global_load_lds_dwordx4 v[238:239], off
	s_add_i32 m0, s4, 0x2000
	v_lshl_add_u64 v[242:243], s[14:15], 0, v[136:137]
	global_load_lds_dwordx4 v[240:241], off
	s_mov_b32 m0, s35
	v_lshl_add_u64 v[244:245], v[242:243], 0, s[8:9]
	global_load_lds_dwordx4 v[242:243], off
	s_mov_b32 m0, s36
	s_nop 0
	global_load_lds_dwordx4 v[244:245], off
	s_waitcnt vmcnt(8)
	s_waitcnt lgkmcnt(0)
	s_barrier
; #define PG8_STAGE(bufoff, gbase, voff) do { _Pragma("unroll") for (int _i = 0; _i < 2; ++_i) \
;         __builtin_amdgcn_global_load_lds((const unsigned*)((const char*)(gbase) + _i * rdelta + (voff)), (LAS unsigned*)(lds + (bufoff) + ldsw + _i * 8192), 16, 0, 0); } while (0)
; #define PG8_LDA(dst, b, h) do { _Pragma("unroll") for (int m = 0; m < 4; ++m) _Pragma("unroll") for (int k = 0; k < 2; ++k) dst[m][k] = *(const LAS bf16x8*)(lds + PG8_SA(b, h) + aoff + m * 2048 + k * 1024); } while (0)
; #define PG8_LDB(dst, b, h) do { _Pragma("unroll") for (int n = 0; n < 2; ++n) _Pragma("unroll") for (int k = 0; k < 2; ++k) dst[n][k] = *(const LAS bf16x8*)(lds + PG8_SB(b, h) + boff + n * 2048 + k * 1024); } while (0)
; #define PG8_MMA(ai, bj, At, Bt) do { __builtin_amdgcn_s_setprio(1); _Pragma("unroll") for (int m = 0; m < 4; ++m) _Pragma("unroll") for (int n = 0; n < 2; ++n) _Pragma("unroll") for (int k = 0; k < 2; ++k) \
;         acc[ai][bj][m][n] = __builtin_amdgcn_mfma_f32_16x16x32_bf16(Bt[n][k], At[m][k], acc[ai][bj][m][n], 0, 0, 0); __builtin_amdgcn_s_setprio(0); } while (0)
; #define PG8_WAIT_V(n) asm volatile("s_waitcnt vmcnt(" #n ")" ::: "memory")
; #define PG8_WAIT_L(n) asm volatile("s_waitcnt lgkmcnt(" #n ")" ::: "memory")
; #define PG8_BAR __builtin_amdgcn_s_barrier()
; #define PG8_SCHED __builtin_amdgcn_sched_barrier(0)
; template <class Epi, class Sched, bool ALIGN_EPI, bool SP2>
; __device__ __forceinline__ void gemm_phase(LAS unsigned char* lds, const Gemm g, const Sched& S, const Epi& E) {
;     ...
;             PG8_WAIT_V(8); PG8_WAIT_L(0); PG8_BAR; PG8_MMA(0, 0, At, B0); PG8_MMA(0, 1, At, B1); PG8_BAR; PG8_SCHED;
;             PG8_LDA(At, 0, 1); PG8_STAGE(PG8_SB(0, 0), b2, voffB); PG8_STAGE(PG8_SB(0, 1), b2 + hstep, voffB); PG8_STAGE(PG8_SA(0, 0), a2, voffA);
;             PG8_WAIT_V(8); PG8_WAIT_L(0); PG8_BAR; PG8_MMA(1, 0, At, B0); PG8_MMA(1, 1, At, B1); PG8_BAR; PG8_SCHED;
;             PG8_LDB(B0, 1, 0); PG8_LDB(B1, 1, 1); PG8_SCHED; PG8_LDA(At, 1, 0); PG8_STAGE(PG8_SA(0, 1), a2 + hstep, voffA);
;             PG8_WAIT_V(8); PG8_WAIT_L(0); PG8_BAR; PG8_MMA(0, 0, At, B0); PG8_MMA(0, 1, At, B1); PG8_BAR; PG8_SCHED;
	s_setprio 1
	s_waitcnt lgkmcnt(0)
	v_mfma_f32_16x16x32_bf16 v[60:63], v[142:145], v[178:181], v[60:63]
	v_mfma_f32_16x16x32_bf16 v[56:59], v[154:157], v[178:181], v[56:59]
	v_mfma_f32_16x16x32_bf16 v[44:47], v[142:145], v[212:215], v[44:47]
	v_mfma_f32_16x16x32_bf16 v[40:43], v[154:157], v[212:215], v[40:43]
	v_mfma_f32_16x16x32_bf16 v[28:31], v[142:145], v[220:223], v[28:31]
	v_mfma_f32_16x16x32_bf16 v[24:27], v[154:157], v[220:223], v[24:27]
	v_mfma_f32_16x16x32_bf16 v[12:15], v[142:145], v[228:231], v[12:15]
	v_mfma_f32_16x16x32_bf16 v[8:11], v[154:157], v[228:231], v[8:11]
	v_mfma_f32_16x16x32_bf16 v[60:63], v[146:149], v[208:211], v[60:63]
	v_mfma_f32_16x16x32_bf16 v[56:59], v[158:161], v[208:211], v[56:59]
	v_mfma_f32_16x16x32_bf16 v[44:47], v[146:149], v[216:219], v[44:47]
	v_mfma_f32_16x16x32_bf16 v[40:43], v[158:161], v[216:219], v[40:43]
	v_mfma_f32_16x16x32_bf16 v[28:31], v[146:149], v[224:227], v[28:31]
	v_mfma_f32_16x16x32_bf16 v[24:27], v[158:161], v[224:227], v[24:27]
	v_mfma_f32_16x16x32_bf16 v[12:15], v[146:149], v[232:235], v[12:15]
	v_mfma_f32_16x16x32_bf16 v[8:11], v[158:161], v[232:235], v[8:11]
	v_mfma_f32_16x16x32_bf16 v[52:55], v[162:165], v[178:181], v[52:55]
	v_mfma_f32_16x16x32_bf16 v[48:51], v[170:173], v[178:181], v[48:51]
	v_mfma_f32_16x16x32_bf16 v[36:39], v[162:165], v[212:215], v[36:39]
	v_mfma_f32_16x16x32_bf16 v[32:35], v[170:173], v[212:215], v[32:35]
	v_mfma_f32_16x16x32_bf16 v[20:23], v[162:165], v[220:223], v[20:23]
	v_mfma_f32_16x16x32_bf16 v[16:19], v[170:173], v[220:223], v[16:19]
	v_mfma_f32_16x16x32_bf16 v[4:7], v[162:165], v[228:231], v[4:7]
	v_mfma_f32_16x16x32_bf16 v[0:3], v[170:173], v[228:231], v[0:3]
	v_mfma_f32_16x16x32_bf16 v[52:55], v[166:169], v[208:211], v[52:55]
	v_mfma_f32_16x16x32_bf16 v[48:51], v[174:177], v[208:211], v[48:51]
	v_mfma_f32_16x16x32_bf16 v[36:39], v[166:169], v[216:219], v[36:39]
	v_mfma_f32_16x16x32_bf16 v[32:35], v[174:177], v[216:219], v[32:35]
	v_mfma_f32_16x16x32_bf16 v[20:23], v[166:169], v[224:227], v[20:23]
	v_mfma_f32_16x16x32_bf16 v[16:19], v[174:177], v[224:227], v[16:19]
	v_mfma_f32_16x16x32_bf16 v[4:7], v[166:169], v[232:235], v[4:7]
	v_mfma_f32_16x16x32_bf16 v[0:3], v[174:177], v[232:235], v[0:3]
	s_setprio 0
	s_barrier
	s_add_i32 s4, 0, 0x18000
	v_add_u32_e32 v128, s4, v151
	s_add_i32 s19, 0, 0x1c000
	ds_read_b128 v[142:145], v128
	ds_read_b128 v[146:149], v128 offset:1024
	ds_read_b128 v[154:157], v128 offset:2048
	ds_read_b128 v[158:161], v128 offset:3072
	v_add_u32_e32 v128, s19, v151
	ds_read_b128 v[162:165], v128
	ds_read_b128 v[166:169], v128 offset:1024
	ds_read_b128 v[170:173], v128 offset:2048
	ds_read_b128 v[174:177], v128 offset:3072
	s_add_u32 s14, s14, s10
	s_addc_u32 s15, s15, s11
	s_mov_b32 m0, s37
	v_lshl_add_u64 v[246:247], s[14:15], 0, v[136:137]
	ds_read_b128 v[178:181], v153 offset:32768
	ds_read_b128 v[208:211], v153 offset:33792
	ds_read_b128 v[212:215], v153 offset:34816
	ds_read_b128 v[216:219], v153 offset:35840
	ds_read_b128 v[220:223], v153 offset:36864
	ds_read_b128 v[224:227], v153 offset:37888
	ds_read_b128 v[228:231], v153 offset:38912
	ds_read_b128 v[232:235], v153 offset:39936
	global_load_lds_dwordx4 v[246:247], off
	v_lshl_add_u64 v[246:247], v[246:247], 0, s[8:9]
	s_mov_b32 m0, s38
	s_nop 0
	global_load_lds_dwordx4 v[246:247], off
	s_waitcnt vmcnt(8)
	s_waitcnt lgkmcnt(0)
	s_barrier
	s_setprio 1
	s_waitcnt lgkmcnt(0)
	v_mfma_f32_16x16x32_bf16 v[120:123], v[142:145], v[178:181], v[120:123]
	v_mfma_f32_16x16x32_bf16 v[124:127], v[154:157], v[178:181], v[124:127]
	v_mfma_f32_16x16x32_bf16 v[108:111], v[142:145], v[212:215], v[108:111]
	v_mfma_f32_16x16x32_bf16 v[104:107], v[154:157], v[212:215], v[104:107]
	v_mfma_f32_16x16x32_bf16 v[92:95], v[142:145], v[220:223], v[92:95]
	v_mfma_f32_16x16x32_bf16 v[88:91], v[154:157], v[220:223], v[88:91]
	v_mfma_f32_16x16x32_bf16 v[76:79], v[142:145], v[228:231], v[76:79]
	v_mfma_f32_16x16x32_bf16 v[72:75], v[154:157], v[228:231], v[72:75]
	v_mfma_f32_16x16x32_bf16 v[120:123], v[146:149], v[208:211], v[120:123]
	v_mfma_f32_16x16x32_bf16 v[124:127], v[158:161], v[208:211], v[124:127]
	v_mfma_f32_16x16x32_bf16 v[108:111], v[146:149], v[216:219], v[108:111]
	v_mfma_f32_16x16x32_bf16 v[104:107], v[158:161], v[216:219], v[104:107]
	v_mfma_f32_16x16x32_bf16 v[92:95], v[146:149], v[224:227], v[92:95]
	v_mfma_f32_16x16x32_bf16 v[88:91], v[158:161], v[224:227], v[88:91]
	v_mfma_f32_16x16x32_bf16 v[76:79], v[146:149], v[232:235], v[76:79]
	v_mfma_f32_16x16x32_bf16 v[72:75], v[158:161], v[232:235], v[72:75]
	v_mfma_f32_16x16x32_bf16 v[116:119], v[162:165], v[178:181], v[116:119]
	v_mfma_f32_16x16x32_bf16 v[112:115], v[170:173], v[178:181], v[112:115]
	v_mfma_f32_16x16x32_bf16 v[100:103], v[162:165], v[212:215], v[100:103]
	v_mfma_f32_16x16x32_bf16 v[96:99], v[170:173], v[212:215], v[96:99]
	v_mfma_f32_16x16x32_bf16 v[84:87], v[162:165], v[220:223], v[84:87]
	v_mfma_f32_16x16x32_bf16 v[80:83], v[170:173], v[220:223], v[80:83]
	v_mfma_f32_16x16x32_bf16 v[68:71], v[162:165], v[228:231], v[68:71]
	v_mfma_f32_16x16x32_bf16 v[64:67], v[170:173], v[228:231], v[64:67]
	v_mfma_f32_16x16x32_bf16 v[116:119], v[166:169], v[208:211], v[116:119]
	v_mfma_f32_16x16x32_bf16 v[112:115], v[174:177], v[208:211], v[112:115]
	v_mfma_f32_16x16x32_bf16 v[100:103], v[166:169], v[216:219], v[100:103]
	v_mfma_f32_16x16x32_bf16 v[96:99], v[174:177], v[216:219], v[96:99]
	v_mfma_f32_16x16x32_bf16 v[84:87], v[166:169], v[224:227], v[84:87]
	v_mfma_f32_16x16x32_bf16 v[80:83], v[174:177], v[224:227], v[80:83]
	v_mfma_f32_16x16x32_bf16 v[68:71], v[166:169], v[232:235], v[68:71]
	v_mfma_f32_16x16x32_bf16 v[64:67], v[174:177], v[232:235], v[64:67]
	s_setprio 0
	s_barrier
; #define PG8_STAGE(bufoff, gbase, voff) do { _Pragma("unroll") for (int _i = 0; _i < 2; ++_i) \
;         __builtin_amdgcn_global_load_lds((const unsigned*)((const char*)(gbase) + _i * rdelta + (voff)), (LAS unsigned*)(lds + (bufoff) + ldsw + _i * 8192), 16, 0, 0); } while (0)
; #define PG8_LDA(dst, b, h) do { _Pragma("unroll") for (int m = 0; m < 4; ++m) _Pragma("unroll") for (int k = 0; k < 2; ++k) dst[m][k] = *(const LAS bf16x8*)(lds + PG8_SA(b, h) + aoff + m * 2048 + k * 1024); } while (0)
; #define PG8_MMA(ai, bj, At, Bt) do { __builtin_amdgcn_s_setprio(1); _Pragma("unroll") for (int m = 0; m < 4; ++m) _Pragma("unroll") for (int n = 0; n < 2; ++n) _Pragma("unroll") for (int k = 0; k < 2; ++k) \
;         acc[ai][bj][m][n] = __builtin_amdgcn_mfma_f32_16x16x32_bf16(Bt[n][k], At[m][k], acc[ai][bj][m][n], 0, 0, 0); __builtin_amdgcn_s_setprio(0); } while (0)
; #define PG8_WAIT_V(n) asm volatile("s_waitcnt vmcnt(" #n ")" ::: "memory")
; #define PG8_WAIT_L(n) asm volatile("s_waitcnt lgkmcnt(" #n ")" ::: "memory")
; #define PG8_BAR __builtin_amdgcn_s_barrier()
; #define PG8_SCHED __builtin_amdgcn_sched_barrier(0)
; template <class Epi, class Sched, bool ALIGN_EPI, bool SP2>
; __device__ __forceinline__ void gemm_phase(LAS unsigned char* lds, const Gemm g, const Sched& S, const Epi& E) {
;     ...
;             PG8_LDA(At, 1, 1); PG8_STAGE(PG8_SB(1, 0), b3, voffB); PG8_STAGE(PG8_SB(1, 1), b3 + hstep, voffB); PG8_STAGE(PG8_SA(1, 0), a3, voffA);
;             PG8_WAIT_V(8); PG8_WAIT_L(0); PG8_BAR; PG8_MMA(1, 0, At, B0); PG8_MMA(1, 1, At, B1); PG8_BAR; PG8_SCHED;
	s_add_i32 s4, s4, s34
	v_lshl_add_u64 v[182:183], v[182:183], 0, s[30:31]
	s_mov_b32 m0, s4
	ds_read_b128 v[178:181], v153 offset:49152
	ds_read_b128 v[208:211], v153 offset:50176
	ds_read_b128 v[212:215], v153 offset:51200
	ds_read_b128 v[216:219], v153 offset:52224
	ds_read_b128 v[220:223], v153 offset:53248
	ds_read_b128 v[224:227], v153 offset:54272
	ds_read_b128 v[228:231], v153 offset:55296
	ds_read_b128 v[232:235], v153 offset:56320
	global_load_lds_dwordx4 v[182:183], off
	v_lshl_add_u64 v[182:183], v[236:237], 0, s[30:31]
	s_add_i32 m0, s4, 0x2000
	s_add_i32 s4, s19, s34
	global_load_lds_dwordx4 v[182:183], off
	v_lshl_add_u64 v[182:183], v[238:239], 0, s[30:31]
	s_mov_b32 m0, s4
	s_nop 0
	global_load_lds_dwordx4 v[182:183], off
	v_lshl_add_u64 v[182:183], v[240:241], 0, s[30:31]
	s_add_i32 m0, s4, 0x2000
	s_nop 0
	global_load_lds_dwordx4 v[182:183], off
	v_lshl_add_u64 v[182:183], v[242:243], 0, s[30:31]
	s_mov_b32 m0, s40
	s_nop 0
	global_load_lds_dwordx4 v[182:183], off
	v_lshl_add_u64 v[182:183], v[244:245], 0, s[30:31]
	s_mov_b32 m0, s41
	s_nop 0
	global_load_lds_dwordx4 v[182:183], off
	s_waitcnt vmcnt(8)
	s_waitcnt lgkmcnt(0)
	s_barrier
	s_setprio 1
	s_waitcnt lgkmcnt(0)
	v_mfma_f32_16x16x32_bf16 v[60:63], v[142:145], v[178:181], v[60:63]
	v_mfma_f32_16x16x32_bf16 v[56:59], v[154:157], v[178:181], v[56:59]
	v_mfma_f32_16x16x32_bf16 v[44:47], v[142:145], v[212:215], v[44:47]
	v_mfma_f32_16x16x32_bf16 v[40:43], v[154:157], v[212:215], v[40:43]
	v_mfma_f32_16x16x32_bf16 v[28:31], v[142:145], v[220:223], v[28:31]
	v_mfma_f32_16x16x32_bf16 v[24:27], v[154:157], v[220:223], v[24:27]
	v_mfma_f32_16x16x32_bf16 v[12:15], v[142:145], v[228:231], v[12:15]
	v_mfma_f32_16x16x32_bf16 v[8:11], v[154:157], v[228:231], v[8:11]
	v_mfma_f32_16x16x32_bf16 v[60:63], v[146:149], v[208:211], v[60:63]
	v_mfma_f32_16x16x32_bf16 v[56:59], v[158:161], v[208:211], v[56:59]
	v_mfma_f32_16x16x32_bf16 v[44:47], v[146:149], v[216:219], v[44:47]
	v_mfma_f32_16x16x32_bf16 v[40:43], v[158:161], v[216:219], v[40:43]
	v_mfma_f32_16x16x32_bf16 v[28:31], v[146:149], v[224:227], v[28:31]
	v_mfma_f32_16x16x32_bf16 v[24:27], v[158:161], v[224:227], v[24:27]
	v_mfma_f32_16x16x32_bf16 v[12:15], v[146:149], v[232:235], v[12:15]
	v_mfma_f32_16x16x32_bf16 v[8:11], v[158:161], v[232:235], v[8:11]
	v_mfma_f32_16x16x32_bf16 v[52:55], v[162:165], v[178:181], v[52:55]
	v_mfma_f32_16x16x32_bf16 v[48:51], v[170:173], v[178:181], v[48:51]
	v_mfma_f32_16x16x32_bf16 v[36:39], v[162:165], v[212:215], v[36:39]
	v_mfma_f32_16x16x32_bf16 v[32:35], v[170:173], v[212:215], v[32:35]
	v_mfma_f32_16x16x32_bf16 v[20:23], v[162:165], v[220:223], v[20:23]
	v_mfma_f32_16x16x32_bf16 v[16:19], v[170:173], v[220:223], v[16:19]
	v_mfma_f32_16x16x32_bf16 v[4:7], v[162:165], v[228:231], v[4:7]
	v_mfma_f32_16x16x32_bf16 v[0:3], v[170:173], v[228:231], v[0:3]
	v_mfma_f32_16x16x32_bf16 v[52:55], v[166:169], v[208:211], v[52:55]
	v_mfma_f32_16x16x32_bf16 v[48:51], v[174:177], v[208:211], v[48:51]
	v_mfma_f32_16x16x32_bf16 v[36:39], v[166:169], v[216:219], v[36:39]
	v_mfma_f32_16x16x32_bf16 v[32:35], v[174:177], v[216:219], v[32:35]
	v_mfma_f32_16x16x32_bf16 v[20:23], v[166:169], v[224:227], v[20:23]
	v_mfma_f32_16x16x32_bf16 v[16:19], v[174:177], v[224:227], v[16:19]
	v_mfma_f32_16x16x32_bf16 v[4:7], v[166:169], v[232:235], v[4:7]
	v_mfma_f32_16x16x32_bf16 v[0:3], v[174:177], v[232:235], v[0:3]
	s_setprio 0
	s_barrier
	s_add_u32 s6, s6, 0x100
	s_addc_u32 s7, s7, 0
	s_add_u32 s16, s16, 0x100
	s_addc_u32 s17, s17, 0
	s_cmp_ge_i32 s18, s62
	s_mov_b32 s4, s18
	s_cbranch_scc0 .LBB0_805

; #define PG8_STAGE(bufoff, gbase, voff) do { _Pragma("unroll") for (int _i = 0; _i < 2; ++_i) \
;         __builtin_amdgcn_global_load_lds((const unsigned*)((const char*)(gbase) + _i * rdelta + (voff)), (LAS unsigned*)(lds + (bufoff) + ldsw + _i * 8192), 16, 0, 0); } while (0)
; #define PG8_LDA(dst, b, h) do { _Pragma("unroll") for (int m = 0; m < 4; ++m) _Pragma("unroll") for (int k = 0; k < 2; ++k) dst[m][k] = *(const LAS bf16x8*)(lds + PG8_SA(b, h) + aoff + m * 2048 + k * 1024); } while (0)
; #define PG8_LDB(dst, b, h) do { _Pragma("unroll") for (int n = 0; n < 2; ++n) _Pragma("unroll") for (int k = 0; k < 2; ++k) dst[n][k] = *(const LAS bf16x8*)(lds + PG8_SB(b, h) + boff + n * 2048 + k * 1024); } while (0)
; #define PG8_MMA(ai, bj, At, Bt) do { __builtin_amdgcn_s_setprio(1); _Pragma("unroll") for (int m = 0; m < 4; ++m) _Pragma("unroll") for (int n = 0; n < 2; ++n) _Pragma("unroll") for (int k = 0; k < 2; ++k) \
;         acc[ai][bj][m][n] = __builtin_amdgcn_mfma_f32_16x16x32_bf16(Bt[n][k], At[m][k], acc[ai][bj][m][n], 0, 0, 0); __builtin_amdgcn_s_setprio(0); } while (0)
; #define PG8_WAIT_V(n) asm volatile("s_waitcnt vmcnt(" #n ")" ::: "memory")
; #define PG8_WAIT_L(n) asm volatile("s_waitcnt lgkmcnt(" #n ")" ::: "memory")
; #define PG8_BAR __builtin_amdgcn_s_barrier()
; #define PG8_SCHED __builtin_amdgcn_sched_barrier(0)
; template <class Epi, class Sched, bool ALIGN_EPI, bool SP2>
; __device__ __forceinline__ void gemm_phase(LAS unsigned char* lds, const Gemm g, const Sched& S, const Epi& E) {
;     ...
;             const bool last = (t == nt - 2);
;             const char* a1 = cA + (size_t)(t + 1) * kstep;
;             const char* a2 = last ? nA : cA + (size_t)(t + 2) * kstep; const char* b2 = last ? nB : cB + (size_t)(t + 2) * kstep;
;             const char* a3 = a2 + kstep; const char* b3 = b2 + kstep;
;             PG8_LDB(B0, 0, 0); PG8_LDB(B1, 0, 1); PG8_SCHED; PG8_LDA(At, 0, 0); PG8_STAGE(PG8_SA(1, 1), a1 + hstep, voffA);
;             PG8_WAIT_V(8); PG8_WAIT_L(0); PG8_BAR; PG8_MMA(0, 0, At, B0); PG8_MMA(0, 1, At, B1); PG8_BAR; PG8_SCHED;
;             PG8_LDA(At, 0, 1); PG8_STAGE(PG8_SB(0, 0), b2, voffB); PG8_STAGE(PG8_SB(0, 1), b2 + hstep, voffB); PG8_STAGE(PG8_SA(0, 0), a2, voffA);
;             PG8_WAIT_V(8); PG8_WAIT_L(0); PG8_BAR; PG8_MMA(1, 0, At, B0); PG8_MMA(1, 1, At, B1); PG8_BAR; PG8_SCHED;
.LBB0_862:
	s_add_i32 s63, s4, 2
	s_add_u32 s16, s14, 0x80
	s_addc_u32 s17, s15, 0
	s_add_i32 s66, 0, 0x10000
	s_cmp_eq_u32 s57, s4
	s_cselect_b32 s17, s7, s17
	s_cselect_b32 s16, s6, s16
	v_add_u32_e32 v128, s66, v145
	s_cselect_b32 s65, s55, s19
	s_cselect_b32 s64, s54, s18
	s_add_i32 s4, 0, 0x14000
	ds_read_b128 v[148:151], v128
	ds_read_b128 v[152:155], v128 offset:1024
	ds_read_b128 v[156:159], v128 offset:2048
	ds_read_b128 v[160:163], v128 offset:3072
	v_add_u32_e32 v128, s4, v145
	ds_read_b128 v[164:167], v128
	ds_read_b128 v[168:171], v128 offset:1024
	ds_read_b128 v[172:175], v128 offset:2048
	ds_read_b128 v[176:179], v128 offset:3072
	v_lshl_add_u64 v[142:143], s[14:15], 0, v[138:139]
	s_add_i32 m0, s35, 0xc000
	ds_read_b128 v[180:183], v147
	ds_read_b128 v[208:211], v147 offset:1024
	ds_read_b128 v[212:215], v147 offset:2048
	ds_read_b128 v[216:219], v147 offset:3072
	ds_read_b128 v[220:223], v147 offset:4096
	ds_read_b128 v[224:227], v147 offset:5120
	ds_read_b128 v[228:231], v147 offset:6144
	ds_read_b128 v[232:235], v147 offset:7168
	global_load_lds_dwordx4 v[142:143], off
	v_lshl_add_u64 v[142:143], s[14:15], 0, v[140:141]
	s_add_i32 m0, s35, 0xe000
	s_nop 0
	global_load_lds_dwordx4 v[142:143], off
	s_waitcnt vmcnt(8)
	s_waitcnt lgkmcnt(0)
	s_barrier
	s_setprio 1
	s_waitcnt lgkmcnt(0)
	v_mfma_f32_16x16x32_bf16 v[120:123], v[148:151], v[180:183], v[120:123]
	v_mfma_f32_16x16x32_bf16 v[124:127], v[156:159], v[180:183], v[124:127]
	v_mfma_f32_16x16x32_bf16 v[108:111], v[148:151], v[212:215], v[108:111]
	v_mfma_f32_16x16x32_bf16 v[104:107], v[156:159], v[212:215], v[104:107]
	v_mfma_f32_16x16x32_bf16 v[92:95], v[148:151], v[220:223], v[92:95]
	v_mfma_f32_16x16x32_bf16 v[88:91], v[156:159], v[220:223], v[88:91]
	v_mfma_f32_16x16x32_bf16 v[76:79], v[148:151], v[228:231], v[76:79]
	v_mfma_f32_16x16x32_bf16 v[72:75], v[156:159], v[228:231], v[72:75]
	v_mfma_f32_16x16x32_bf16 v[120:123], v[152:155], v[208:211], v[120:123]
	v_mfma_f32_16x16x32_bf16 v[124:127], v[160:163], v[208:211], v[124:127]
	v_mfma_f32_16x16x32_bf16 v[108:111], v[152:155], v[216:219], v[108:111]
	v_mfma_f32_16x16x32_bf16 v[104:107], v[160:163], v[216:219], v[104:107]
	v_mfma_f32_16x16x32_bf16 v[92:95], v[152:155], v[224:227], v[92:95]
	v_mfma_f32_16x16x32_bf16 v[88:91], v[160:163], v[224:227], v[88:91]
	v_mfma_f32_16x16x32_bf16 v[76:79], v[152:155], v[232:235], v[76:79]
	v_mfma_f32_16x16x32_bf16 v[72:75], v[160:163], v[232:235], v[72:75]
	v_mfma_f32_16x16x32_bf16 v[116:119], v[164:167], v[180:183], v[116:119]
	v_mfma_f32_16x16x32_bf16 v[112:115], v[172:175], v[180:183], v[112:115]
	v_mfma_f32_16x16x32_bf16 v[100:103], v[164:167], v[212:215], v[100:103]
	v_mfma_f32_16x16x32_bf16 v[96:99], v[172:175], v[212:215], v[96:99]
	v_mfma_f32_16x16x32_bf16 v[84:87], v[164:167], v[220:223], v[84:87]
	v_mfma_f32_16x16x32_bf16 v[80:83], v[172:175], v[220:223], v[80:83]
	v_mfma_f32_16x16x32_bf16 v[68:71], v[164:167], v[228:231], v[68:71]
	v_mfma_f32_16x16x32_bf16 v[64:67], v[172:175], v[228:231], v[64:67]
	v_mfma_f32_16x16x32_bf16 v[116:119], v[168:171], v[208:211], v[116:119]
	v_mfma_f32_16x16x32_bf16 v[112:115], v[176:179], v[208:211], v[112:115]
	v_mfma_f32_16x16x32_bf16 v[100:103], v[168:171], v[216:219], v[100:103]
	v_mfma_f32_16x16x32_bf16 v[96:99], v[176:179], v[216:219], v[96:99]
	v_mfma_f32_16x16x32_bf16 v[84:87], v[168:171], v[224:227], v[84:87]
	v_mfma_f32_16x16x32_bf16 v[80:83], v[176:179], v[224:227], v[80:83]
	v_mfma_f32_16x16x32_bf16 v[68:71], v[168:171], v[232:235], v[68:71]
	v_mfma_f32_16x16x32_bf16 v[64:67], v[176:179], v[232:235], v[64:67]
	s_setprio 0
	s_barrier
	s_add_i32 s66, s66, s34
	v_lshl_add_u64 v[142:143], s[64:65], 0, v[130:131]
	s_mov_b32 m0, s66
	ds_read_b128 v[180:183], v147 offset:16384
	ds_read_b128 v[208:211], v147 offset:17408
	ds_read_b128 v[212:215], v147 offset:18432
	ds_read_b128 v[216:219], v147 offset:19456
	ds_read_b128 v[220:223], v147 offset:20480
	ds_read_b128 v[224:227], v147 offset:21504
	ds_read_b128 v[228:231], v147 offset:22528
	ds_read_b128 v[232:235], v147 offset:23552
	global_load_lds_dwordx4 v[142:143], off
	s_add_i32 m0, s66, 0x2000
	s_add_u32 s64, s64, s10
	v_lshl_add_u64 v[236:237], v[142:143], 0, s[8:9]
	s_addc_u32 s65, s65, s11
	s_add_i32 s4, s4, s34
	global_load_lds_dwordx4 v[236:237], off
	v_lshl_add_u64 v[238:239], s[64:65], 0, v[130:131]
	s_mov_b32 m0, s4
	v_lshl_add_u64 v[240:241], v[238:239], 0, s[8:9]
	global_load_lds_dwordx4 v[238:239], off
	s_add_i32 m0, s4, 0x2000
	v_lshl_add_u64 v[242:243], s[16:17], 0, v[136:137]
	global_load_lds_dwordx4 v[240:241], off
	s_mov_b32 m0, s35
	v_lshl_add_u64 v[244:245], v[242:243], 0, s[8:9]
	global_load_lds_dwordx4 v[242:243], off
	s_mov_b32 m0, s36
	s_nop 0
	global_load_lds_dwordx4 v[244:245], off
	s_waitcnt vmcnt(8)
	s_waitcnt lgkmcnt(0)
	s_barrier
; #define PG8_STAGE(bufoff, gbase, voff) do { _Pragma("unroll") for (int _i = 0; _i < 2; ++_i) \
;         __builtin_amdgcn_global_load_lds((const unsigned*)((const char*)(gbase) + _i * rdelta + (voff)), (LAS unsigned*)(lds + (bufoff) + ldsw + _i * 8192), 16, 0, 0); } while (0)
; #define PG8_LDA(dst, b, h) do { _Pragma("unroll") for (int m = 0; m < 4; ++m) _Pragma("unroll") for (int k = 0; k < 2; ++k) dst[m][k] = *(const LAS bf16x8*)(lds + PG8_SA(b, h) + aoff + m * 2048 + k * 1024); } while (0)
; #define PG8_LDB(dst, b, h) do { _Pragma("unroll") for (int n = 0; n < 2; ++n) _Pragma("unroll") for (int k = 0; k < 2; ++k) dst[n][k] = *(const LAS bf16x8*)(lds + PG8_SB(b, h) + boff + n * 2048 + k * 1024); } while (0)
; #define PG8_MMA(ai, bj, At, Bt) do { __builtin_amdgcn_s_setprio(1); _Pragma("unroll") for (int m = 0; m < 4; ++m) _Pragma("unroll") for (int n = 0; n < 2; ++n) _Pragma("unroll") for (int k = 0; k < 2; ++k) \
;         acc[ai][bj][m][n] = __builtin_amdgcn_mfma_f32_16x16x32_bf16(Bt[n][k], At[m][k], acc[ai][bj][m][n], 0, 0, 0); __builtin_amdgcn_s_setprio(0); } while (0)
; #define PG8_WAIT_V(n) asm volatile("s_waitcnt vmcnt(" #n ")" ::: "memory")
; #define PG8_WAIT_L(n) asm volatile("s_waitcnt lgkmcnt(" #n ")" ::: "memory")
; #define PG8_BAR __builtin_amdgcn_s_barrier()
; #define PG8_SCHED __builtin_amdgcn_sched_barrier(0)
; template <class Epi, class Sched, bool ALIGN_EPI, bool SP2>
; __device__ __forceinline__ void gemm_phase(LAS unsigned char* lds, const Gemm g, const Sched& S, const Epi& E) {
;     ...
;             PG8_WAIT_V(8); PG8_WAIT_L(0); PG8_BAR; PG8_MMA(0, 0, At, B0); PG8_MMA(0, 1, At, B1); PG8_BAR; PG8_SCHED;
;             PG8_LDA(At, 0, 1); PG8_STAGE(PG8_SB(0, 0), b2, voffB); PG8_STAGE(PG8_SB(0, 1), b2 + hstep, voffB); PG8_STAGE(PG8_SA(0, 0), a2, voffA);
;             PG8_WAIT_V(8); PG8_WAIT_L(0); PG8_BAR; PG8_MMA(1, 0, At, B0); PG8_MMA(1, 1, At, B1); PG8_BAR; PG8_SCHED;
;             PG8_LDB(B0, 1, 0); PG8_LDB(B1, 1, 1); PG8_SCHED; PG8_LDA(At, 1, 0); PG8_STAGE(PG8_SA(0, 1), a2 + hstep, voffA);
;             PG8_WAIT_V(8); PG8_WAIT_L(0); PG8_BAR; PG8_MMA(0, 0, At, B0); PG8_MMA(0, 1, At, B1); PG8_BAR; PG8_SCHED;
	s_setprio 1
	s_waitcnt lgkmcnt(0)
	v_mfma_f32_16x16x32_bf16 v[60:63], v[148:151], v[180:183], v[60:63]
	v_mfma_f32_16x16x32_bf16 v[56:59], v[156:159], v[180:183], v[56:59]
	v_mfma_f32_16x16x32_bf16 v[44:47], v[148:151], v[212:215], v[44:47]
	v_mfma_f32_16x16x32_bf16 v[40:43], v[156:159], v[212:215], v[40:43]
	v_mfma_f32_16x16x32_bf16 v[28:31], v[148:151], v[220:223], v[28:31]
	v_mfma_f32_16x16x32_bf16 v[24:27], v[156:159], v[220:223], v[24:27]
	v_mfma_f32_16x16x32_bf16 v[12:15], v[148:151], v[228:231], v[12:15]
	v_mfma_f32_16x16x32_bf16 v[8:11], v[156:159], v[228:231], v[8:11]
	v_mfma_f32_16x16x32_bf16 v[60:63], v[152:155], v[208:211], v[60:63]
	v_mfma_f32_16x16x32_bf16 v[56:59], v[160:163], v[208:211], v[56:59]
	v_mfma_f32_16x16x32_bf16 v[44:47], v[152:155], v[216:219], v[44:47]
	v_mfma_f32_16x16x32_bf16 v[40:43], v[160:163], v[216:219], v[40:43]
	v_mfma_f32_16x16x32_bf16 v[28:31], v[152:155], v[224:227], v[28:31]
	v_mfma_f32_16x16x32_bf16 v[24:27], v[160:163], v[224:227], v[24:27]
	v_mfma_f32_16x16x32_bf16 v[12:15], v[152:155], v[232:235], v[12:15]
	v_mfma_f32_16x16x32_bf16 v[8:11], v[160:163], v[232:235], v[8:11]
	v_mfma_f32_16x16x32_bf16 v[52:55], v[164:167], v[180:183], v[52:55]
	v_mfma_f32_16x16x32_bf16 v[48:51], v[172:175], v[180:183], v[48:51]
	v_mfma_f32_16x16x32_bf16 v[36:39], v[164:167], v[212:215], v[36:39]
	v_mfma_f32_16x16x32_bf16 v[32:35], v[172:175], v[212:215], v[32:35]
	v_mfma_f32_16x16x32_bf16 v[20:23], v[164:167], v[220:223], v[20:23]
	v_mfma_f32_16x16x32_bf16 v[16:19], v[172:175], v[220:223], v[16:19]
	v_mfma_f32_16x16x32_bf16 v[4:7], v[164:167], v[228:231], v[4:7]
	v_mfma_f32_16x16x32_bf16 v[0:3], v[172:175], v[228:231], v[0:3]
	v_mfma_f32_16x16x32_bf16 v[52:55], v[168:171], v[208:211], v[52:55]
	v_mfma_f32_16x16x32_bf16 v[48:51], v[176:179], v[208:211], v[48:51]
	v_mfma_f32_16x16x32_bf16 v[36:39], v[168:171], v[216:219], v[36:39]
	v_mfma_f32_16x16x32_bf16 v[32:35], v[176:179], v[216:219], v[32:35]
	v_mfma_f32_16x16x32_bf16 v[20:23], v[168:171], v[224:227], v[20:23]
	v_mfma_f32_16x16x32_bf16 v[16:19], v[176:179], v[224:227], v[16:19]
	v_mfma_f32_16x16x32_bf16 v[4:7], v[168:171], v[232:235], v[4:7]
	v_mfma_f32_16x16x32_bf16 v[0:3], v[176:179], v[232:235], v[0:3]
	s_setprio 0
	s_barrier
	s_add_i32 s4, 0, 0x18000
	v_add_u32_e32 v128, s4, v145
	s_add_i32 s64, 0, 0x1c000
	ds_read_b128 v[148:151], v128
	ds_read_b128 v[152:155], v128 offset:1024
	ds_read_b128 v[156:159], v128 offset:2048
	ds_read_b128 v[160:163], v128 offset:3072
	v_add_u32_e32 v128, s64, v145
	ds_read_b128 v[164:167], v128
	ds_read_b128 v[168:171], v128 offset:1024
	ds_read_b128 v[172:175], v128 offset:2048
	ds_read_b128 v[176:179], v128 offset:3072
	s_add_u32 s16, s16, s10
	s_addc_u32 s17, s17, s11
	s_mov_b32 m0, s37
	v_lshl_add_u64 v[246:247], s[16:17], 0, v[136:137]
	ds_read_b128 v[180:183], v147 offset:32768
	ds_read_b128 v[208:211], v147 offset:33792
	ds_read_b128 v[212:215], v147 offset:34816
	ds_read_b128 v[216:219], v147 offset:35840
	ds_read_b128 v[220:223], v147 offset:36864
	ds_read_b128 v[224:227], v147 offset:37888
	ds_read_b128 v[228:231], v147 offset:38912
	ds_read_b128 v[232:235], v147 offset:39936
	global_load_lds_dwordx4 v[246:247], off
	v_lshl_add_u64 v[246:247], v[246:247], 0, s[8:9]
	s_mov_b32 m0, s38
	s_nop 0
	global_load_lds_dwordx4 v[246:247], off
	s_waitcnt vmcnt(8)
	s_waitcnt lgkmcnt(0)
	s_barrier
	s_setprio 1
	s_waitcnt lgkmcnt(0)
	v_mfma_f32_16x16x32_bf16 v[120:123], v[148:151], v[180:183], v[120:123]
	v_mfma_f32_16x16x32_bf16 v[124:127], v[156:159], v[180:183], v[124:127]
	v_mfma_f32_16x16x32_bf16 v[108:111], v[148:151], v[212:215], v[108:111]
	v_mfma_f32_16x16x32_bf16 v[104:107], v[156:159], v[212:215], v[104:107]
	v_mfma_f32_16x16x32_bf16 v[92:95], v[148:151], v[220:223], v[92:95]
	v_mfma_f32_16x16x32_bf16 v[88:91], v[156:159], v[220:223], v[88:91]
	v_mfma_f32_16x16x32_bf16 v[76:79], v[148:151], v[228:231], v[76:79]
	v_mfma_f32_16x16x32_bf16 v[72:75], v[156:159], v[228:231], v[72:75]
	v_mfma_f32_16x16x32_bf16 v[120:123], v[152:155], v[208:211], v[120:123]
	v_mfma_f32_16x16x32_bf16 v[124:127], v[160:163], v[208:211], v[124:127]
	v_mfma_f32_16x16x32_bf16 v[108:111], v[152:155], v[216:219], v[108:111]
	v_mfma_f32_16x16x32_bf16 v[104:107], v[160:163], v[216:219], v[104:107]
	v_mfma_f32_16x16x32_bf16 v[92:95], v[152:155], v[224:227], v[92:95]
	v_mfma_f32_16x16x32_bf16 v[88:91], v[160:163], v[224:227], v[88:91]
	v_mfma_f32_16x16x32_bf16 v[76:79], v[152:155], v[232:235], v[76:79]
	v_mfma_f32_16x16x32_bf16 v[72:75], v[160:163], v[232:235], v[72:75]
	v_mfma_f32_16x16x32_bf16 v[116:119], v[164:167], v[180:183], v[116:119]
	v_mfma_f32_16x16x32_bf16 v[112:115], v[172:175], v[180:183], v[112:115]
	v_mfma_f32_16x16x32_bf16 v[100:103], v[164:167], v[212:215], v[100:103]
	v_mfma_f32_16x16x32_bf16 v[96:99], v[172:175], v[212:215], v[96:99]
	v_mfma_f32_16x16x32_bf16 v[84:87], v[164:167], v[220:223], v[84:87]
	v_mfma_f32_16x16x32_bf16 v[80:83], v[172:175], v[220:223], v[80:83]
	v_mfma_f32_16x16x32_bf16 v[68:71], v[164:167], v[228:231], v[68:71]
	v_mfma_f32_16x16x32_bf16 v[64:67], v[172:175], v[228:231], v[64:67]
	v_mfma_f32_16x16x32_bf16 v[116:119], v[168:171], v[208:211], v[116:119]
	v_mfma_f32_16x16x32_bf16 v[112:115], v[176:179], v[208:211], v[112:115]
	v_mfma_f32_16x16x32_bf16 v[100:103], v[168:171], v[216:219], v[100:103]
	v_mfma_f32_16x16x32_bf16 v[96:99], v[176:179], v[216:219], v[96:99]
	v_mfma_f32_16x16x32_bf16 v[84:87], v[168:171], v[224:227], v[84:87]
	v_mfma_f32_16x16x32_bf16 v[80:83], v[176:179], v[224:227], v[80:83]
	v_mfma_f32_16x16x32_bf16 v[68:71], v[168:171], v[232:235], v[68:71]
	v_mfma_f32_16x16x32_bf16 v[64:67], v[176:179], v[232:235], v[64:67]
	s_setprio 0
	s_barrier
; #define PG8_STAGE(bufoff, gbase, voff) do { _Pragma("unroll") for (int _i = 0; _i < 2; ++_i) \
;         __builtin_amdgcn_global_load_lds((const unsigned*)((const char*)(gbase) + _i * rdelta + (voff)), (LAS unsigned*)(lds + (bufoff) + ldsw + _i * 8192), 16, 0, 0); } while (0)
; #define PG8_LDA(dst, b, h) do { _Pragma("unroll") for (int m = 0; m < 4; ++m) _Pragma("unroll") for (int k = 0; k < 2; ++k) dst[m][k] = *(const LAS bf16x8*)(lds + PG8_SA(b, h) + aoff + m * 2048 + k * 1024); } while (0)
; #define PG8_MMA(ai, bj, At, Bt) do { __builtin_amdgcn_s_setprio(1); _Pragma("unroll") for (int m = 0; m < 4; ++m) _Pragma("unroll") for (int n = 0; n < 2; ++n) _Pragma("unroll") for (int k = 0; k < 2; ++k) \
;         acc[ai][bj][m][n] = __builtin_amdgcn_mfma_f32_16x16x32_bf16(Bt[n][k], At[m][k], acc[ai][bj][m][n], 0, 0, 0); __builtin_amdgcn_s_setprio(0); } while (0)
; #define PG8_WAIT_V(n) asm volatile("s_waitcnt vmcnt(" #n ")" ::: "memory")
; #define PG8_WAIT_L(n) asm volatile("s_waitcnt lgkmcnt(" #n ")" ::: "memory")
; #define PG8_BAR __builtin_amdgcn_s_barrier()
; #define PG8_SCHED __builtin_amdgcn_sched_barrier(0)
; template <class Epi, class Sched, bool ALIGN_EPI, bool SP2>
; __device__ __forceinline__ void gemm_phase(LAS unsigned char* lds, const Gemm g, const Sched& S, const Epi& E) {
;     ...
;             PG8_LDA(At, 1, 1); PG8_STAGE(PG8_SB(1, 0), b3, voffB); PG8_STAGE(PG8_SB(1, 1), b3 + hstep, voffB); PG8_STAGE(PG8_SA(1, 0), a3, voffA);
;             PG8_WAIT_V(8); PG8_WAIT_L(0); PG8_BAR; PG8_MMA(1, 0, At, B0); PG8_MMA(1, 1, At, B1); PG8_BAR; PG8_SCHED;
	s_add_i32 s4, s4, s34
	v_lshl_add_u64 v[142:143], v[142:143], 0, s[30:31]
	s_mov_b32 m0, s4
	ds_read_b128 v[180:183], v147 offset:49152
	ds_read_b128 v[208:211], v147 offset:50176
	ds_read_b128 v[212:215], v147 offset:51200
	ds_read_b128 v[216:219], v147 offset:52224
	ds_read_b128 v[220:223], v147 offset:53248
	ds_read_b128 v[224:227], v147 offset:54272
	ds_read_b128 v[228:231], v147 offset:55296
	ds_read_b128 v[232:235], v147 offset:56320
	global_load_lds_dwordx4 v[142:143], off
	v_lshl_add_u64 v[142:143], v[236:237], 0, s[30:31]
	s_add_i32 m0, s4, 0x2000
	s_add_i32 s4, s64, s34
	global_load_lds_dwordx4 v[142:143], off
	v_lshl_add_u64 v[142:143], v[238:239], 0, s[30:31]
	s_mov_b32 m0, s4
	s_nop 0
	global_load_lds_dwordx4 v[142:143], off
	v_lshl_add_u64 v[142:143], v[240:241], 0, s[30:31]
	s_add_i32 m0, s4, 0x2000
	s_nop 0
	global_load_lds_dwordx4 v[142:143], off
	v_lshl_add_u64 v[142:143], v[242:243], 0, s[30:31]
	s_mov_b32 m0, s40
	s_nop 0
	global_load_lds_dwordx4 v[142:143], off
	v_lshl_add_u64 v[142:143], v[244:245], 0, s[30:31]
	s_mov_b32 m0, s41
	s_nop 0
	global_load_lds_dwordx4 v[142:143], off
	s_waitcnt vmcnt(8)
	s_waitcnt lgkmcnt(0)
	s_barrier
	s_setprio 1
	s_waitcnt lgkmcnt(0)
	v_mfma_f32_16x16x32_bf16 v[60:63], v[148:151], v[180:183], v[60:63]
	v_mfma_f32_16x16x32_bf16 v[56:59], v[156:159], v[180:183], v[56:59]
	v_mfma_f32_16x16x32_bf16 v[44:47], v[148:151], v[212:215], v[44:47]
	v_mfma_f32_16x16x32_bf16 v[40:43], v[156:159], v[212:215], v[40:43]
	v_mfma_f32_16x16x32_bf16 v[28:31], v[148:151], v[220:223], v[28:31]
	v_mfma_f32_16x16x32_bf16 v[24:27], v[156:159], v[220:223], v[24:27]
	v_mfma_f32_16x16x32_bf16 v[12:15], v[148:151], v[228:231], v[12:15]
	v_mfma_f32_16x16x32_bf16 v[8:11], v[156:159], v[228:231], v[8:11]
	v_mfma_f32_16x16x32_bf16 v[60:63], v[152:155], v[208:211], v[60:63]
	v_mfma_f32_16x16x32_bf16 v[56:59], v[160:163], v[208:211], v[56:59]
	v_mfma_f32_16x16x32_bf16 v[44:47], v[152:155], v[216:219], v[44:47]
	v_mfma_f32_16x16x32_bf16 v[40:43], v[160:163], v[216:219], v[40:43]
	v_mfma_f32_16x16x32_bf16 v[28:31], v[152:155], v[224:227], v[28:31]
	v_mfma_f32_16x16x32_bf16 v[24:27], v[160:163], v[224:227], v[24:27]
	v_mfma_f32_16x16x32_bf16 v[12:15], v[152:155], v[232:235], v[12:15]
	v_mfma_f32_16x16x32_bf16 v[8:11], v[160:163], v[232:235], v[8:11]
	v_mfma_f32_16x16x32_bf16 v[52:55], v[164:167], v[180:183], v[52:55]
	v_mfma_f32_16x16x32_bf16 v[48:51], v[172:175], v[180:183], v[48:51]
	v_mfma_f32_16x16x32_bf16 v[36:39], v[164:167], v[212:215], v[36:39]
	v_mfma_f32_16x16x32_bf16 v[32:35], v[172:175], v[212:215], v[32:35]
	v_mfma_f32_16x16x32_bf16 v[20:23], v[164:167], v[220:223], v[20:23]
	v_mfma_f32_16x16x32_bf16 v[16:19], v[172:175], v[220:223], v[16:19]
	v_mfma_f32_16x16x32_bf16 v[4:7], v[164:167], v[228:231], v[4:7]
	v_mfma_f32_16x16x32_bf16 v[0:3], v[172:175], v[228:231], v[0:3]
	v_mfma_f32_16x16x32_bf16 v[52:55], v[168:171], v[208:211], v[52:55]
	v_mfma_f32_16x16x32_bf16 v[48:51], v[176:179], v[208:211], v[48:51]
	v_mfma_f32_16x16x32_bf16 v[36:39], v[168:171], v[216:219], v[36:39]
	v_mfma_f32_16x16x32_bf16 v[32:35], v[176:179], v[216:219], v[32:35]
	v_mfma_f32_16x16x32_bf16 v[20:23], v[168:171], v[224:227], v[20:23]
	v_mfma_f32_16x16x32_bf16 v[16:19], v[176:179], v[224:227], v[16:19]
	v_mfma_f32_16x16x32_bf16 v[4:7], v[168:171], v[232:235], v[4:7]
	v_mfma_f32_16x16x32_bf16 v[0:3], v[176:179], v[232:235], v[0:3]
	s_setprio 0
	s_barrier
	s_add_u32 s14, s14, 0x100
	s_addc_u32 s15, s15, 0
	s_add_u32 s18, s18, 0x100
	s_addc_u32 s19, s19, 0
	s_cmp_ge_i32 s63, s56
	s_mov_b32 s4, s63
	s_cbranch_scc0 .LBB0_862

; #define PG8_STAGE(bufoff, gbase, voff) do { _Pragma("unroll") for (int _i = 0; _i < 2; ++_i) \
;         __builtin_amdgcn_global_load_lds((const unsigned*)((const char*)(gbase) + _i * rdelta + (voff)), (LAS unsigned*)(lds + (bufoff) + ldsw + _i * 8192), 16, 0, 0); } while (0)
; #define PG8_LDA(dst, b, h) do { _Pragma("unroll") for (int m = 0; m < 4; ++m) _Pragma("unroll") for (int k = 0; k < 2; ++k) dst[m][k] = *(const LAS bf16x8*)(lds + PG8_SA(b, h) + aoff + m * 2048 + k * 1024); } while (0)
; #define PG8_LDB(dst, b, h) do { _Pragma("unroll") for (int n = 0; n < 2; ++n) _Pragma("unroll") for (int k = 0; k < 2; ++k) dst[n][k] = *(const LAS bf16x8*)(lds + PG8_SB(b, h) + boff + n * 2048 + k * 1024); } while (0)
; #define PG8_MMA(ai, bj, At, Bt) do { __builtin_amdgcn_s_setprio(1); _Pragma("unroll") for (int m = 0; m < 4; ++m) _Pragma("unroll") for (int n = 0; n < 2; ++n) _Pragma("unroll") for (int k = 0; k < 2; ++k) \
;         acc[ai][bj][m][n] = __builtin_amdgcn_mfma_f32_16x16x32_bf16(Bt[n][k], At[m][k], acc[ai][bj][m][n], 0, 0, 0); __builtin_amdgcn_s_setprio(0); } while (0)
; #define PG8_WAIT_V(n) asm volatile("s_waitcnt vmcnt(" #n ")" ::: "memory")
; #define PG8_WAIT_L(n) asm volatile("s_waitcnt lgkmcnt(" #n ")" ::: "memory")
; #define PG8_BAR __builtin_amdgcn_s_barrier()
; #define PG8_SCHED __builtin_amdgcn_sched_barrier(0)
; template <class Epi, class Sched, bool ALIGN_EPI, bool SP2>
; __device__ __forceinline__ void gemm_phase(LAS unsigned char* lds, const Gemm g, const Sched& S, const Epi& E) {
;     ...
;             const bool last = (t == nt - 2);
;             const char* a1 = cA + (size_t)(t + 1) * kstep;
;             const char* a2 = last ? nA : cA + (size_t)(t + 2) * kstep; const char* b2 = last ? nB : cB + (size_t)(t + 2) * kstep;
;             const char* a3 = a2 + kstep; const char* b3 = b2 + kstep;
;             PG8_LDB(B0, 0, 0); PG8_LDB(B1, 0, 1); PG8_SCHED; PG8_LDA(At, 0, 0); PG8_STAGE(PG8_SA(1, 1), a1 + hstep, voffA);
;             PG8_WAIT_V(8); PG8_WAIT_L(0); PG8_BAR; PG8_MMA(0, 0, At, B0); PG8_MMA(0, 1, At, B1); PG8_BAR; PG8_SCHED;
;             PG8_LDA(At, 0, 1); PG8_STAGE(PG8_SB(0, 0), b2, voffB); PG8_STAGE(PG8_SB(0, 1), b2 + hstep, voffB); PG8_STAGE(PG8_SA(0, 0), a2, voffA);
;             PG8_WAIT_V(8); PG8_WAIT_L(0); PG8_BAR; PG8_MMA(1, 0, At, B0); PG8_MMA(1, 1, At, B1); PG8_BAR; PG8_SCHED;
.LBB0_1169:
	s_add_i32 s69, s4, 2
	s_add_u32 s16, s14, 0x80
	s_addc_u32 s17, s15, 0
	s_add_i32 s72, 0, 0x10000
	s_cmp_eq_u32 s63, s4
	s_cselect_b32 s17, s7, s17
	s_cselect_b32 s16, s6, s16
	v_add_u32_e32 v144, s72, v147
	s_cselect_b32 s71, s61, s19
	s_cselect_b32 s70, s60, s18
	s_add_i32 s4, 0, 0x14000
	ds_read_b128 v[140:143], v144
	ds_read_b128 v[150:153], v144 offset:1024
	ds_read_b128 v[154:157], v144 offset:2048
	ds_read_b128 v[158:161], v144 offset:3072
	v_add_u32_e32 v144, s4, v147
	ds_read_b128 v[162:165], v144
	ds_read_b128 v[166:169], v144 offset:1024
	ds_read_b128 v[170:173], v144 offset:2048
	ds_read_b128 v[174:177], v144 offset:3072
	v_lshl_add_u64 v[144:145], s[14:15], 0, v[136:137]
	s_add_i32 m0, s37, 0xc000
	ds_read_b128 v[178:181], v149
	ds_read_b128 v[208:211], v149 offset:1024
	ds_read_b128 v[212:215], v149 offset:2048
	ds_read_b128 v[216:219], v149 offset:3072
	ds_read_b128 v[220:223], v149 offset:4096
	ds_read_b128 v[224:227], v149 offset:5120
	ds_read_b128 v[228:231], v149 offset:6144
	ds_read_b128 v[232:235], v149 offset:7168
	global_load_lds_dwordx4 v[144:145], off
	v_lshl_add_u64 v[144:145], s[14:15], 0, v[138:139]
	s_add_i32 m0, s37, 0xe000
	s_nop 0
	global_load_lds_dwordx4 v[144:145], off
	s_waitcnt vmcnt(8)
	s_waitcnt lgkmcnt(0)
	s_barrier
	s_setprio 1
	s_waitcnt lgkmcnt(0)
	v_mfma_f32_16x16x32_bf16 v[120:123], v[140:143], v[178:181], v[120:123]
	v_mfma_f32_16x16x32_bf16 v[124:127], v[154:157], v[178:181], v[124:127]
	v_mfma_f32_16x16x32_bf16 v[108:111], v[140:143], v[212:215], v[108:111]
	v_mfma_f32_16x16x32_bf16 v[104:107], v[154:157], v[212:215], v[104:107]
	v_mfma_f32_16x16x32_bf16 v[92:95], v[140:143], v[220:223], v[92:95]
	v_mfma_f32_16x16x32_bf16 v[88:91], v[154:157], v[220:223], v[88:91]
	v_mfma_f32_16x16x32_bf16 v[76:79], v[140:143], v[228:231], v[76:79]
	v_mfma_f32_16x16x32_bf16 v[72:75], v[154:157], v[228:231], v[72:75]
	v_mfma_f32_16x16x32_bf16 v[120:123], v[150:153], v[208:211], v[120:123]
	v_mfma_f32_16x16x32_bf16 v[124:127], v[158:161], v[208:211], v[124:127]
	v_mfma_f32_16x16x32_bf16 v[108:111], v[150:153], v[216:219], v[108:111]
	v_mfma_f32_16x16x32_bf16 v[104:107], v[158:161], v[216:219], v[104:107]
	v_mfma_f32_16x16x32_bf16 v[92:95], v[150:153], v[224:227], v[92:95]
	v_mfma_f32_16x16x32_bf16 v[88:91], v[158:161], v[224:227], v[88:91]
	v_mfma_f32_16x16x32_bf16 v[76:79], v[150:153], v[232:235], v[76:79]
	v_mfma_f32_16x16x32_bf16 v[72:75], v[158:161], v[232:235], v[72:75]
	v_mfma_f32_16x16x32_bf16 v[116:119], v[162:165], v[178:181], v[116:119]
	v_mfma_f32_16x16x32_bf16 v[112:115], v[170:173], v[178:181], v[112:115]
	v_mfma_f32_16x16x32_bf16 v[100:103], v[162:165], v[212:215], v[100:103]
	v_mfma_f32_16x16x32_bf16 v[96:99], v[170:173], v[212:215], v[96:99]
	v_mfma_f32_16x16x32_bf16 v[84:87], v[162:165], v[220:223], v[84:87]
	v_mfma_f32_16x16x32_bf16 v[80:83], v[170:173], v[220:223], v[80:83]
	v_mfma_f32_16x16x32_bf16 v[68:71], v[162:165], v[228:231], v[68:71]
	v_mfma_f32_16x16x32_bf16 v[64:67], v[170:173], v[228:231], v[64:67]
	v_mfma_f32_16x16x32_bf16 v[116:119], v[166:169], v[208:211], v[116:119]
	v_mfma_f32_16x16x32_bf16 v[112:115], v[174:177], v[208:211], v[112:115]
	v_mfma_f32_16x16x32_bf16 v[100:103], v[166:169], v[216:219], v[100:103]
	v_mfma_f32_16x16x32_bf16 v[96:99], v[174:177], v[216:219], v[96:99]
	v_mfma_f32_16x16x32_bf16 v[84:87], v[166:169], v[224:227], v[84:87]
	v_mfma_f32_16x16x32_bf16 v[80:83], v[174:177], v[224:227], v[80:83]
	v_mfma_f32_16x16x32_bf16 v[68:71], v[166:169], v[232:235], v[68:71]
	v_mfma_f32_16x16x32_bf16 v[64:67], v[174:177], v[232:235], v[64:67]
	s_setprio 0
	s_barrier
	s_add_i32 s72, s72, s36
	v_lshl_add_u64 v[144:145], s[70:71], 0, v[128:129]
	s_mov_b32 m0, s72
	ds_read_b128 v[178:181], v149 offset:16384
	ds_read_b128 v[208:211], v149 offset:17408
	ds_read_b128 v[212:215], v149 offset:18432
	ds_read_b128 v[216:219], v149 offset:19456
	ds_read_b128 v[220:223], v149 offset:20480
	ds_read_b128 v[224:227], v149 offset:21504
	ds_read_b128 v[228:231], v149 offset:22528
	ds_read_b128 v[232:235], v149 offset:23552
	global_load_lds_dwordx4 v[144:145], off
	s_add_i32 m0, s72, 0x2000
	s_add_u32 s70, s70, s10
	v_lshl_add_u64 v[182:183], v[144:145], 0, s[8:9]
	s_addc_u32 s71, s71, s11
	s_add_i32 s4, s4, s36
	global_load_lds_dwordx4 v[182:183], off
	v_lshl_add_u64 v[236:237], s[70:71], 0, v[128:129]
	s_mov_b32 m0, s4
	v_lshl_add_u64 v[238:239], v[236:237], 0, s[8:9]
	global_load_lds_dwordx4 v[236:237], off
	s_add_i32 m0, s4, 0x2000
	v_lshl_add_u64 v[240:241], s[16:17], 0, v[130:131]
	global_load_lds_dwordx4 v[238:239], off
	s_mov_b32 m0, s37
	v_lshl_add_u64 v[242:243], v[240:241], 0, s[8:9]
	global_load_lds_dwordx4 v[240:241], off
	s_mov_b32 m0, s40
	s_nop 0
	global_load_lds_dwordx4 v[242:243], off
	s_waitcnt vmcnt(8)
	s_waitcnt lgkmcnt(0)
	s_barrier
; #define PG8_STAGE(bufoff, gbase, voff) do { _Pragma("unroll") for (int _i = 0; _i < 2; ++_i) \
;         __builtin_amdgcn_global_load_lds((const unsigned*)((const char*)(gbase) + _i * rdelta + (voff)), (LAS unsigned*)(lds + (bufoff) + ldsw + _i * 8192), 16, 0, 0); } while (0)
; #define PG8_LDA(dst, b, h) do { _Pragma("unroll") for (int m = 0; m < 4; ++m) _Pragma("unroll") for (int k = 0; k < 2; ++k) dst[m][k] = *(const LAS bf16x8*)(lds + PG8_SA(b, h) + aoff + m * 2048 + k * 1024); } while (0)
; #define PG8_LDB(dst, b, h) do { _Pragma("unroll") for (int n = 0; n < 2; ++n) _Pragma("unroll") for (int k = 0; k < 2; ++k) dst[n][k] = *(const LAS bf16x8*)(lds + PG8_SB(b, h) + boff + n * 2048 + k * 1024); } while (0)
; #define PG8_MMA(ai, bj, At, Bt) do { __builtin_amdgcn_s_setprio(1); _Pragma("unroll") for (int m = 0; m < 4; ++m) _Pragma("unroll") for (int n = 0; n < 2; ++n) _Pragma("unroll") for (int k = 0; k < 2; ++k) \
;         acc[ai][bj][m][n] = __builtin_amdgcn_mfma_f32_16x16x32_bf16(Bt[n][k], At[m][k], acc[ai][bj][m][n], 0, 0, 0); __builtin_amdgcn_s_setprio(0); } while (0)
; #define PG8_WAIT_V(n) asm volatile("s_waitcnt vmcnt(" #n ")" ::: "memory")
; #define PG8_WAIT_L(n) asm volatile("s_waitcnt lgkmcnt(" #n ")" ::: "memory")
; #define PG8_BAR __builtin_amdgcn_s_barrier()
; #define PG8_SCHED __builtin_amdgcn_sched_barrier(0)
; template <class Epi, class Sched, bool ALIGN_EPI, bool SP2>
; __device__ __forceinline__ void gemm_phase(LAS unsigned char* lds, const Gemm g, const Sched& S, const Epi& E) {
;     ...
;             PG8_WAIT_V(8); PG8_WAIT_L(0); PG8_BAR; PG8_MMA(0, 0, At, B0); PG8_MMA(0, 1, At, B1); PG8_BAR; PG8_SCHED;
;             PG8_LDA(At, 0, 1); PG8_STAGE(PG8_SB(0, 0), b2, voffB); PG8_STAGE(PG8_SB(0, 1), b2 + hstep, voffB); PG8_STAGE(PG8_SA(0, 0), a2, voffA);
;             PG8_WAIT_V(8); PG8_WAIT_L(0); PG8_BAR; PG8_MMA(1, 0, At, B0); PG8_MMA(1, 1, At, B1); PG8_BAR; PG8_SCHED;
;             PG8_LDB(B0, 1, 0); PG8_LDB(B1, 1, 1); PG8_SCHED; PG8_LDA(At, 1, 0); PG8_STAGE(PG8_SA(0, 1), a2 + hstep, voffA);
;             PG8_WAIT_V(8); PG8_WAIT_L(0); PG8_BAR; PG8_MMA(0, 0, At, B0); PG8_MMA(0, 1, At, B1); PG8_BAR; PG8_SCHED;
	s_setprio 1
	s_waitcnt lgkmcnt(0)
	v_mfma_f32_16x16x32_bf16 v[60:63], v[140:143], v[178:181], v[60:63]
	v_mfma_f32_16x16x32_bf16 v[56:59], v[154:157], v[178:181], v[56:59]
	v_mfma_f32_16x16x32_bf16 v[44:47], v[140:143], v[212:215], v[44:47]
	v_mfma_f32_16x16x32_bf16 v[40:43], v[154:157], v[212:215], v[40:43]
	v_mfma_f32_16x16x32_bf16 v[28:31], v[140:143], v[220:223], v[28:31]
	v_mfma_f32_16x16x32_bf16 v[24:27], v[154:157], v[220:223], v[24:27]
	v_mfma_f32_16x16x32_bf16 v[12:15], v[140:143], v[228:231], v[12:15]
	v_mfma_f32_16x16x32_bf16 v[8:11], v[154:157], v[228:231], v[8:11]
	v_mfma_f32_16x16x32_bf16 v[60:63], v[150:153], v[208:211], v[60:63]
	v_mfma_f32_16x16x32_bf16 v[56:59], v[158:161], v[208:211], v[56:59]
	v_mfma_f32_16x16x32_bf16 v[44:47], v[150:153], v[216:219], v[44:47]
	v_mfma_f32_16x16x32_bf16 v[40:43], v[158:161], v[216:219], v[40:43]
	v_mfma_f32_16x16x32_bf16 v[28:31], v[150:153], v[224:227], v[28:31]
	v_mfma_f32_16x16x32_bf16 v[24:27], v[158:161], v[224:227], v[24:27]
	v_mfma_f32_16x16x32_bf16 v[12:15], v[150:153], v[232:235], v[12:15]
	v_mfma_f32_16x16x32_bf16 v[8:11], v[158:161], v[232:235], v[8:11]
	v_mfma_f32_16x16x32_bf16 v[52:55], v[162:165], v[178:181], v[52:55]
	v_mfma_f32_16x16x32_bf16 v[48:51], v[170:173], v[178:181], v[48:51]
	v_mfma_f32_16x16x32_bf16 v[36:39], v[162:165], v[212:215], v[36:39]
	v_mfma_f32_16x16x32_bf16 v[32:35], v[170:173], v[212:215], v[32:35]
	v_mfma_f32_16x16x32_bf16 v[20:23], v[162:165], v[220:223], v[20:23]
	v_mfma_f32_16x16x32_bf16 v[16:19], v[170:173], v[220:223], v[16:19]
	v_mfma_f32_16x16x32_bf16 v[4:7], v[162:165], v[228:231], v[4:7]
	v_mfma_f32_16x16x32_bf16 v[0:3], v[170:173], v[228:231], v[0:3]
	v_mfma_f32_16x16x32_bf16 v[52:55], v[166:169], v[208:211], v[52:55]
	v_mfma_f32_16x16x32_bf16 v[48:51], v[174:177], v[208:211], v[48:51]
	v_mfma_f32_16x16x32_bf16 v[36:39], v[166:169], v[216:219], v[36:39]
	v_mfma_f32_16x16x32_bf16 v[32:35], v[174:177], v[216:219], v[32:35]
	v_mfma_f32_16x16x32_bf16 v[20:23], v[166:169], v[224:227], v[20:23]
	v_mfma_f32_16x16x32_bf16 v[16:19], v[174:177], v[224:227], v[16:19]
	v_mfma_f32_16x16x32_bf16 v[4:7], v[166:169], v[232:235], v[4:7]
	v_mfma_f32_16x16x32_bf16 v[0:3], v[174:177], v[232:235], v[0:3]
	s_setprio 0
	s_barrier
	s_add_i32 s4, 0, 0x18000
	s_add_i32 s70, 0, 0x1c000
	v_add_u32_e32 v158, s4, v147
	v_add_u32_e32 v174, s70, v147
	ds_read_b128 v[140:143], v158
	ds_read_b128 v[150:153], v158 offset:1024
	ds_read_b128 v[154:157], v158 offset:2048
	ds_read_b128 v[158:161], v158 offset:3072
	ds_read_b128 v[162:165], v174
	ds_read_b128 v[166:169], v174 offset:1024
	ds_read_b128 v[170:173], v174 offset:2048
	ds_read_b128 v[174:177], v174 offset:3072
	s_add_u32 s16, s16, s10
	s_addc_u32 s17, s17, s11
	s_mov_b32 m0, s41
	v_lshl_add_u64 v[244:245], s[16:17], 0, v[130:131]
	ds_read_b128 v[178:181], v149 offset:32768
	ds_read_b128 v[208:211], v149 offset:33792
	ds_read_b128 v[212:215], v149 offset:34816
	ds_read_b128 v[216:219], v149 offset:35840
	ds_read_b128 v[220:223], v149 offset:36864
	ds_read_b128 v[224:227], v149 offset:37888
	ds_read_b128 v[228:231], v149 offset:38912
	ds_read_b128 v[232:235], v149 offset:39936
	global_load_lds_dwordx4 v[244:245], off
	v_lshl_add_u64 v[244:245], v[244:245], 0, s[8:9]
	s_mov_b32 m0, s62
	s_nop 0
	global_load_lds_dwordx4 v[244:245], off
	s_waitcnt vmcnt(8)
	s_waitcnt lgkmcnt(0)
	s_barrier
	s_setprio 1
	s_waitcnt lgkmcnt(0)
	v_mfma_f32_16x16x32_bf16 v[120:123], v[140:143], v[178:181], v[120:123]
	v_mfma_f32_16x16x32_bf16 v[124:127], v[154:157], v[178:181], v[124:127]
	v_mfma_f32_16x16x32_bf16 v[108:111], v[140:143], v[212:215], v[108:111]
	v_mfma_f32_16x16x32_bf16 v[104:107], v[154:157], v[212:215], v[104:107]
	v_mfma_f32_16x16x32_bf16 v[92:95], v[140:143], v[220:223], v[92:95]
	v_mfma_f32_16x16x32_bf16 v[88:91], v[154:157], v[220:223], v[88:91]
	v_mfma_f32_16x16x32_bf16 v[76:79], v[140:143], v[228:231], v[76:79]
	v_mfma_f32_16x16x32_bf16 v[72:75], v[154:157], v[228:231], v[72:75]
	v_mfma_f32_16x16x32_bf16 v[120:123], v[150:153], v[208:211], v[120:123]
	v_mfma_f32_16x16x32_bf16 v[124:127], v[158:161], v[208:211], v[124:127]
	v_mfma_f32_16x16x32_bf16 v[108:111], v[150:153], v[216:219], v[108:111]
	v_mfma_f32_16x16x32_bf16 v[104:107], v[158:161], v[216:219], v[104:107]
	v_mfma_f32_16x16x32_bf16 v[92:95], v[150:153], v[224:227], v[92:95]
	v_mfma_f32_16x16x32_bf16 v[88:91], v[158:161], v[224:227], v[88:91]
	v_mfma_f32_16x16x32_bf16 v[76:79], v[150:153], v[232:235], v[76:79]
	v_mfma_f32_16x16x32_bf16 v[72:75], v[158:161], v[232:235], v[72:75]
	v_mfma_f32_16x16x32_bf16 v[116:119], v[162:165], v[178:181], v[116:119]
	v_mfma_f32_16x16x32_bf16 v[112:115], v[170:173], v[178:181], v[112:115]
	v_mfma_f32_16x16x32_bf16 v[100:103], v[162:165], v[212:215], v[100:103]
	v_mfma_f32_16x16x32_bf16 v[96:99], v[170:173], v[212:215], v[96:99]
	v_mfma_f32_16x16x32_bf16 v[84:87], v[162:165], v[220:223], v[84:87]
	v_mfma_f32_16x16x32_bf16 v[80:83], v[170:173], v[220:223], v[80:83]
	v_mfma_f32_16x16x32_bf16 v[68:71], v[162:165], v[228:231], v[68:71]
	v_mfma_f32_16x16x32_bf16 v[64:67], v[170:173], v[228:231], v[64:67]
	v_mfma_f32_16x16x32_bf16 v[116:119], v[166:169], v[208:211], v[116:119]
	v_mfma_f32_16x16x32_bf16 v[112:115], v[174:177], v[208:211], v[112:115]
	v_mfma_f32_16x16x32_bf16 v[100:103], v[166:169], v[216:219], v[100:103]
	v_mfma_f32_16x16x32_bf16 v[96:99], v[174:177], v[216:219], v[96:99]
	v_mfma_f32_16x16x32_bf16 v[84:87], v[166:169], v[224:227], v[84:87]
	v_mfma_f32_16x16x32_bf16 v[80:83], v[174:177], v[224:227], v[80:83]
	v_mfma_f32_16x16x32_bf16 v[68:71], v[166:169], v[232:235], v[68:71]
	v_mfma_f32_16x16x32_bf16 v[64:67], v[174:177], v[232:235], v[64:67]
	s_setprio 0
	s_barrier
; #define PG8_STAGE(bufoff, gbase, voff) do { _Pragma("unroll") for (int _i = 0; _i < 2; ++_i) \
;         __builtin_amdgcn_global_load_lds((const unsigned*)((const char*)(gbase) + _i * rdelta + (voff)), (LAS unsigned*)(lds + (bufoff) + ldsw + _i * 8192), 16, 0, 0); } while (0)
; #define PG8_LDA(dst, b, h) do { _Pragma("unroll") for (int m = 0; m < 4; ++m) _Pragma("unroll") for (int k = 0; k < 2; ++k) dst[m][k] = *(const LAS bf16x8*)(lds + PG8_SA(b, h) + aoff + m * 2048 + k * 1024); } while (0)
; #define PG8_MMA(ai, bj, At, Bt) do { __builtin_amdgcn_s_setprio(1); _Pragma("unroll") for (int m = 0; m < 4; ++m) _Pragma("unroll") for (int n = 0; n < 2; ++n) _Pragma("unroll") for (int k = 0; k < 2; ++k) \
;         acc[ai][bj][m][n] = __builtin_amdgcn_mfma_f32_16x16x32_bf16(Bt[n][k], At[m][k], acc[ai][bj][m][n], 0, 0, 0); __builtin_amdgcn_s_setprio(0); } while (0)
; #define PG8_WAIT_V(n) asm volatile("s_waitcnt vmcnt(" #n ")" ::: "memory")
; #define PG8_WAIT_L(n) asm volatile("s_waitcnt lgkmcnt(" #n ")" ::: "memory")
; #define PG8_BAR __builtin_amdgcn_s_barrier()
; #define PG8_SCHED __builtin_amdgcn_sched_barrier(0)
; template <class Epi, class Sched, bool ALIGN_EPI, bool SP2>
; __device__ __forceinline__ void gemm_phase(LAS unsigned char* lds, const Gemm g, const Sched& S, const Epi& E) {
;     ...
;             PG8_LDA(At, 1, 1); PG8_STAGE(PG8_SB(1, 0), b3, voffB); PG8_STAGE(PG8_SB(1, 1), b3 + hstep, voffB); PG8_STAGE(PG8_SA(1, 0), a3, voffA);
;             PG8_WAIT_V(8); PG8_WAIT_L(0); PG8_BAR; PG8_MMA(1, 0, At, B0); PG8_MMA(1, 1, At, B1); PG8_BAR; PG8_SCHED;
	s_add_i32 s4, s4, s36
	v_lshl_add_u64 v[144:145], v[144:145], 0, s[30:31]
	s_mov_b32 m0, s4
	ds_read_b128 v[178:181], v149 offset:49152
	ds_read_b128 v[208:211], v149 offset:50176
	ds_read_b128 v[212:215], v149 offset:51200
	ds_read_b128 v[216:219], v149 offset:52224
	ds_read_b128 v[220:223], v149 offset:53248
	ds_read_b128 v[224:227], v149 offset:54272
	ds_read_b128 v[228:231], v149 offset:55296
	ds_read_b128 v[232:235], v149 offset:56320
	global_load_lds_dwordx4 v[144:145], off
	v_lshl_add_u64 v[144:145], v[182:183], 0, s[30:31]
	s_add_i32 m0, s4, 0x2000
	s_add_i32 s4, s70, s36
	global_load_lds_dwordx4 v[144:145], off
	v_lshl_add_u64 v[144:145], v[236:237], 0, s[30:31]
	s_mov_b32 m0, s4
	s_nop 0
	global_load_lds_dwordx4 v[144:145], off
	v_lshl_add_u64 v[144:145], v[238:239], 0, s[30:31]
	s_add_i32 m0, s4, 0x2000
	s_nop 0
	global_load_lds_dwordx4 v[144:145], off
	v_lshl_add_u64 v[144:145], v[240:241], 0, s[30:31]
	s_mov_b32 m0, s22
	s_nop 0
	global_load_lds_dwordx4 v[144:145], off
	v_lshl_add_u64 v[144:145], v[242:243], 0, s[30:31]
	s_mov_b32 m0, s23
	s_nop 0
	global_load_lds_dwordx4 v[144:145], off
	s_waitcnt vmcnt(8)
	s_waitcnt lgkmcnt(0)
	s_barrier
	s_setprio 1
	s_waitcnt lgkmcnt(0)
	v_mfma_f32_16x16x32_bf16 v[60:63], v[140:143], v[178:181], v[60:63]
	v_mfma_f32_16x16x32_bf16 v[56:59], v[154:157], v[178:181], v[56:59]
	v_mfma_f32_16x16x32_bf16 v[44:47], v[140:143], v[212:215], v[44:47]
	v_mfma_f32_16x16x32_bf16 v[40:43], v[154:157], v[212:215], v[40:43]
	v_mfma_f32_16x16x32_bf16 v[28:31], v[140:143], v[220:223], v[28:31]
	v_mfma_f32_16x16x32_bf16 v[24:27], v[154:157], v[220:223], v[24:27]
	v_mfma_f32_16x16x32_bf16 v[12:15], v[140:143], v[228:231], v[12:15]
	v_mfma_f32_16x16x32_bf16 v[8:11], v[154:157], v[228:231], v[8:11]
	v_mfma_f32_16x16x32_bf16 v[60:63], v[150:153], v[208:211], v[60:63]
	v_mfma_f32_16x16x32_bf16 v[56:59], v[158:161], v[208:211], v[56:59]
	v_mfma_f32_16x16x32_bf16 v[44:47], v[150:153], v[216:219], v[44:47]
	v_mfma_f32_16x16x32_bf16 v[40:43], v[158:161], v[216:219], v[40:43]
	v_mfma_f32_16x16x32_bf16 v[28:31], v[150:153], v[224:227], v[28:31]
	v_mfma_f32_16x16x32_bf16 v[24:27], v[158:161], v[224:227], v[24:27]
	v_mfma_f32_16x16x32_bf16 v[12:15], v[150:153], v[232:235], v[12:15]
	v_mfma_f32_16x16x32_bf16 v[8:11], v[158:161], v[232:235], v[8:11]
	v_mfma_f32_16x16x32_bf16 v[52:55], v[162:165], v[178:181], v[52:55]
	v_mfma_f32_16x16x32_bf16 v[48:51], v[170:173], v[178:181], v[48:51]
	v_mfma_f32_16x16x32_bf16 v[36:39], v[162:165], v[212:215], v[36:39]
	v_mfma_f32_16x16x32_bf16 v[32:35], v[170:173], v[212:215], v[32:35]
	v_mfma_f32_16x16x32_bf16 v[20:23], v[162:165], v[220:223], v[20:23]
	v_mfma_f32_16x16x32_bf16 v[16:19], v[170:173], v[220:223], v[16:19]
	v_mfma_f32_16x16x32_bf16 v[4:7], v[162:165], v[228:231], v[4:7]
	v_mfma_f32_16x16x32_bf16 v[0:3], v[170:173], v[228:231], v[0:3]
	v_mfma_f32_16x16x32_bf16 v[52:55], v[166:169], v[208:211], v[52:55]
	v_mfma_f32_16x16x32_bf16 v[48:51], v[174:177], v[208:211], v[48:51]
	v_mfma_f32_16x16x32_bf16 v[36:39], v[166:169], v[216:219], v[36:39]
	v_mfma_f32_16x16x32_bf16 v[32:35], v[174:177], v[216:219], v[32:35]
	v_mfma_f32_16x16x32_bf16 v[20:23], v[166:169], v[224:227], v[20:23]
	v_mfma_f32_16x16x32_bf16 v[16:19], v[174:177], v[224:227], v[16:19]
	v_mfma_f32_16x16x32_bf16 v[4:7], v[166:169], v[232:235], v[4:7]
	v_mfma_f32_16x16x32_bf16 v[0:3], v[174:177], v[232:235], v[0:3]
	s_setprio 0
	s_barrier
	s_add_u32 s14, s14, 0x100
	s_addc_u32 s15, s15, 0
	s_add_u32 s18, s18, 0x100
	s_addc_u32 s19, s19, 0
	s_cmp_ge_i32 s69, s38
	s_mov_b32 s4, s69
	s_cbranch_scc0 .LBB0_1169

; #define PG8_STAGE(bufoff, gbase, voff) do { _Pragma("unroll") for (int _i = 0; _i < 2; ++_i) \
;         __builtin_amdgcn_global_load_lds((const unsigned*)((const char*)(gbase) + _i * rdelta + (voff)), (LAS unsigned*)(lds + (bufoff) + ldsw + _i * 8192), 16, 0, 0); } while (0)
; #define PG8_LDA(dst, b, h) do { _Pragma("unroll") for (int m = 0; m < 4; ++m) _Pragma("unroll") for (int k = 0; k < 2; ++k) dst[m][k] = *(const LAS bf16x8*)(lds + PG8_SA(b, h) + aoff + m * 2048 + k * 1024); } while (0)
; #define PG8_LDB(dst, b, h) do { _Pragma("unroll") for (int n = 0; n < 2; ++n) _Pragma("unroll") for (int k = 0; k < 2; ++k) dst[n][k] = *(const LAS bf16x8*)(lds + PG8_SB(b, h) + boff + n * 2048 + k * 1024); } while (0)
; #define PG8_MMA(ai, bj, At, Bt) do { __builtin_amdgcn_s_setprio(1); _Pragma("unroll") for (int m = 0; m < 4; ++m) _Pragma("unroll") for (int n = 0; n < 2; ++n) _Pragma("unroll") for (int k = 0; k < 2; ++k) \
;         acc[ai][bj][m][n] = __builtin_amdgcn_mfma_f32_16x16x32_bf16(Bt[n][k], At[m][k], acc[ai][bj][m][n], 0, 0, 0); __builtin_amdgcn_s_setprio(0); } while (0)
; #define PG8_WAIT_V(n) asm volatile("s_waitcnt vmcnt(" #n ")" ::: "memory")
; #define PG8_WAIT_L(n) asm volatile("s_waitcnt lgkmcnt(" #n ")" ::: "memory")
; #define PG8_BAR __builtin_amdgcn_s_barrier()
; #define PG8_SCHED __builtin_amdgcn_sched_barrier(0)
; template <class Epi, class Sched, bool ALIGN_EPI, bool SP2>
; __device__ __forceinline__ void gemm_phase(LAS unsigned char* lds, const Gemm g, const Sched& S, const Epi& E) {
;     ...
;             const bool last = (t == nt - 2);
;             const char* a1 = cA + (size_t)(t + 1) * kstep;
;             const char* a2 = last ? nA : cA + (size_t)(t + 2) * kstep; const char* b2 = last ? nB : cB + (size_t)(t + 2) * kstep;
;             const char* a3 = a2 + kstep; const char* b3 = b2 + kstep;
;             PG8_LDB(B0, 0, 0); PG8_LDB(B1, 0, 1); PG8_SCHED; PG8_LDA(At, 0, 0); PG8_STAGE(PG8_SA(1, 1), a1 + hstep, voffA);
;             PG8_WAIT_V(8); PG8_WAIT_L(0); PG8_BAR; PG8_MMA(0, 0, At, B0); PG8_MMA(0, 1, At, B1); PG8_BAR; PG8_SCHED;
;             PG8_LDA(At, 0, 1); PG8_STAGE(PG8_SB(0, 0), b2, voffB); PG8_STAGE(PG8_SB(0, 1), b2 + hstep, voffB); PG8_STAGE(PG8_SA(0, 0), a2, voffA);
;             PG8_WAIT_V(8); PG8_WAIT_L(0); PG8_BAR; PG8_MMA(1, 0, At, B0); PG8_MMA(1, 1, At, B1); PG8_BAR; PG8_SCHED;
.LBB0_1274:
	s_add_i32 s75, s4, 2
	s_add_u32 s18, s14, s16
	s_addc_u32 s19, s15, s17
	s_add_u32 s18, s18, 0x100
	s_addc_u32 s19, s19, 0
	s_add_u32 s76, s73, s16
	s_addc_u32 s77, s74, s17
	s_add_i32 s78, 0, 0x10000
	s_cmp_eq_u32 s69, s4
	s_cselect_b32 s19, s7, s19
	s_cselect_b32 s18, s6, s18
	v_add_u32_e32 v128, s78, v152
	s_cselect_b32 s77, s65, s77
	s_cselect_b32 s76, s64, s76
	s_add_i32 s4, 0, 0x14000
	ds_read_b128 v[156:159], v128
	ds_read_b128 v[160:163], v128 offset:1024
	ds_read_b128 v[164:167], v128 offset:2048
	ds_read_b128 v[168:171], v128 offset:3072
	v_add_u32_e32 v128, s4, v152
	ds_read_b128 v[172:175], v128
	ds_read_b128 v[176:179], v128 offset:1024
	ds_read_b128 v[180:183], v128 offset:2048
	ds_read_b128 v[208:211], v128 offset:3072
	v_lshl_add_u64 v[130:131], v[146:147], 0, s[16:17]
	s_add_i32 m0, s35, 0xc000
	ds_read_b128 v[212:215], v154
	ds_read_b128 v[216:219], v154 offset:1024
	ds_read_b128 v[220:223], v154 offset:2048
	ds_read_b128 v[224:227], v154 offset:3072
	ds_read_b128 v[228:231], v154 offset:4096
	ds_read_b128 v[232:235], v154 offset:5120
	ds_read_b128 v[236:239], v154 offset:6144
	ds_read_b128 v[240:243], v154 offset:7168
	global_load_lds_dwordx4 v[130:131], off
	v_lshl_add_u64 v[130:131], v[148:149], 0, s[16:17]
	s_add_i32 m0, s35, 0xe000
	s_nop 0
	global_load_lds_dwordx4 v[130:131], off
	s_waitcnt vmcnt(8)
	s_waitcnt lgkmcnt(0)
	s_barrier
	s_setprio 1
	s_waitcnt lgkmcnt(0)
	v_mfma_f32_16x16x32_bf16 v[120:123], v[156:159], v[212:215], v[120:123]
	v_mfma_f32_16x16x32_bf16 v[124:127], v[164:167], v[212:215], v[124:127]
	v_mfma_f32_16x16x32_bf16 v[104:107], v[156:159], v[220:223], v[104:107]
	v_mfma_f32_16x16x32_bf16 v[108:111], v[164:167], v[220:223], v[108:111]
	v_mfma_f32_16x16x32_bf16 v[88:91], v[156:159], v[228:231], v[88:91]
	v_mfma_f32_16x16x32_bf16 v[92:95], v[164:167], v[228:231], v[92:95]
	v_mfma_f32_16x16x32_bf16 v[72:75], v[156:159], v[236:239], v[72:75]
	v_mfma_f32_16x16x32_bf16 v[76:79], v[164:167], v[236:239], v[76:79]
	v_mfma_f32_16x16x32_bf16 v[120:123], v[160:163], v[216:219], v[120:123]
	v_mfma_f32_16x16x32_bf16 v[124:127], v[168:171], v[216:219], v[124:127]
	v_mfma_f32_16x16x32_bf16 v[104:107], v[160:163], v[224:227], v[104:107]
	v_mfma_f32_16x16x32_bf16 v[108:111], v[168:171], v[224:227], v[108:111]
	v_mfma_f32_16x16x32_bf16 v[88:91], v[160:163], v[232:235], v[88:91]
	v_mfma_f32_16x16x32_bf16 v[92:95], v[168:171], v[232:235], v[92:95]
	v_mfma_f32_16x16x32_bf16 v[72:75], v[160:163], v[240:243], v[72:75]
	v_mfma_f32_16x16x32_bf16 v[76:79], v[168:171], v[240:243], v[76:79]
	v_mfma_f32_16x16x32_bf16 v[112:115], v[172:175], v[212:215], v[112:115]
	v_mfma_f32_16x16x32_bf16 v[116:119], v[180:183], v[212:215], v[116:119]
	v_mfma_f32_16x16x32_bf16 v[96:99], v[172:175], v[220:223], v[96:99]
	v_mfma_f32_16x16x32_bf16 v[100:103], v[180:183], v[220:223], v[100:103]
	v_mfma_f32_16x16x32_bf16 v[80:83], v[172:175], v[228:231], v[80:83]
	v_mfma_f32_16x16x32_bf16 v[84:87], v[180:183], v[228:231], v[84:87]
	v_mfma_f32_16x16x32_bf16 v[64:67], v[172:175], v[236:239], v[64:67]
	v_mfma_f32_16x16x32_bf16 v[68:71], v[180:183], v[236:239], v[68:71]
	v_mfma_f32_16x16x32_bf16 v[112:115], v[176:179], v[216:219], v[112:115]
	v_mfma_f32_16x16x32_bf16 v[116:119], v[208:211], v[216:219], v[116:119]
	v_mfma_f32_16x16x32_bf16 v[96:99], v[176:179], v[224:227], v[96:99]
	v_mfma_f32_16x16x32_bf16 v[100:103], v[208:211], v[224:227], v[100:103]
	v_mfma_f32_16x16x32_bf16 v[80:83], v[176:179], v[232:235], v[80:83]
	v_mfma_f32_16x16x32_bf16 v[84:87], v[208:211], v[232:235], v[84:87]
	v_mfma_f32_16x16x32_bf16 v[64:67], v[176:179], v[240:243], v[64:67]
	v_mfma_f32_16x16x32_bf16 v[68:71], v[208:211], v[240:243], v[68:71]
	s_setprio 0
	s_barrier
	s_add_i32 s78, s78, s34
	v_lshl_add_u64 v[130:131], s[76:77], 0, v[136:137]
	s_mov_b32 m0, s78
	ds_read_b128 v[212:215], v154 offset:16384
	ds_read_b128 v[216:219], v154 offset:17408
	ds_read_b128 v[220:223], v154 offset:18432
	ds_read_b128 v[224:227], v154 offset:19456
	ds_read_b128 v[228:231], v154 offset:20480
	ds_read_b128 v[232:235], v154 offset:21504
	ds_read_b128 v[236:239], v154 offset:22528
	ds_read_b128 v[240:243], v154 offset:23552
	global_load_lds_dwordx4 v[130:131], off
	s_add_i32 m0, s78, 0x2000
	s_add_u32 s76, s76, s12
	v_lshl_add_u64 v[244:245], v[130:131], 0, s[10:11]
	s_addc_u32 s77, s77, s13
	s_add_i32 s4, s4, s34
	global_load_lds_dwordx4 v[244:245], off
	v_lshl_add_u64 v[246:247], s[76:77], 0, v[136:137]
	s_mov_b32 m0, s4
	v_lshl_add_u64 v[248:249], v[246:247], 0, s[10:11]
	global_load_lds_dwordx4 v[246:247], off
	s_add_i32 m0, s4, 0x2000
	v_lshl_add_u64 v[250:251], s[18:19], 0, v[138:139]
	global_load_lds_dwordx4 v[248:249], off
	s_mov_b32 m0, s35
	v_lshl_add_u64 v[190:191], v[250:251], 0, s[10:11]
	global_load_lds_dwordx4 v[250:251], off
	s_mov_b32 m0, s36
	s_nop 0
	global_load_lds_dwordx4 v[190:191], off
	s_waitcnt vmcnt(8)
	s_waitcnt lgkmcnt(0)
	s_barrier
; #define PG8_STAGE(bufoff, gbase, voff) do { _Pragma("unroll") for (int _i = 0; _i < 2; ++_i) \
;         __builtin_amdgcn_global_load_lds((const unsigned*)((const char*)(gbase) + _i * rdelta + (voff)), (LAS unsigned*)(lds + (bufoff) + ldsw + _i * 8192), 16, 0, 0); } while (0)
; #define PG8_LDA(dst, b, h) do { _Pragma("unroll") for (int m = 0; m < 4; ++m) _Pragma("unroll") for (int k = 0; k < 2; ++k) dst[m][k] = *(const LAS bf16x8*)(lds + PG8_SA(b, h) + aoff + m * 2048 + k * 1024); } while (0)
; #define PG8_LDB(dst, b, h) do { _Pragma("unroll") for (int n = 0; n < 2; ++n) _Pragma("unroll") for (int k = 0; k < 2; ++k) dst[n][k] = *(const LAS bf16x8*)(lds + PG8_SB(b, h) + boff + n * 2048 + k * 1024); } while (0)
; #define PG8_MMA(ai, bj, At, Bt) do { __builtin_amdgcn_s_setprio(1); _Pragma("unroll") for (int m = 0; m < 4; ++m) _Pragma("unroll") for (int n = 0; n < 2; ++n) _Pragma("unroll") for (int k = 0; k < 2; ++k) \
;         acc[ai][bj][m][n] = __builtin_amdgcn_mfma_f32_16x16x32_bf16(Bt[n][k], At[m][k], acc[ai][bj][m][n], 0, 0, 0); __builtin_amdgcn_s_setprio(0); } while (0)
; #define PG8_WAIT_V(n) asm volatile("s_waitcnt vmcnt(" #n ")" ::: "memory")
; #define PG8_WAIT_L(n) asm volatile("s_waitcnt lgkmcnt(" #n ")" ::: "memory")
; #define PG8_BAR __builtin_amdgcn_s_barrier()
; #define PG8_SCHED __builtin_amdgcn_sched_barrier(0)
; template <class Epi, class Sched, bool ALIGN_EPI, bool SP2>
; __device__ __forceinline__ void gemm_phase(LAS unsigned char* lds, const Gemm g, const Sched& S, const Epi& E) {
;     ...
;             PG8_WAIT_V(8); PG8_WAIT_L(0); PG8_BAR; PG8_MMA(0, 0, At, B0); PG8_MMA(0, 1, At, B1); PG8_BAR; PG8_SCHED;
;             PG8_LDA(At, 0, 1); PG8_STAGE(PG8_SB(0, 0), b2, voffB); PG8_STAGE(PG8_SB(0, 1), b2 + hstep, voffB); PG8_STAGE(PG8_SA(0, 0), a2, voffA);
;             PG8_WAIT_V(8); PG8_WAIT_L(0); PG8_BAR; PG8_MMA(1, 0, At, B0); PG8_MMA(1, 1, At, B1); PG8_BAR; PG8_SCHED;
;             PG8_LDB(B0, 1, 0); PG8_LDB(B1, 1, 1); PG8_SCHED; PG8_LDA(At, 1, 0); PG8_STAGE(PG8_SA(0, 1), a2 + hstep, voffA);
;             PG8_WAIT_V(8); PG8_WAIT_L(0); PG8_BAR; PG8_MMA(0, 0, At, B0); PG8_MMA(0, 1, At, B1); PG8_BAR; PG8_SCHED;
	s_setprio 1
	s_waitcnt lgkmcnt(0)
	v_mfma_f32_16x16x32_bf16 v[56:59], v[156:159], v[212:215], v[56:59]
	v_mfma_f32_16x16x32_bf16 v[60:63], v[164:167], v[212:215], v[60:63]
	v_mfma_f32_16x16x32_bf16 v[40:43], v[156:159], v[220:223], v[40:43]
	v_mfma_f32_16x16x32_bf16 v[44:47], v[164:167], v[220:223], v[44:47]
	v_mfma_f32_16x16x32_bf16 v[24:27], v[156:159], v[228:231], v[24:27]
	v_mfma_f32_16x16x32_bf16 v[28:31], v[164:167], v[228:231], v[28:31]
	v_mfma_f32_16x16x32_bf16 v[8:11], v[156:159], v[236:239], v[8:11]
	v_mfma_f32_16x16x32_bf16 v[12:15], v[164:167], v[236:239], v[12:15]
	v_mfma_f32_16x16x32_bf16 v[56:59], v[160:163], v[216:219], v[56:59]
	v_mfma_f32_16x16x32_bf16 v[60:63], v[168:171], v[216:219], v[60:63]
	v_mfma_f32_16x16x32_bf16 v[40:43], v[160:163], v[224:227], v[40:43]
	v_mfma_f32_16x16x32_bf16 v[44:47], v[168:171], v[224:227], v[44:47]
	v_mfma_f32_16x16x32_bf16 v[24:27], v[160:163], v[232:235], v[24:27]
	v_mfma_f32_16x16x32_bf16 v[28:31], v[168:171], v[232:235], v[28:31]
	v_mfma_f32_16x16x32_bf16 v[8:11], v[160:163], v[240:243], v[8:11]
	v_mfma_f32_16x16x32_bf16 v[12:15], v[168:171], v[240:243], v[12:15]
	v_mfma_f32_16x16x32_bf16 v[48:51], v[172:175], v[212:215], v[48:51]
	v_mfma_f32_16x16x32_bf16 v[52:55], v[180:183], v[212:215], v[52:55]
	v_mfma_f32_16x16x32_bf16 v[32:35], v[172:175], v[220:223], v[32:35]
	v_mfma_f32_16x16x32_bf16 v[36:39], v[180:183], v[220:223], v[36:39]
	v_mfma_f32_16x16x32_bf16 v[16:19], v[172:175], v[228:231], v[16:19]
	v_mfma_f32_16x16x32_bf16 v[20:23], v[180:183], v[228:231], v[20:23]
	v_mfma_f32_16x16x32_bf16 v[0:3], v[172:175], v[236:239], v[0:3]
	v_mfma_f32_16x16x32_bf16 v[4:7], v[180:183], v[236:239], v[4:7]
	v_mfma_f32_16x16x32_bf16 v[48:51], v[176:179], v[216:219], v[48:51]
	v_mfma_f32_16x16x32_bf16 v[52:55], v[208:211], v[216:219], v[52:55]
	v_mfma_f32_16x16x32_bf16 v[32:35], v[176:179], v[224:227], v[32:35]
	v_mfma_f32_16x16x32_bf16 v[36:39], v[208:211], v[224:227], v[36:39]
	v_mfma_f32_16x16x32_bf16 v[16:19], v[176:179], v[232:235], v[16:19]
	v_mfma_f32_16x16x32_bf16 v[20:23], v[208:211], v[232:235], v[20:23]
	v_mfma_f32_16x16x32_bf16 v[0:3], v[176:179], v[240:243], v[0:3]
	v_mfma_f32_16x16x32_bf16 v[4:7], v[208:211], v[240:243], v[4:7]
	s_setprio 0
	s_barrier
	s_add_i32 s4, 0, 0x18000
	v_add_u32_e32 v128, s4, v152
	s_add_i32 s76, 0, 0x1c000
	ds_read_b128 v[156:159], v128
	ds_read_b128 v[160:163], v128 offset:1024
	ds_read_b128 v[164:167], v128 offset:2048
	ds_read_b128 v[168:171], v128 offset:3072
	v_add_u32_e32 v128, s76, v152
	ds_read_b128 v[172:175], v128
	ds_read_b128 v[176:179], v128 offset:1024
	ds_read_b128 v[180:183], v128 offset:2048
	ds_read_b128 v[208:211], v128 offset:3072
	s_add_u32 s18, s18, s12
	s_addc_u32 s19, s19, s13
	s_mov_b32 m0, s37
	v_lshl_add_u64 v[192:193], s[18:19], 0, v[138:139]
	ds_read_b128 v[212:215], v154 offset:32768
	ds_read_b128 v[216:219], v154 offset:33792
	ds_read_b128 v[220:223], v154 offset:34816
	ds_read_b128 v[224:227], v154 offset:35840
	ds_read_b128 v[228:231], v154 offset:36864
	ds_read_b128 v[232:235], v154 offset:37888
	ds_read_b128 v[236:239], v154 offset:38912
	ds_read_b128 v[240:243], v154 offset:39936
	global_load_lds_dwordx4 v[192:193], off
	v_lshl_add_u64 v[192:193], v[192:193], 0, s[10:11]
	s_mov_b32 m0, s38
	s_nop 0
	global_load_lds_dwordx4 v[192:193], off
	s_waitcnt vmcnt(8)
	s_waitcnt lgkmcnt(0)
	s_barrier
	s_setprio 1
	s_waitcnt lgkmcnt(0)
	v_mfma_f32_16x16x32_bf16 v[120:123], v[156:159], v[212:215], v[120:123]
	v_mfma_f32_16x16x32_bf16 v[124:127], v[164:167], v[212:215], v[124:127]
	v_mfma_f32_16x16x32_bf16 v[104:107], v[156:159], v[220:223], v[104:107]
	v_mfma_f32_16x16x32_bf16 v[108:111], v[164:167], v[220:223], v[108:111]
	v_mfma_f32_16x16x32_bf16 v[88:91], v[156:159], v[228:231], v[88:91]
	v_mfma_f32_16x16x32_bf16 v[92:95], v[164:167], v[228:231], v[92:95]
	v_mfma_f32_16x16x32_bf16 v[72:75], v[156:159], v[236:239], v[72:75]
	v_mfma_f32_16x16x32_bf16 v[76:79], v[164:167], v[236:239], v[76:79]
	v_mfma_f32_16x16x32_bf16 v[120:123], v[160:163], v[216:219], v[120:123]
	v_mfma_f32_16x16x32_bf16 v[124:127], v[168:171], v[216:219], v[124:127]
	v_mfma_f32_16x16x32_bf16 v[104:107], v[160:163], v[224:227], v[104:107]
	v_mfma_f32_16x16x32_bf16 v[108:111], v[168:171], v[224:227], v[108:111]
	v_mfma_f32_16x16x32_bf16 v[88:91], v[160:163], v[232:235], v[88:91]
	v_mfma_f32_16x16x32_bf16 v[92:95], v[168:171], v[232:235], v[92:95]
	v_mfma_f32_16x16x32_bf16 v[72:75], v[160:163], v[240:243], v[72:75]
	v_mfma_f32_16x16x32_bf16 v[76:79], v[168:171], v[240:243], v[76:79]
	v_mfma_f32_16x16x32_bf16 v[112:115], v[172:175], v[212:215], v[112:115]
	v_mfma_f32_16x16x32_bf16 v[116:119], v[180:183], v[212:215], v[116:119]
	v_mfma_f32_16x16x32_bf16 v[96:99], v[172:175], v[220:223], v[96:99]
	v_mfma_f32_16x16x32_bf16 v[100:103], v[180:183], v[220:223], v[100:103]
	v_mfma_f32_16x16x32_bf16 v[80:83], v[172:175], v[228:231], v[80:83]
	v_mfma_f32_16x16x32_bf16 v[84:87], v[180:183], v[228:231], v[84:87]
	v_mfma_f32_16x16x32_bf16 v[64:67], v[172:175], v[236:239], v[64:67]
	v_mfma_f32_16x16x32_bf16 v[68:71], v[180:183], v[236:239], v[68:71]
	v_mfma_f32_16x16x32_bf16 v[112:115], v[176:179], v[216:219], v[112:115]
	v_mfma_f32_16x16x32_bf16 v[116:119], v[208:211], v[216:219], v[116:119]
	v_mfma_f32_16x16x32_bf16 v[96:99], v[176:179], v[224:227], v[96:99]
	v_mfma_f32_16x16x32_bf16 v[100:103], v[208:211], v[224:227], v[100:103]
	v_mfma_f32_16x16x32_bf16 v[80:83], v[176:179], v[232:235], v[80:83]
	v_mfma_f32_16x16x32_bf16 v[84:87], v[208:211], v[232:235], v[84:87]
	v_mfma_f32_16x16x32_bf16 v[64:67], v[176:179], v[240:243], v[64:67]
	v_mfma_f32_16x16x32_bf16 v[68:71], v[208:211], v[240:243], v[68:71]
	s_setprio 0
	s_barrier
; #define PG8_STAGE(bufoff, gbase, voff) do { _Pragma("unroll") for (int _i = 0; _i < 2; ++_i) \
;         __builtin_amdgcn_global_load_lds((const unsigned*)((const char*)(gbase) + _i * rdelta + (voff)), (LAS unsigned*)(lds + (bufoff) + ldsw + _i * 8192), 16, 0, 0); } while (0)
; #define PG8_LDA(dst, b, h) do { _Pragma("unroll") for (int m = 0; m < 4; ++m) _Pragma("unroll") for (int k = 0; k < 2; ++k) dst[m][k] = *(const LAS bf16x8*)(lds + PG8_SA(b, h) + aoff + m * 2048 + k * 1024); } while (0)
; #define PG8_MMA(ai, bj, At, Bt) do { __builtin_amdgcn_s_setprio(1); _Pragma("unroll") for (int m = 0; m < 4; ++m) _Pragma("unroll") for (int n = 0; n < 2; ++n) _Pragma("unroll") for (int k = 0; k < 2; ++k) \
;         acc[ai][bj][m][n] = __builtin_amdgcn_mfma_f32_16x16x32_bf16(Bt[n][k], At[m][k], acc[ai][bj][m][n], 0, 0, 0); __builtin_amdgcn_s_setprio(0); } while (0)
; #define PG8_WAIT_V(n) asm volatile("s_waitcnt vmcnt(" #n ")" ::: "memory")
; #define PG8_WAIT_L(n) asm volatile("s_waitcnt lgkmcnt(" #n ")" ::: "memory")
; #define PG8_BAR __builtin_amdgcn_s_barrier()
; #define PG8_SCHED __builtin_amdgcn_sched_barrier(0)
; template <class Epi, class Sched, bool ALIGN_EPI, bool SP2>
; __device__ __forceinline__ void gemm_phase(LAS unsigned char* lds, const Gemm g, const Sched& S, const Epi& E) {
;     ...
;             if constexpr (Epi::HOOK) { if (t == Epi::T1 || t == Epi::T2) E.hook(acc, ui, t, wr, fr); }
;     ...
;             PG8_LDA(At, 1, 1); PG8_STAGE(PG8_SB(1, 0), b3, voffB); PG8_STAGE(PG8_SB(1, 1), b3 + hstep, voffB); PG8_STAGE(PG8_SA(1, 0), a3, voffA);
;             PG8_WAIT_V(8); PG8_WAIT_L(0); PG8_BAR; PG8_MMA(1, 0, At, B0); PG8_MMA(1, 1, At, B1); PG8_BAR; PG8_SCHED;
	s_add_i32 s4, s4, s34
	v_lshl_add_u64 v[130:131], v[130:131], 0, s[30:31]
	s_mov_b32 m0, s4
	ds_read_b128 v[212:215], v154 offset:49152
	ds_read_b128 v[216:219], v154 offset:50176
	ds_read_b128 v[220:223], v154 offset:51200
	ds_read_b128 v[224:227], v154 offset:52224
	ds_read_b128 v[228:231], v154 offset:53248
	ds_read_b128 v[232:235], v154 offset:54272
	ds_read_b128 v[236:239], v154 offset:55296
	ds_read_b128 v[240:243], v154 offset:56320
	global_load_lds_dwordx4 v[130:131], off
	v_lshl_add_u64 v[130:131], v[244:245], 0, s[30:31]
	s_add_i32 m0, s4, 0x2000
	s_add_i32 s4, s76, s34
	global_load_lds_dwordx4 v[130:131], off
	v_lshl_add_u64 v[130:131], v[246:247], 0, s[30:31]
	s_mov_b32 m0, s4
	s_nop 0
	global_load_lds_dwordx4 v[130:131], off
	v_lshl_add_u64 v[130:131], v[248:249], 0, s[30:31]
	s_add_i32 m0, s4, 0x2000
	s_nop 0
	global_load_lds_dwordx4 v[130:131], off
	v_lshl_add_u64 v[130:131], v[250:251], 0, s[30:31]
	s_mov_b32 m0, s66
	s_nop 0
	global_load_lds_dwordx4 v[130:131], off
	v_lshl_add_u64 v[130:131], v[190:191], 0, s[30:31]
	s_mov_b32 m0, s67
	s_nop 0
	global_load_lds_dwordx4 v[130:131], off
	s_waitcnt vmcnt(8)
	s_waitcnt lgkmcnt(0)
	s_barrier
	s_setprio 1
	s_waitcnt lgkmcnt(0)
	v_mfma_f32_16x16x32_bf16 v[56:59], v[156:159], v[212:215], v[56:59]
	v_mfma_f32_16x16x32_bf16 v[60:63], v[164:167], v[212:215], v[60:63]
	v_mfma_f32_16x16x32_bf16 v[40:43], v[156:159], v[220:223], v[40:43]
	v_mfma_f32_16x16x32_bf16 v[44:47], v[164:167], v[220:223], v[44:47]
	v_mfma_f32_16x16x32_bf16 v[24:27], v[156:159], v[228:231], v[24:27]
	v_mfma_f32_16x16x32_bf16 v[28:31], v[164:167], v[228:231], v[28:31]
	v_mfma_f32_16x16x32_bf16 v[8:11], v[156:159], v[236:239], v[8:11]
	v_mfma_f32_16x16x32_bf16 v[12:15], v[164:167], v[236:239], v[12:15]
	v_mfma_f32_16x16x32_bf16 v[56:59], v[160:163], v[216:219], v[56:59]
	v_mfma_f32_16x16x32_bf16 v[60:63], v[168:171], v[216:219], v[60:63]
	v_mfma_f32_16x16x32_bf16 v[40:43], v[160:163], v[224:227], v[40:43]
	v_mfma_f32_16x16x32_bf16 v[44:47], v[168:171], v[224:227], v[44:47]
	v_mfma_f32_16x16x32_bf16 v[24:27], v[160:163], v[232:235], v[24:27]
	v_mfma_f32_16x16x32_bf16 v[28:31], v[168:171], v[232:235], v[28:31]
	v_mfma_f32_16x16x32_bf16 v[8:11], v[160:163], v[240:243], v[8:11]
	v_mfma_f32_16x16x32_bf16 v[12:15], v[168:171], v[240:243], v[12:15]
	v_mfma_f32_16x16x32_bf16 v[48:51], v[172:175], v[212:215], v[48:51]
	v_mfma_f32_16x16x32_bf16 v[52:55], v[180:183], v[212:215], v[52:55]
	v_mfma_f32_16x16x32_bf16 v[32:35], v[172:175], v[220:223], v[32:35]
	v_mfma_f32_16x16x32_bf16 v[36:39], v[180:183], v[220:223], v[36:39]
	v_mfma_f32_16x16x32_bf16 v[16:19], v[172:175], v[228:231], v[16:19]
	v_mfma_f32_16x16x32_bf16 v[20:23], v[180:183], v[228:231], v[20:23]
	v_mfma_f32_16x16x32_bf16 v[0:3], v[172:175], v[236:239], v[0:3]
	v_mfma_f32_16x16x32_bf16 v[4:7], v[180:183], v[236:239], v[4:7]
	v_mfma_f32_16x16x32_bf16 v[48:51], v[176:179], v[216:219], v[48:51]
	v_mfma_f32_16x16x32_bf16 v[52:55], v[208:211], v[216:219], v[52:55]
	v_mfma_f32_16x16x32_bf16 v[32:35], v[176:179], v[224:227], v[32:35]
	v_mfma_f32_16x16x32_bf16 v[36:39], v[208:211], v[224:227], v[36:39]
	v_mfma_f32_16x16x32_bf16 v[16:19], v[176:179], v[232:235], v[16:19]
	v_mfma_f32_16x16x32_bf16 v[20:23], v[208:211], v[232:235], v[20:23]
	v_mfma_f32_16x16x32_bf16 v[0:3], v[176:179], v[240:243], v[0:3]
	v_mfma_f32_16x16x32_bf16 v[4:7], v[208:211], v[240:243], v[4:7]
	s_setprio 0
	s_barrier
	s_add_u32 s16, s16, 0x100
	s_addc_u32 s17, s17, 0
	s_cmp_ge_i32 s75, s68
	s_cbranch_scc1 .LBB0_1276
	s_mov_b32 s4, s75
	s_and_b32 s18, s4, 0x7fffffee
	s_cmp_lg_u32 s18, 8
	s_cbranch_scc0 .LBB0_1273
	s_branch .LBB0_1274

; #define PG8_STAGE(bufoff, gbase, voff) do { _Pragma("unroll") for (int _i = 0; _i < 2; ++_i) \
;         __builtin_amdgcn_global_load_lds((const unsigned*)((const char*)(gbase) + _i * rdelta + (voff)), (LAS unsigned*)(lds + (bufoff) + ldsw + _i * 8192), 16, 0, 0); } while (0)
; #define PG8_LDA(dst, b, h) do { _Pragma("unroll") for (int m = 0; m < 4; ++m) _Pragma("unroll") for (int k = 0; k < 2; ++k) dst[m][k] = *(const LAS bf16x8*)(lds + PG8_SA(b, h) + aoff + m * 2048 + k * 1024); } while (0)
; #define PG8_LDB(dst, b, h) do { _Pragma("unroll") for (int n = 0; n < 2; ++n) _Pragma("unroll") for (int k = 0; k < 2; ++k) dst[n][k] = *(const LAS bf16x8*)(lds + PG8_SB(b, h) + boff + n * 2048 + k * 1024); } while (0)
; #define PG8_MMA(ai, bj, At, Bt) do { __builtin_amdgcn_s_setprio(1); _Pragma("unroll") for (int m = 0; m < 4; ++m) _Pragma("unroll") for (int n = 0; n < 2; ++n) _Pragma("unroll") for (int k = 0; k < 2; ++k) \
;         acc[ai][bj][m][n] = __builtin_amdgcn_mfma_f32_16x16x32_bf16(Bt[n][k], At[m][k], acc[ai][bj][m][n], 0, 0, 0); __builtin_amdgcn_s_setprio(0); } while (0)
; #define PG8_WAIT_V(n) asm volatile("s_waitcnt vmcnt(" #n ")" ::: "memory")
; #define PG8_WAIT_L(n) asm volatile("s_waitcnt lgkmcnt(" #n ")" ::: "memory")
; #define PG8_BAR __builtin_amdgcn_s_barrier()
; #define PG8_SCHED __builtin_amdgcn_sched_barrier(0)
; template <class Epi, class Sched, bool ALIGN_EPI, bool SP2>
; __device__ __forceinline__ void gemm_phase(LAS unsigned char* lds, const Gemm g, const Sched& S, const Epi& E) {
;     ...
;             const bool last = (t == nt - 2);
;             const char* a1 = cA + (size_t)(t + 1) * kstep;
;             const char* a2 = last ? nA : cA + (size_t)(t + 2) * kstep; const char* b2 = last ? nB : cB + (size_t)(t + 2) * kstep;
;             const char* a3 = a2 + kstep; const char* b3 = b2 + kstep;
;             PG8_LDB(B0, 0, 0); PG8_LDB(B1, 0, 1); PG8_SCHED; PG8_LDA(At, 0, 0); PG8_STAGE(PG8_SA(1, 1), a1 + hstep, voffA);
;             PG8_WAIT_V(8); PG8_WAIT_L(0); PG8_BAR; PG8_MMA(0, 0, At, B0); PG8_MMA(0, 1, At, B1); PG8_BAR; PG8_SCHED;
;             PG8_LDA(At, 0, 1); PG8_STAGE(PG8_SB(0, 0), b2, voffB); PG8_STAGE(PG8_SB(0, 1), b2 + hstep, voffB); PG8_STAGE(PG8_SA(0, 0), a2, voffA);
;             PG8_WAIT_V(8); PG8_WAIT_L(0); PG8_BAR; PG8_MMA(1, 0, At, B0); PG8_MMA(1, 1, At, B1); PG8_BAR; PG8_SCHED;
.LBB0_1365:
	s_add_i32 s65, s4, 2
	s_add_u32 s16, s14, 0x80
	s_addc_u32 s17, s15, 0
	s_add_i32 s68, 0, 0x10000
	s_cmp_eq_u32 s61, s4
	s_cselect_b32 s17, s7, s17
	s_cselect_b32 s16, s6, s16
	v_add_u32_e32 v128, s68, v145
	s_cselect_b32 s67, s57, s19
	s_cselect_b32 s66, s56, s18
	s_add_i32 s4, 0, 0x14000
	ds_read_b128 v[148:151], v128
	ds_read_b128 v[152:155], v128 offset:1024
	ds_read_b128 v[156:159], v128 offset:2048
	ds_read_b128 v[160:163], v128 offset:3072
	v_add_u32_e32 v128, s4, v145
	ds_read_b128 v[164:167], v128
	ds_read_b128 v[168:171], v128 offset:1024
	ds_read_b128 v[172:175], v128 offset:2048
	ds_read_b128 v[176:179], v128 offset:3072
	v_lshl_add_u64 v[142:143], s[14:15], 0, v[138:139]
	s_add_i32 m0, s35, 0xc000
	ds_read_b128 v[180:183], v147
	ds_read_b128 v[208:211], v147 offset:1024
	ds_read_b128 v[212:215], v147 offset:2048
	ds_read_b128 v[216:219], v147 offset:3072
	ds_read_b128 v[220:223], v147 offset:4096
	ds_read_b128 v[224:227], v147 offset:5120
	ds_read_b128 v[228:231], v147 offset:6144
	ds_read_b128 v[232:235], v147 offset:7168
	global_load_lds_dwordx4 v[142:143], off
	v_lshl_add_u64 v[142:143], s[14:15], 0, v[140:141]
	s_add_i32 m0, s35, 0xe000
	s_nop 0
	global_load_lds_dwordx4 v[142:143], off
	s_waitcnt vmcnt(8)
	s_waitcnt lgkmcnt(0)
	s_barrier
	s_setprio 1
	s_waitcnt lgkmcnt(0)
	v_mfma_f32_16x16x32_bf16 v[120:123], v[148:151], v[180:183], v[120:123]
	v_mfma_f32_16x16x32_bf16 v[124:127], v[156:159], v[180:183], v[124:127]
	v_mfma_f32_16x16x32_bf16 v[108:111], v[148:151], v[212:215], v[108:111]
	v_mfma_f32_16x16x32_bf16 v[104:107], v[156:159], v[212:215], v[104:107]
	v_mfma_f32_16x16x32_bf16 v[92:95], v[148:151], v[220:223], v[92:95]
	v_mfma_f32_16x16x32_bf16 v[88:91], v[156:159], v[220:223], v[88:91]
	v_mfma_f32_16x16x32_bf16 v[76:79], v[148:151], v[228:231], v[76:79]
	v_mfma_f32_16x16x32_bf16 v[72:75], v[156:159], v[228:231], v[72:75]
	v_mfma_f32_16x16x32_bf16 v[120:123], v[152:155], v[208:211], v[120:123]
	v_mfma_f32_16x16x32_bf16 v[124:127], v[160:163], v[208:211], v[124:127]
	v_mfma_f32_16x16x32_bf16 v[108:111], v[152:155], v[216:219], v[108:111]
	v_mfma_f32_16x16x32_bf16 v[104:107], v[160:163], v[216:219], v[104:107]
	v_mfma_f32_16x16x32_bf16 v[92:95], v[152:155], v[224:227], v[92:95]
	v_mfma_f32_16x16x32_bf16 v[88:91], v[160:163], v[224:227], v[88:91]
	v_mfma_f32_16x16x32_bf16 v[76:79], v[152:155], v[232:235], v[76:79]
	v_mfma_f32_16x16x32_bf16 v[72:75], v[160:163], v[232:235], v[72:75]
	v_mfma_f32_16x16x32_bf16 v[116:119], v[164:167], v[180:183], v[116:119]
	v_mfma_f32_16x16x32_bf16 v[112:115], v[172:175], v[180:183], v[112:115]
	v_mfma_f32_16x16x32_bf16 v[100:103], v[164:167], v[212:215], v[100:103]
	v_mfma_f32_16x16x32_bf16 v[96:99], v[172:175], v[212:215], v[96:99]
	v_mfma_f32_16x16x32_bf16 v[84:87], v[164:167], v[220:223], v[84:87]
	v_mfma_f32_16x16x32_bf16 v[80:83], v[172:175], v[220:223], v[80:83]
	v_mfma_f32_16x16x32_bf16 v[68:71], v[164:167], v[228:231], v[68:71]
	v_mfma_f32_16x16x32_bf16 v[64:67], v[172:175], v[228:231], v[64:67]
	v_mfma_f32_16x16x32_bf16 v[116:119], v[168:171], v[208:211], v[116:119]
	v_mfma_f32_16x16x32_bf16 v[112:115], v[176:179], v[208:211], v[112:115]
	v_mfma_f32_16x16x32_bf16 v[100:103], v[168:171], v[216:219], v[100:103]
	v_mfma_f32_16x16x32_bf16 v[96:99], v[176:179], v[216:219], v[96:99]
	v_mfma_f32_16x16x32_bf16 v[84:87], v[168:171], v[224:227], v[84:87]
	v_mfma_f32_16x16x32_bf16 v[80:83], v[176:179], v[224:227], v[80:83]
	v_mfma_f32_16x16x32_bf16 v[68:71], v[168:171], v[232:235], v[68:71]
	v_mfma_f32_16x16x32_bf16 v[64:67], v[176:179], v[232:235], v[64:67]
	s_setprio 0
	s_barrier
	s_add_i32 s68, s68, s34
	v_lshl_add_u64 v[142:143], s[66:67], 0, v[130:131]
	s_mov_b32 m0, s68
	ds_read_b128 v[180:183], v147 offset:16384
	ds_read_b128 v[208:211], v147 offset:17408
	ds_read_b128 v[212:215], v147 offset:18432
	ds_read_b128 v[216:219], v147 offset:19456
	ds_read_b128 v[220:223], v147 offset:20480
	ds_read_b128 v[224:227], v147 offset:21504
	ds_read_b128 v[228:231], v147 offset:22528
	ds_read_b128 v[232:235], v147 offset:23552
	global_load_lds_dwordx4 v[142:143], off
	s_add_i32 m0, s68, 0x2000
	s_add_u32 s66, s66, s10
	v_lshl_add_u64 v[190:191], v[142:143], 0, s[8:9]
	s_addc_u32 s67, s67, s11
	s_add_i32 s4, s4, s34
	global_load_lds_dwordx4 v[190:191], off
	v_lshl_add_u64 v[192:193], s[66:67], 0, v[130:131]
	s_mov_b32 m0, s4
	v_lshl_add_u64 v[236:237], v[192:193], 0, s[8:9]
	global_load_lds_dwordx4 v[192:193], off
	s_add_i32 m0, s4, 0x2000
	v_lshl_add_u64 v[238:239], s[16:17], 0, v[136:137]
	global_load_lds_dwordx4 v[236:237], off
	s_mov_b32 m0, s35
	v_lshl_add_u64 v[240:241], v[238:239], 0, s[8:9]
	global_load_lds_dwordx4 v[238:239], off
	s_mov_b32 m0, s36
	s_nop 0
	global_load_lds_dwordx4 v[240:241], off
	s_waitcnt vmcnt(8)
	s_waitcnt lgkmcnt(0)
	s_barrier
; #define PG8_STAGE(bufoff, gbase, voff) do { _Pragma("unroll") for (int _i = 0; _i < 2; ++_i) \
;         __builtin_amdgcn_global_load_lds((const unsigned*)((const char*)(gbase) + _i * rdelta + (voff)), (LAS unsigned*)(lds + (bufoff) + ldsw + _i * 8192), 16, 0, 0); } while (0)
; #define PG8_LDA(dst, b, h) do { _Pragma("unroll") for (int m = 0; m < 4; ++m) _Pragma("unroll") for (int k = 0; k < 2; ++k) dst[m][k] = *(const LAS bf16x8*)(lds + PG8_SA(b, h) + aoff + m * 2048 + k * 1024); } while (0)
; #define PG8_LDB(dst, b, h) do { _Pragma("unroll") for (int n = 0; n < 2; ++n) _Pragma("unroll") for (int k = 0; k < 2; ++k) dst[n][k] = *(const LAS bf16x8*)(lds + PG8_SB(b, h) + boff + n * 2048 + k * 1024); } while (0)
; #define PG8_MMA(ai, bj, At, Bt) do { __builtin_amdgcn_s_setprio(1); _Pragma("unroll") for (int m = 0; m < 4; ++m) _Pragma("unroll") for (int n = 0; n < 2; ++n) _Pragma("unroll") for (int k = 0; k < 2; ++k) \
;         acc[ai][bj][m][n] = __builtin_amdgcn_mfma_f32_16x16x32_bf16(Bt[n][k], At[m][k], acc[ai][bj][m][n], 0, 0, 0); __builtin_amdgcn_s_setprio(0); } while (0)
; #define PG8_WAIT_V(n) asm volatile("s_waitcnt vmcnt(" #n ")" ::: "memory")
; #define PG8_WAIT_L(n) asm volatile("s_waitcnt lgkmcnt(" #n ")" ::: "memory")
; #define PG8_BAR __builtin_amdgcn_s_barrier()
; #define PG8_SCHED __builtin_amdgcn_sched_barrier(0)
; template <class Epi, class Sched, bool ALIGN_EPI, bool SP2>
; __device__ __forceinline__ void gemm_phase(LAS unsigned char* lds, const Gemm g, const Sched& S, const Epi& E) {
;     ...
;             PG8_WAIT_V(8); PG8_WAIT_L(0); PG8_BAR; PG8_MMA(0, 0, At, B0); PG8_MMA(0, 1, At, B1); PG8_BAR; PG8_SCHED;
;             PG8_LDA(At, 0, 1); PG8_STAGE(PG8_SB(0, 0), b2, voffB); PG8_STAGE(PG8_SB(0, 1), b2 + hstep, voffB); PG8_STAGE(PG8_SA(0, 0), a2, voffA);
;             PG8_WAIT_V(8); PG8_WAIT_L(0); PG8_BAR; PG8_MMA(1, 0, At, B0); PG8_MMA(1, 1, At, B1); PG8_BAR; PG8_SCHED;
;             PG8_LDB(B0, 1, 0); PG8_LDB(B1, 1, 1); PG8_SCHED; PG8_LDA(At, 1, 0); PG8_STAGE(PG8_SA(0, 1), a2 + hstep, voffA);
;             PG8_WAIT_V(8); PG8_WAIT_L(0); PG8_BAR; PG8_MMA(0, 0, At, B0); PG8_MMA(0, 1, At, B1); PG8_BAR; PG8_SCHED;
	s_setprio 1
	s_waitcnt lgkmcnt(0)
	v_mfma_f32_16x16x32_bf16 v[60:63], v[148:151], v[180:183], v[60:63]
	v_mfma_f32_16x16x32_bf16 v[56:59], v[156:159], v[180:183], v[56:59]
	v_mfma_f32_16x16x32_bf16 v[44:47], v[148:151], v[212:215], v[44:47]
	v_mfma_f32_16x16x32_bf16 v[40:43], v[156:159], v[212:215], v[40:43]
	v_mfma_f32_16x16x32_bf16 v[28:31], v[148:151], v[220:223], v[28:31]
	v_mfma_f32_16x16x32_bf16 v[24:27], v[156:159], v[220:223], v[24:27]
	v_mfma_f32_16x16x32_bf16 v[12:15], v[148:151], v[228:231], v[12:15]
	v_mfma_f32_16x16x32_bf16 v[8:11], v[156:159], v[228:231], v[8:11]
	v_mfma_f32_16x16x32_bf16 v[60:63], v[152:155], v[208:211], v[60:63]
	v_mfma_f32_16x16x32_bf16 v[56:59], v[160:163], v[208:211], v[56:59]
	v_mfma_f32_16x16x32_bf16 v[44:47], v[152:155], v[216:219], v[44:47]
	v_mfma_f32_16x16x32_bf16 v[40:43], v[160:163], v[216:219], v[40:43]
	v_mfma_f32_16x16x32_bf16 v[28:31], v[152:155], v[224:227], v[28:31]
	v_mfma_f32_16x16x32_bf16 v[24:27], v[160:163], v[224:227], v[24:27]
	v_mfma_f32_16x16x32_bf16 v[12:15], v[152:155], v[232:235], v[12:15]
	v_mfma_f32_16x16x32_bf16 v[8:11], v[160:163], v[232:235], v[8:11]
	v_mfma_f32_16x16x32_bf16 v[52:55], v[164:167], v[180:183], v[52:55]
	v_mfma_f32_16x16x32_bf16 v[48:51], v[172:175], v[180:183], v[48:51]
	v_mfma_f32_16x16x32_bf16 v[36:39], v[164:167], v[212:215], v[36:39]
	v_mfma_f32_16x16x32_bf16 v[32:35], v[172:175], v[212:215], v[32:35]
	v_mfma_f32_16x16x32_bf16 v[20:23], v[164:167], v[220:223], v[20:23]
	v_mfma_f32_16x16x32_bf16 v[16:19], v[172:175], v[220:223], v[16:19]
	v_mfma_f32_16x16x32_bf16 v[4:7], v[164:167], v[228:231], v[4:7]
	v_mfma_f32_16x16x32_bf16 v[0:3], v[172:175], v[228:231], v[0:3]
	v_mfma_f32_16x16x32_bf16 v[52:55], v[168:171], v[208:211], v[52:55]
	v_mfma_f32_16x16x32_bf16 v[48:51], v[176:179], v[208:211], v[48:51]
	v_mfma_f32_16x16x32_bf16 v[36:39], v[168:171], v[216:219], v[36:39]
	v_mfma_f32_16x16x32_bf16 v[32:35], v[176:179], v[216:219], v[32:35]
	v_mfma_f32_16x16x32_bf16 v[20:23], v[168:171], v[224:227], v[20:23]
	v_mfma_f32_16x16x32_bf16 v[16:19], v[176:179], v[224:227], v[16:19]
	v_mfma_f32_16x16x32_bf16 v[4:7], v[168:171], v[232:235], v[4:7]
	v_mfma_f32_16x16x32_bf16 v[0:3], v[176:179], v[232:235], v[0:3]
	s_setprio 0
	s_barrier
	s_add_i32 s4, 0, 0x18000
	v_add_u32_e32 v128, s4, v145
	s_add_i32 s66, 0, 0x1c000
	ds_read_b128 v[148:151], v128
	ds_read_b128 v[152:155], v128 offset:1024
	ds_read_b128 v[156:159], v128 offset:2048
	ds_read_b128 v[160:163], v128 offset:3072
	v_add_u32_e32 v128, s66, v145
	ds_read_b128 v[164:167], v128
	ds_read_b128 v[168:171], v128 offset:1024
	ds_read_b128 v[172:175], v128 offset:2048
	ds_read_b128 v[176:179], v128 offset:3072
	s_add_u32 s16, s16, s10
	s_addc_u32 s17, s17, s11
	s_mov_b32 m0, s37
	v_lshl_add_u64 v[242:243], s[16:17], 0, v[136:137]
	ds_read_b128 v[180:183], v147 offset:32768
	ds_read_b128 v[208:211], v147 offset:33792
	ds_read_b128 v[212:215], v147 offset:34816
	ds_read_b128 v[216:219], v147 offset:35840
	ds_read_b128 v[220:223], v147 offset:36864
	ds_read_b128 v[224:227], v147 offset:37888
	ds_read_b128 v[228:231], v147 offset:38912
	ds_read_b128 v[232:235], v147 offset:39936
	global_load_lds_dwordx4 v[242:243], off
	v_lshl_add_u64 v[242:243], v[242:243], 0, s[8:9]
	s_mov_b32 m0, s38
	s_nop 0
	global_load_lds_dwordx4 v[242:243], off
	s_waitcnt vmcnt(8)
	s_waitcnt lgkmcnt(0)
	s_barrier
	s_setprio 1
	s_waitcnt lgkmcnt(0)
	v_mfma_f32_16x16x32_bf16 v[120:123], v[148:151], v[180:183], v[120:123]
	v_mfma_f32_16x16x32_bf16 v[124:127], v[156:159], v[180:183], v[124:127]
	v_mfma_f32_16x16x32_bf16 v[108:111], v[148:151], v[212:215], v[108:111]
	v_mfma_f32_16x16x32_bf16 v[104:107], v[156:159], v[212:215], v[104:107]
	v_mfma_f32_16x16x32_bf16 v[92:95], v[148:151], v[220:223], v[92:95]
	v_mfma_f32_16x16x32_bf16 v[88:91], v[156:159], v[220:223], v[88:91]
	v_mfma_f32_16x16x32_bf16 v[76:79], v[148:151], v[228:231], v[76:79]
	v_mfma_f32_16x16x32_bf16 v[72:75], v[156:159], v[228:231], v[72:75]
	v_mfma_f32_16x16x32_bf16 v[120:123], v[152:155], v[208:211], v[120:123]
	v_mfma_f32_16x16x32_bf16 v[124:127], v[160:163], v[208:211], v[124:127]
	v_mfma_f32_16x16x32_bf16 v[108:111], v[152:155], v[216:219], v[108:111]
	v_mfma_f32_16x16x32_bf16 v[104:107], v[160:163], v[216:219], v[104:107]
	v_mfma_f32_16x16x32_bf16 v[92:95], v[152:155], v[224:227], v[92:95]
	v_mfma_f32_16x16x32_bf16 v[88:91], v[160:163], v[224:227], v[88:91]
	v_mfma_f32_16x16x32_bf16 v[76:79], v[152:155], v[232:235], v[76:79]
	v_mfma_f32_16x16x32_bf16 v[72:75], v[160:163], v[232:235], v[72:75]
	v_mfma_f32_16x16x32_bf16 v[116:119], v[164:167], v[180:183], v[116:119]
	v_mfma_f32_16x16x32_bf16 v[112:115], v[172:175], v[180:183], v[112:115]
	v_mfma_f32_16x16x32_bf16 v[100:103], v[164:167], v[212:215], v[100:103]
	v_mfma_f32_16x16x32_bf16 v[96:99], v[172:175], v[212:215], v[96:99]
	v_mfma_f32_16x16x32_bf16 v[84:87], v[164:167], v[220:223], v[84:87]
	v_mfma_f32_16x16x32_bf16 v[80:83], v[172:175], v[220:223], v[80:83]
	v_mfma_f32_16x16x32_bf16 v[68:71], v[164:167], v[228:231], v[68:71]
	v_mfma_f32_16x16x32_bf16 v[64:67], v[172:175], v[228:231], v[64:67]
	v_mfma_f32_16x16x32_bf16 v[116:119], v[168:171], v[208:211], v[116:119]
	v_mfma_f32_16x16x32_bf16 v[112:115], v[176:179], v[208:211], v[112:115]
	v_mfma_f32_16x16x32_bf16 v[100:103], v[168:171], v[216:219], v[100:103]
	v_mfma_f32_16x16x32_bf16 v[96:99], v[176:179], v[216:219], v[96:99]
	v_mfma_f32_16x16x32_bf16 v[84:87], v[168:171], v[224:227], v[84:87]
	v_mfma_f32_16x16x32_bf16 v[80:83], v[176:179], v[224:227], v[80:83]
	v_mfma_f32_16x16x32_bf16 v[68:71], v[168:171], v[232:235], v[68:71]
	v_mfma_f32_16x16x32_bf16 v[64:67], v[176:179], v[232:235], v[64:67]
	s_setprio 0
	s_barrier
; #define PG8_STAGE(bufoff, gbase, voff) do { _Pragma("unroll") for (int _i = 0; _i < 2; ++_i) \
;         __builtin_amdgcn_global_load_lds((const unsigned*)((const char*)(gbase) + _i * rdelta + (voff)), (LAS unsigned*)(lds + (bufoff) + ldsw + _i * 8192), 16, 0, 0); } while (0)
; #define PG8_LDA(dst, b, h) do { _Pragma("unroll") for (int m = 0; m < 4; ++m) _Pragma("unroll") for (int k = 0; k < 2; ++k) dst[m][k] = *(const LAS bf16x8*)(lds + PG8_SA(b, h) + aoff + m * 2048 + k * 1024); } while (0)
; #define PG8_MMA(ai, bj, At, Bt) do { __builtin_amdgcn_s_setprio(1); _Pragma("unroll") for (int m = 0; m < 4; ++m) _Pragma("unroll") for (int n = 0; n < 2; ++n) _Pragma("unroll") for (int k = 0; k < 2; ++k) \
;         acc[ai][bj][m][n] = __builtin_amdgcn_mfma_f32_16x16x32_bf16(Bt[n][k], At[m][k], acc[ai][bj][m][n], 0, 0, 0); __builtin_amdgcn_s_setprio(0); } while (0)
; #define PG8_WAIT_V(n) asm volatile("s_waitcnt vmcnt(" #n ")" ::: "memory")
; #define PG8_WAIT_L(n) asm volatile("s_waitcnt lgkmcnt(" #n ")" ::: "memory")
; #define PG8_BAR __builtin_amdgcn_s_barrier()
; #define PG8_SCHED __builtin_amdgcn_sched_barrier(0)
; template <class Epi, class Sched, bool ALIGN_EPI, bool SP2>
; __device__ __forceinline__ void gemm_phase(LAS unsigned char* lds, const Gemm g, const Sched& S, const Epi& E) {
;     ...
;             PG8_LDA(At, 1, 1); PG8_STAGE(PG8_SB(1, 0), b3, voffB); PG8_STAGE(PG8_SB(1, 1), b3 + hstep, voffB); PG8_STAGE(PG8_SA(1, 0), a3, voffA);
;             PG8_WAIT_V(8); PG8_WAIT_L(0); PG8_BAR; PG8_MMA(1, 0, At, B0); PG8_MMA(1, 1, At, B1); PG8_BAR; PG8_SCHED;
;         }
	s_add_i32 s4, s4, s34
	v_lshl_add_u64 v[142:143], v[142:143], 0, s[30:31]
	s_mov_b32 m0, s4
	ds_read_b128 v[180:183], v147 offset:49152
	ds_read_b128 v[208:211], v147 offset:50176
	ds_read_b128 v[212:215], v147 offset:51200
	ds_read_b128 v[216:219], v147 offset:52224
	ds_read_b128 v[220:223], v147 offset:53248
	ds_read_b128 v[224:227], v147 offset:54272
	ds_read_b128 v[228:231], v147 offset:55296
	ds_read_b128 v[232:235], v147 offset:56320
	global_load_lds_dwordx4 v[142:143], off
	v_lshl_add_u64 v[142:143], v[190:191], 0, s[30:31]
	s_add_i32 m0, s4, 0x2000
	s_add_i32 s4, s66, s34
	global_load_lds_dwordx4 v[142:143], off
	v_lshl_add_u64 v[142:143], v[192:193], 0, s[30:31]
	s_mov_b32 m0, s4
	s_nop 0
	global_load_lds_dwordx4 v[142:143], off
	v_lshl_add_u64 v[142:143], v[236:237], 0, s[30:31]
	s_add_i32 m0, s4, 0x2000
	s_nop 0
	global_load_lds_dwordx4 v[142:143], off
	v_lshl_add_u64 v[142:143], v[238:239], 0, s[30:31]
	s_mov_b32 m0, s58
	s_nop 0
	global_load_lds_dwordx4 v[142:143], off
	v_lshl_add_u64 v[142:143], v[240:241], 0, s[30:31]
	s_mov_b32 m0, s59
	s_nop 0
	global_load_lds_dwordx4 v[142:143], off
	s_waitcnt vmcnt(8)
	s_waitcnt lgkmcnt(0)
	s_barrier
	s_setprio 1
	s_waitcnt lgkmcnt(0)
	v_mfma_f32_16x16x32_bf16 v[60:63], v[148:151], v[180:183], v[60:63]
	v_mfma_f32_16x16x32_bf16 v[56:59], v[156:159], v[180:183], v[56:59]
	v_mfma_f32_16x16x32_bf16 v[44:47], v[148:151], v[212:215], v[44:47]
	v_mfma_f32_16x16x32_bf16 v[40:43], v[156:159], v[212:215], v[40:43]
	v_mfma_f32_16x16x32_bf16 v[28:31], v[148:151], v[220:223], v[28:31]
	v_mfma_f32_16x16x32_bf16 v[24:27], v[156:159], v[220:223], v[24:27]
	v_mfma_f32_16x16x32_bf16 v[12:15], v[148:151], v[228:231], v[12:15]
	v_mfma_f32_16x16x32_bf16 v[8:11], v[156:159], v[228:231], v[8:11]
	v_mfma_f32_16x16x32_bf16 v[60:63], v[152:155], v[208:211], v[60:63]
	v_mfma_f32_16x16x32_bf16 v[56:59], v[160:163], v[208:211], v[56:59]
	v_mfma_f32_16x16x32_bf16 v[44:47], v[152:155], v[216:219], v[44:47]
	v_mfma_f32_16x16x32_bf16 v[40:43], v[160:163], v[216:219], v[40:43]
	v_mfma_f32_16x16x32_bf16 v[28:31], v[152:155], v[224:227], v[28:31]
	v_mfma_f32_16x16x32_bf16 v[24:27], v[160:163], v[224:227], v[24:27]
	v_mfma_f32_16x16x32_bf16 v[12:15], v[152:155], v[232:235], v[12:15]
	v_mfma_f32_16x16x32_bf16 v[8:11], v[160:163], v[232:235], v[8:11]
	v_mfma_f32_16x16x32_bf16 v[52:55], v[164:167], v[180:183], v[52:55]
	v_mfma_f32_16x16x32_bf16 v[48:51], v[172:175], v[180:183], v[48:51]
	v_mfma_f32_16x16x32_bf16 v[36:39], v[164:167], v[212:215], v[36:39]
	v_mfma_f32_16x16x32_bf16 v[32:35], v[172:175], v[212:215], v[32:35]
	v_mfma_f32_16x16x32_bf16 v[20:23], v[164:167], v[220:223], v[20:23]
	v_mfma_f32_16x16x32_bf16 v[16:19], v[172:175], v[220:223], v[16:19]
	v_mfma_f32_16x16x32_bf16 v[4:7], v[164:167], v[228:231], v[4:7]
	v_mfma_f32_16x16x32_bf16 v[0:3], v[172:175], v[228:231], v[0:3]
	v_mfma_f32_16x16x32_bf16 v[52:55], v[168:171], v[208:211], v[52:55]
	v_mfma_f32_16x16x32_bf16 v[48:51], v[176:179], v[208:211], v[48:51]
	v_mfma_f32_16x16x32_bf16 v[36:39], v[168:171], v[216:219], v[36:39]
	v_mfma_f32_16x16x32_bf16 v[32:35], v[176:179], v[216:219], v[32:35]
	v_mfma_f32_16x16x32_bf16 v[20:23], v[168:171], v[224:227], v[20:23]
	v_mfma_f32_16x16x32_bf16 v[16:19], v[176:179], v[224:227], v[16:19]
	v_mfma_f32_16x16x32_bf16 v[4:7], v[168:171], v[232:235], v[4:7]
	v_mfma_f32_16x16x32_bf16 v[0:3], v[176:179], v[232:235], v[0:3]
	s_setprio 0
	s_barrier
	s_add_u32 s14, s14, 0x100
	s_addc_u32 s15, s15, 0
	s_add_u32 s18, s18, 0x100
	s_addc_u32 s19, s19, 0
	s_cmp_ge_i32 s65, s60
	s_mov_b32 s4, s65
	s_cbranch_scc0 .LBB0_1365

; #define PG8_STAGE(bufoff, gbase, voff) do { _Pragma("unroll") for (int _i = 0; _i < 2; ++_i) \
;         __builtin_amdgcn_global_load_lds((const unsigned*)((const char*)(gbase) + _i * rdelta + (voff)), (LAS unsigned*)(lds + (bufoff) + ldsw + _i * 8192), 16, 0, 0); } while (0)
; #define PG8_LDA(dst, b, h) do { _Pragma("unroll") for (int m = 0; m < 4; ++m) _Pragma("unroll") for (int k = 0; k < 2; ++k) dst[m][k] = *(const LAS bf16x8*)(lds + PG8_SA(b, h) + aoff + m * 2048 + k * 1024); } while (0)
; #define PG8_LDB(dst, b, h) do { _Pragma("unroll") for (int n = 0; n < 2; ++n) _Pragma("unroll") for (int k = 0; k < 2; ++k) dst[n][k] = *(const LAS bf16x8*)(lds + PG8_SB(b, h) + boff + n * 2048 + k * 1024); } while (0)
; #define PG8_MMA(ai, bj, At, Bt) do { __builtin_amdgcn_s_setprio(1); _Pragma("unroll") for (int m = 0; m < 4; ++m) _Pragma("unroll") for (int n = 0; n < 2; ++n) _Pragma("unroll") for (int k = 0; k < 2; ++k) \
;         acc[ai][bj][m][n] = __builtin_amdgcn_mfma_f32_16x16x32_bf16(Bt[n][k], At[m][k], acc[ai][bj][m][n], 0, 0, 0); __builtin_amdgcn_s_setprio(0); } while (0)
; #define PG8_WAIT_V(n) asm volatile("s_waitcnt vmcnt(" #n ")" ::: "memory")
; #define PG8_WAIT_L(n) asm volatile("s_waitcnt lgkmcnt(" #n ")" ::: "memory")
; template <class Epi, class Sched, bool ALIGN_EPI, bool SP2>
; __device__ __forceinline__ void gemm_phase(LAS unsigned char* lds, const Gemm g, const Sched& S, const Epi& E) {
;     ...
;         for (int t = 0; t < nt; t += 2) {
;             if constexpr (Epi::HOOK) { if (t == Epi::T1 || t == Epi::T2) E.hook(acc, ui, t, wr, fr); }
;             const bool last = (t == nt - 2);
;             const char* a1 = cA + (size_t)(t + 1) * kstep;
;             const char* a2 = last ? nA : cA + (size_t)(t + 2) * kstep; const char* b2 = last ? nB : cB + (size_t)(t + 2) * kstep;
;             const char* a3 = a2 + kstep; const char* b3 = b2 + kstep;
;             PG8_LDB(B0, 0, 0); PG8_LDB(B1, 0, 1); PG8_SCHED; PG8_LDA(At, 0, 0); PG8_STAGE(PG8_SA(1, 1), a1 + hstep, voffA);
;             PG8_WAIT_V(8); PG8_WAIT_L(0); PG8_BAR; PG8_MMA(0, 0, At, B0); PG8_MMA(0, 1, At, B1); PG8_BAR; PG8_SCHED;
;             PG8_LDA(At, 0, 1); PG8_STAGE(PG8_SB(0, 0), b2, voffB); PG8_STAGE(PG8_SB(0, 1), b2 + hstep, voffB); PG8_STAGE(PG8_SA(0, 0), a2, voffA);
;             PG8_WAIT_V(8); PG8_WAIT_L(0); PG8_BAR; PG8_MMA(1, 0, At, B0); PG8_MMA(1, 1, At, B1); PG8_BAR; PG8_SCHED;
.LBB0_1564:
	s_add_i32 s67, s4, 2
	s_add_u32 s16, s14, 0x80
	s_addc_u32 s17, s15, 0
	s_add_i32 s70, 0, 0x10000
	s_cmp_eq_u32 s61, s4
	s_cselect_b32 s17, s7, s17
	s_cselect_b32 s16, s6, s16
	s_cselect_b32 s69, s59, s19
	s_cselect_b32 s68, s58, s18
	s_add_i32 s4, 0, 0x14000
	v_add_u32_e32 v156, s70, v146
	v_add_u32_e32 v172, s4, v146
	ds_read_b128 v[142:145], v156
	ds_read_b128 v[148:151], v156 offset:1024
	ds_read_b128 v[152:155], v156 offset:2048
	ds_read_b128 v[156:159], v156 offset:3072
	ds_read_b128 v[160:163], v172
	ds_read_b128 v[164:167], v172 offset:1024
	ds_read_b128 v[168:171], v172 offset:2048
	ds_read_b128 v[172:175], v172 offset:3072
	v_lshl_add_u64 v[190:191], s[14:15], 0, v[138:139]
	s_add_i32 m0, s35, 0xc000
	ds_read_b128 v[176:179], v147
	ds_read_b128 v[180:183], v147 offset:1024
	ds_read_b128 v[208:211], v147 offset:2048
	ds_read_b128 v[212:215], v147 offset:3072
	ds_read_b128 v[216:219], v147 offset:4096
	ds_read_b128 v[220:223], v147 offset:5120
	ds_read_b128 v[224:227], v147 offset:6144
	ds_read_b128 v[228:231], v147 offset:7168
	global_load_lds_dwordx4 v[190:191], off
	v_lshl_add_u64 v[190:191], s[14:15], 0, v[140:141]
	s_add_i32 m0, s35, 0xe000
	s_nop 0
	global_load_lds_dwordx4 v[190:191], off
	s_waitcnt vmcnt(8)
	s_waitcnt lgkmcnt(0)
	s_barrier
	s_setprio 1
	s_waitcnt lgkmcnt(0)
	v_mfma_f32_16x16x32_bf16 v[120:123], v[142:145], v[176:179], v[120:123]
	v_mfma_f32_16x16x32_bf16 v[124:127], v[152:155], v[176:179], v[124:127]
	v_mfma_f32_16x16x32_bf16 v[108:111], v[142:145], v[208:211], v[108:111]
	v_mfma_f32_16x16x32_bf16 v[104:107], v[152:155], v[208:211], v[104:107]
	v_mfma_f32_16x16x32_bf16 v[92:95], v[142:145], v[216:219], v[92:95]
	v_mfma_f32_16x16x32_bf16 v[88:91], v[152:155], v[216:219], v[88:91]
	v_mfma_f32_16x16x32_bf16 v[76:79], v[142:145], v[224:227], v[76:79]
	v_mfma_f32_16x16x32_bf16 v[72:75], v[152:155], v[224:227], v[72:75]
	v_mfma_f32_16x16x32_bf16 v[120:123], v[148:151], v[180:183], v[120:123]
	v_mfma_f32_16x16x32_bf16 v[124:127], v[156:159], v[180:183], v[124:127]
	v_mfma_f32_16x16x32_bf16 v[108:111], v[148:151], v[212:215], v[108:111]
	v_mfma_f32_16x16x32_bf16 v[104:107], v[156:159], v[212:215], v[104:107]
	v_mfma_f32_16x16x32_bf16 v[92:95], v[148:151], v[220:223], v[92:95]
	v_mfma_f32_16x16x32_bf16 v[88:91], v[156:159], v[220:223], v[88:91]
	v_mfma_f32_16x16x32_bf16 v[76:79], v[148:151], v[228:231], v[76:79]
	v_mfma_f32_16x16x32_bf16 v[72:75], v[156:159], v[228:231], v[72:75]
	v_mfma_f32_16x16x32_bf16 v[116:119], v[160:163], v[176:179], v[116:119]
	v_mfma_f32_16x16x32_bf16 v[112:115], v[168:171], v[176:179], v[112:115]
	v_mfma_f32_16x16x32_bf16 v[100:103], v[160:163], v[208:211], v[100:103]
	v_mfma_f32_16x16x32_bf16 v[96:99], v[168:171], v[208:211], v[96:99]
	v_mfma_f32_16x16x32_bf16 v[84:87], v[160:163], v[216:219], v[84:87]
	v_mfma_f32_16x16x32_bf16 v[80:83], v[168:171], v[216:219], v[80:83]
	v_mfma_f32_16x16x32_bf16 v[68:71], v[160:163], v[224:227], v[68:71]
	v_mfma_f32_16x16x32_bf16 v[64:67], v[168:171], v[224:227], v[64:67]
	v_mfma_f32_16x16x32_bf16 v[116:119], v[164:167], v[180:183], v[116:119]
	v_mfma_f32_16x16x32_bf16 v[112:115], v[172:175], v[180:183], v[112:115]
	v_mfma_f32_16x16x32_bf16 v[100:103], v[164:167], v[212:215], v[100:103]
	v_mfma_f32_16x16x32_bf16 v[96:99], v[172:175], v[212:215], v[96:99]
	v_mfma_f32_16x16x32_bf16 v[84:87], v[164:167], v[220:223], v[84:87]
	v_mfma_f32_16x16x32_bf16 v[80:83], v[172:175], v[220:223], v[80:83]
	v_mfma_f32_16x16x32_bf16 v[68:71], v[164:167], v[228:231], v[68:71]
	v_mfma_f32_16x16x32_bf16 v[64:67], v[172:175], v[228:231], v[64:67]
	s_setprio 0
	s_barrier
	s_add_i32 s70, s70, s34
	v_lshl_add_u64 v[190:191], s[68:69], 0, v[128:129]
	s_mov_b32 m0, s70
	ds_read_b128 v[176:179], v147 offset:16384
	ds_read_b128 v[180:183], v147 offset:17408
	ds_read_b128 v[208:211], v147 offset:18432
	ds_read_b128 v[212:215], v147 offset:19456
	ds_read_b128 v[216:219], v147 offset:20480
	ds_read_b128 v[220:223], v147 offset:21504
	ds_read_b128 v[224:227], v147 offset:22528
	ds_read_b128 v[228:231], v147 offset:23552
	global_load_lds_dwordx4 v[190:191], off
	s_add_i32 m0, s70, 0x2000
	s_add_u32 s68, s68, s10
	v_lshl_add_u64 v[192:193], v[190:191], 0, s[8:9]
	s_addc_u32 s69, s69, s11
	s_add_i32 s4, s4, s34
	global_load_lds_dwordx4 v[192:193], off
	v_lshl_add_u64 v[232:233], s[68:69], 0, v[128:129]
	s_mov_b32 m0, s4
	v_lshl_add_u64 v[234:235], v[232:233], 0, s[8:9]
	global_load_lds_dwordx4 v[232:233], off
	s_add_i32 m0, s4, 0x2000
	v_lshl_add_u64 v[236:237], s[16:17], 0, v[130:131]
	global_load_lds_dwordx4 v[234:235], off
	s_mov_b32 m0, s35
	v_lshl_add_u64 v[238:239], v[236:237], 0, s[8:9]
	global_load_lds_dwordx4 v[236:237], off
	s_mov_b32 m0, s36
	s_nop 0
	global_load_lds_dwordx4 v[238:239], off
	s_waitcnt vmcnt(8)
	s_waitcnt lgkmcnt(0)
	s_barrier
; #define PG8_STAGE(bufoff, gbase, voff) do { _Pragma("unroll") for (int _i = 0; _i < 2; ++_i) \
;         __builtin_amdgcn_global_load_lds((const unsigned*)((const char*)(gbase) + _i * rdelta + (voff)), (LAS unsigned*)(lds + (bufoff) + ldsw + _i * 8192), 16, 0, 0); } while (0)
; #define PG8_LDA(dst, b, h) do { _Pragma("unroll") for (int m = 0; m < 4; ++m) _Pragma("unroll") for (int k = 0; k < 2; ++k) dst[m][k] = *(const LAS bf16x8*)(lds + PG8_SA(b, h) + aoff + m * 2048 + k * 1024); } while (0)
; #define PG8_LDB(dst, b, h) do { _Pragma("unroll") for (int n = 0; n < 2; ++n) _Pragma("unroll") for (int k = 0; k < 2; ++k) dst[n][k] = *(const LAS bf16x8*)(lds + PG8_SB(b, h) + boff + n * 2048 + k * 1024); } while (0)
; #define PG8_MMA(ai, bj, At, Bt) do { __builtin_amdgcn_s_setprio(1); _Pragma("unroll") for (int m = 0; m < 4; ++m) _Pragma("unroll") for (int n = 0; n < 2; ++n) _Pragma("unroll") for (int k = 0; k < 2; ++k) \
;         acc[ai][bj][m][n] = __builtin_amdgcn_mfma_f32_16x16x32_bf16(Bt[n][k], At[m][k], acc[ai][bj][m][n], 0, 0, 0); __builtin_amdgcn_s_setprio(0); } while (0)
; #define PG8_WAIT_V(n) asm volatile("s_waitcnt vmcnt(" #n ")" ::: "memory")
; #define PG8_WAIT_L(n) asm volatile("s_waitcnt lgkmcnt(" #n ")" ::: "memory")
; #define PG8_BAR __builtin_amdgcn_s_barrier()
; #define PG8_SCHED __builtin_amdgcn_sched_barrier(0)
; template <class Epi, class Sched, bool ALIGN_EPI, bool SP2>
; __device__ __forceinline__ void gemm_phase(LAS unsigned char* lds, const Gemm g, const Sched& S, const Epi& E) {
;     ...
;             PG8_WAIT_V(8); PG8_WAIT_L(0); PG8_BAR; PG8_MMA(1, 0, At, B0); PG8_MMA(1, 1, At, B1); PG8_BAR; PG8_SCHED;
;             PG8_LDB(B0, 1, 0); PG8_LDB(B1, 1, 1); PG8_SCHED; PG8_LDA(At, 1, 0); PG8_STAGE(PG8_SA(0, 1), a2 + hstep, voffA);
;             PG8_WAIT_V(8); PG8_WAIT_L(0); PG8_BAR; PG8_MMA(0, 0, At, B0); PG8_MMA(0, 1, At, B1); PG8_BAR; PG8_SCHED;
	s_setprio 1
	s_waitcnt lgkmcnt(0)
	v_mfma_f32_16x16x32_bf16 v[60:63], v[142:145], v[176:179], v[60:63]
	v_mfma_f32_16x16x32_bf16 v[56:59], v[152:155], v[176:179], v[56:59]
	v_mfma_f32_16x16x32_bf16 v[44:47], v[142:145], v[208:211], v[44:47]
	v_mfma_f32_16x16x32_bf16 v[40:43], v[152:155], v[208:211], v[40:43]
	v_mfma_f32_16x16x32_bf16 v[28:31], v[142:145], v[216:219], v[28:31]
	v_mfma_f32_16x16x32_bf16 v[24:27], v[152:155], v[216:219], v[24:27]
	v_mfma_f32_16x16x32_bf16 v[12:15], v[142:145], v[224:227], v[12:15]
	v_mfma_f32_16x16x32_bf16 v[8:11], v[152:155], v[224:227], v[8:11]
	v_mfma_f32_16x16x32_bf16 v[60:63], v[148:151], v[180:183], v[60:63]
	v_mfma_f32_16x16x32_bf16 v[56:59], v[156:159], v[180:183], v[56:59]
	v_mfma_f32_16x16x32_bf16 v[44:47], v[148:151], v[212:215], v[44:47]
	v_mfma_f32_16x16x32_bf16 v[40:43], v[156:159], v[212:215], v[40:43]
	v_mfma_f32_16x16x32_bf16 v[28:31], v[148:151], v[220:223], v[28:31]
	v_mfma_f32_16x16x32_bf16 v[24:27], v[156:159], v[220:223], v[24:27]
	v_mfma_f32_16x16x32_bf16 v[12:15], v[148:151], v[228:231], v[12:15]
	v_mfma_f32_16x16x32_bf16 v[8:11], v[156:159], v[228:231], v[8:11]
	v_mfma_f32_16x16x32_bf16 v[52:55], v[160:163], v[176:179], v[52:55]
	v_mfma_f32_16x16x32_bf16 v[48:51], v[168:171], v[176:179], v[48:51]
	v_mfma_f32_16x16x32_bf16 v[36:39], v[160:163], v[208:211], v[36:39]
	v_mfma_f32_16x16x32_bf16 v[32:35], v[168:171], v[208:211], v[32:35]
	v_mfma_f32_16x16x32_bf16 v[20:23], v[160:163], v[216:219], v[20:23]
	v_mfma_f32_16x16x32_bf16 v[16:19], v[168:171], v[216:219], v[16:19]
	v_mfma_f32_16x16x32_bf16 v[4:7], v[160:163], v[224:227], v[4:7]
	v_mfma_f32_16x16x32_bf16 v[0:3], v[168:171], v[224:227], v[0:3]
	v_mfma_f32_16x16x32_bf16 v[52:55], v[164:167], v[180:183], v[52:55]
	v_mfma_f32_16x16x32_bf16 v[48:51], v[172:175], v[180:183], v[48:51]
	v_mfma_f32_16x16x32_bf16 v[36:39], v[164:167], v[212:215], v[36:39]
	v_mfma_f32_16x16x32_bf16 v[32:35], v[172:175], v[212:215], v[32:35]
	v_mfma_f32_16x16x32_bf16 v[20:23], v[164:167], v[220:223], v[20:23]
	v_mfma_f32_16x16x32_bf16 v[16:19], v[172:175], v[220:223], v[16:19]
	v_mfma_f32_16x16x32_bf16 v[4:7], v[164:167], v[228:231], v[4:7]
	v_mfma_f32_16x16x32_bf16 v[0:3], v[172:175], v[228:231], v[0:3]
	s_setprio 0
	s_barrier
	s_add_i32 s4, 0, 0x18000
	s_add_i32 s68, 0, 0x1c000
	v_add_u32_e32 v156, s4, v146
	v_add_u32_e32 v172, s68, v146
	ds_read_b128 v[142:145], v156
	ds_read_b128 v[148:151], v156 offset:1024
	ds_read_b128 v[152:155], v156 offset:2048
	ds_read_b128 v[156:159], v156 offset:3072
	ds_read_b128 v[160:163], v172
	ds_read_b128 v[164:167], v172 offset:1024
	ds_read_b128 v[168:171], v172 offset:2048
	ds_read_b128 v[172:175], v172 offset:3072
	s_add_u32 s16, s16, s10
	s_addc_u32 s17, s17, s11
	s_mov_b32 m0, s37
	v_lshl_add_u64 v[240:241], s[16:17], 0, v[130:131]
	ds_read_b128 v[176:179], v147 offset:32768
	ds_read_b128 v[180:183], v147 offset:33792
	ds_read_b128 v[208:211], v147 offset:34816
	ds_read_b128 v[212:215], v147 offset:35840
	ds_read_b128 v[216:219], v147 offset:36864
	ds_read_b128 v[220:223], v147 offset:37888
	ds_read_b128 v[224:227], v147 offset:38912
	ds_read_b128 v[228:231], v147 offset:39936
	global_load_lds_dwordx4 v[240:241], off
	v_lshl_add_u64 v[240:241], v[240:241], 0, s[8:9]
	s_mov_b32 m0, s40
	s_nop 0
	global_load_lds_dwordx4 v[240:241], off
	s_waitcnt vmcnt(8)
	s_waitcnt lgkmcnt(0)
	s_barrier
	s_setprio 1
	s_waitcnt lgkmcnt(0)
	v_mfma_f32_16x16x32_bf16 v[120:123], v[142:145], v[176:179], v[120:123]
	v_mfma_f32_16x16x32_bf16 v[124:127], v[152:155], v[176:179], v[124:127]
	v_mfma_f32_16x16x32_bf16 v[108:111], v[142:145], v[208:211], v[108:111]
	v_mfma_f32_16x16x32_bf16 v[104:107], v[152:155], v[208:211], v[104:107]
	v_mfma_f32_16x16x32_bf16 v[92:95], v[142:145], v[216:219], v[92:95]
	v_mfma_f32_16x16x32_bf16 v[88:91], v[152:155], v[216:219], v[88:91]
	v_mfma_f32_16x16x32_bf16 v[76:79], v[142:145], v[224:227], v[76:79]
	v_mfma_f32_16x16x32_bf16 v[72:75], v[152:155], v[224:227], v[72:75]
	v_mfma_f32_16x16x32_bf16 v[120:123], v[148:151], v[180:183], v[120:123]
	v_mfma_f32_16x16x32_bf16 v[124:127], v[156:159], v[180:183], v[124:127]
	v_mfma_f32_16x16x32_bf16 v[108:111], v[148:151], v[212:215], v[108:111]
	v_mfma_f32_16x16x32_bf16 v[104:107], v[156:159], v[212:215], v[104:107]
	v_mfma_f32_16x16x32_bf16 v[92:95], v[148:151], v[220:223], v[92:95]
	v_mfma_f32_16x16x32_bf16 v[88:91], v[156:159], v[220:223], v[88:91]
	v_mfma_f32_16x16x32_bf16 v[76:79], v[148:151], v[228:231], v[76:79]
	v_mfma_f32_16x16x32_bf16 v[72:75], v[156:159], v[228:231], v[72:75]
	v_mfma_f32_16x16x32_bf16 v[116:119], v[160:163], v[176:179], v[116:119]
	v_mfma_f32_16x16x32_bf16 v[112:115], v[168:171], v[176:179], v[112:115]
	v_mfma_f32_16x16x32_bf16 v[100:103], v[160:163], v[208:211], v[100:103]
	v_mfma_f32_16x16x32_bf16 v[96:99], v[168:171], v[208:211], v[96:99]
	v_mfma_f32_16x16x32_bf16 v[84:87], v[160:163], v[216:219], v[84:87]
	v_mfma_f32_16x16x32_bf16 v[80:83], v[168:171], v[216:219], v[80:83]
	v_mfma_f32_16x16x32_bf16 v[68:71], v[160:163], v[224:227], v[68:71]
	v_mfma_f32_16x16x32_bf16 v[64:67], v[168:171], v[224:227], v[64:67]
	v_mfma_f32_16x16x32_bf16 v[116:119], v[164:167], v[180:183], v[116:119]
	v_mfma_f32_16x16x32_bf16 v[112:115], v[172:175], v[180:183], v[112:115]
	v_mfma_f32_16x16x32_bf16 v[100:103], v[164:167], v[212:215], v[100:103]
	v_mfma_f32_16x16x32_bf16 v[96:99], v[172:175], v[212:215], v[96:99]
	v_mfma_f32_16x16x32_bf16 v[84:87], v[164:167], v[220:223], v[84:87]
	v_mfma_f32_16x16x32_bf16 v[80:83], v[172:175], v[220:223], v[80:83]
	v_mfma_f32_16x16x32_bf16 v[68:71], v[164:167], v[228:231], v[68:71]
	v_mfma_f32_16x16x32_bf16 v[64:67], v[172:175], v[228:231], v[64:67]
	s_setprio 0
	s_barrier
; #define PG8_STAGE(bufoff, gbase, voff) do { _Pragma("unroll") for (int _i = 0; _i < 2; ++_i) \
;         __builtin_amdgcn_global_load_lds((const unsigned*)((const char*)(gbase) + _i * rdelta + (voff)), (LAS unsigned*)(lds + (bufoff) + ldsw + _i * 8192), 16, 0, 0); } while (0)
; #define PG8_LDA(dst, b, h) do { _Pragma("unroll") for (int m = 0; m < 4; ++m) _Pragma("unroll") for (int k = 0; k < 2; ++k) dst[m][k] = *(const LAS bf16x8*)(lds + PG8_SA(b, h) + aoff + m * 2048 + k * 1024); } while (0)
; #define PG8_MMA(ai, bj, At, Bt) do { __builtin_amdgcn_s_setprio(1); _Pragma("unroll") for (int m = 0; m < 4; ++m) _Pragma("unroll") for (int n = 0; n < 2; ++n) _Pragma("unroll") for (int k = 0; k < 2; ++k) \
;         acc[ai][bj][m][n] = __builtin_amdgcn_mfma_f32_16x16x32_bf16(Bt[n][k], At[m][k], acc[ai][bj][m][n], 0, 0, 0); __builtin_amdgcn_s_setprio(0); } while (0)
; #define PG8_WAIT_V(n) asm volatile("s_waitcnt vmcnt(" #n ")" ::: "memory")
; #define PG8_WAIT_L(n) asm volatile("s_waitcnt lgkmcnt(" #n ")" ::: "memory")
; #define PG8_BAR __builtin_amdgcn_s_barrier()
; #define PG8_SCHED __builtin_amdgcn_sched_barrier(0)
; template <class Epi, class Sched, bool ALIGN_EPI, bool SP2>
; __device__ __forceinline__ void gemm_phase(LAS unsigned char* lds, const Gemm g, const Sched& S, const Epi& E) {
;     ...
;             PG8_LDA(At, 1, 1); PG8_STAGE(PG8_SB(1, 0), b3, voffB); PG8_STAGE(PG8_SB(1, 1), b3 + hstep, voffB); PG8_STAGE(PG8_SA(1, 0), a3, voffA);
;             PG8_WAIT_V(8); PG8_WAIT_L(0); PG8_BAR; PG8_MMA(1, 0, At, B0); PG8_MMA(1, 1, At, B1); PG8_BAR; PG8_SCHED;
;         }
	s_add_i32 s4, s4, s34
	v_lshl_add_u64 v[190:191], v[190:191], 0, s[30:31]
	s_mov_b32 m0, s4
	ds_read_b128 v[176:179], v147 offset:49152
	ds_read_b128 v[180:183], v147 offset:50176
	ds_read_b128 v[208:211], v147 offset:51200
	ds_read_b128 v[212:215], v147 offset:52224
	ds_read_b128 v[216:219], v147 offset:53248
	ds_read_b128 v[220:223], v147 offset:54272
	ds_read_b128 v[224:227], v147 offset:55296
	ds_read_b128 v[228:231], v147 offset:56320
	global_load_lds_dwordx4 v[190:191], off
	v_lshl_add_u64 v[190:191], v[192:193], 0, s[30:31]
	s_add_i32 m0, s4, 0x2000
	s_add_i32 s4, s68, s34
	global_load_lds_dwordx4 v[190:191], off
	v_lshl_add_u64 v[190:191], v[232:233], 0, s[30:31]
	s_mov_b32 m0, s4
	s_nop 0
	global_load_lds_dwordx4 v[190:191], off
	v_lshl_add_u64 v[190:191], v[234:235], 0, s[30:31]
	s_add_i32 m0, s4, 0x2000
	s_nop 0
	global_load_lds_dwordx4 v[190:191], off
	v_lshl_add_u64 v[190:191], v[236:237], 0, s[30:31]
	s_mov_b32 m0, s38
	s_nop 0
	global_load_lds_dwordx4 v[190:191], off
	v_lshl_add_u64 v[190:191], v[238:239], 0, s[30:31]
	s_mov_b32 m0, s41
	s_nop 0
	global_load_lds_dwordx4 v[190:191], off
	s_waitcnt vmcnt(8)
	s_waitcnt lgkmcnt(0)
	s_barrier
	s_setprio 1
	s_waitcnt lgkmcnt(0)
	v_mfma_f32_16x16x32_bf16 v[60:63], v[142:145], v[176:179], v[60:63]
	v_mfma_f32_16x16x32_bf16 v[56:59], v[152:155], v[176:179], v[56:59]
	v_mfma_f32_16x16x32_bf16 v[44:47], v[142:145], v[208:211], v[44:47]
	v_mfma_f32_16x16x32_bf16 v[40:43], v[152:155], v[208:211], v[40:43]
	v_mfma_f32_16x16x32_bf16 v[28:31], v[142:145], v[216:219], v[28:31]
	v_mfma_f32_16x16x32_bf16 v[24:27], v[152:155], v[216:219], v[24:27]
	v_mfma_f32_16x16x32_bf16 v[12:15], v[142:145], v[224:227], v[12:15]
	v_mfma_f32_16x16x32_bf16 v[8:11], v[152:155], v[224:227], v[8:11]
	v_mfma_f32_16x16x32_bf16 v[60:63], v[148:151], v[180:183], v[60:63]
	v_mfma_f32_16x16x32_bf16 v[56:59], v[156:159], v[180:183], v[56:59]
	v_mfma_f32_16x16x32_bf16 v[44:47], v[148:151], v[212:215], v[44:47]
	v_mfma_f32_16x16x32_bf16 v[40:43], v[156:159], v[212:215], v[40:43]
	v_mfma_f32_16x16x32_bf16 v[28:31], v[148:151], v[220:223], v[28:31]
	v_mfma_f32_16x16x32_bf16 v[24:27], v[156:159], v[220:223], v[24:27]
	v_mfma_f32_16x16x32_bf16 v[12:15], v[148:151], v[228:231], v[12:15]
	v_mfma_f32_16x16x32_bf16 v[8:11], v[156:159], v[228:231], v[8:11]
	v_mfma_f32_16x16x32_bf16 v[52:55], v[160:163], v[176:179], v[52:55]
	v_mfma_f32_16x16x32_bf16 v[48:51], v[168:171], v[176:179], v[48:51]
	v_mfma_f32_16x16x32_bf16 v[36:39], v[160:163], v[208:211], v[36:39]
	v_mfma_f32_16x16x32_bf16 v[32:35], v[168:171], v[208:211], v[32:35]
	v_mfma_f32_16x16x32_bf16 v[20:23], v[160:163], v[216:219], v[20:23]
	v_mfma_f32_16x16x32_bf16 v[16:19], v[168:171], v[216:219], v[16:19]
	v_mfma_f32_16x16x32_bf16 v[4:7], v[160:163], v[224:227], v[4:7]
	v_mfma_f32_16x16x32_bf16 v[0:3], v[168:171], v[224:227], v[0:3]
	v_mfma_f32_16x16x32_bf16 v[52:55], v[164:167], v[180:183], v[52:55]
	v_mfma_f32_16x16x32_bf16 v[48:51], v[172:175], v[180:183], v[48:51]
	v_mfma_f32_16x16x32_bf16 v[36:39], v[164:167], v[212:215], v[36:39]
	v_mfma_f32_16x16x32_bf16 v[32:35], v[172:175], v[212:215], v[32:35]
	v_mfma_f32_16x16x32_bf16 v[20:23], v[164:167], v[220:223], v[20:23]
	v_mfma_f32_16x16x32_bf16 v[16:19], v[172:175], v[220:223], v[16:19]
	v_mfma_f32_16x16x32_bf16 v[4:7], v[164:167], v[228:231], v[4:7]
	v_mfma_f32_16x16x32_bf16 v[0:3], v[172:175], v[228:231], v[0:3]
	s_setprio 0
	s_barrier
	s_add_u32 s14, s14, 0x100
	s_addc_u32 s15, s15, 0
	s_add_u32 s18, s18, 0x100
	s_addc_u32 s19, s19, 0
	s_cmp_ge_i32 s67, s60
	s_mov_b32 s4, s67
	s_cbranch_scc0 .LBB0_1564
